# mixer phase: every global store write-through (sc1), and the grid barrier behind it without the leader's L2 writeback (buffer_wbl2)
# baseline (speedup 1.0000x reference)
.LBB0_650:
	s_mov_b64 s[10:11], 0
	s_and_b64 vcc, exec, s[6:7]
	s_cbranch_vccz .LBB0_652
	s_lshl_b32 s0, s12, 6
	v_ashrrev_i32_e32 v0, 3, v206
	s_addk_i32 s0, 0x8000
	v_and_b32_e32 v0, -4, v0
	v_add_u32_e32 v34, s0, v0
	v_lshlrev_b32_e32 v0, 3, v206
	s_movk_i32 s13, 0x4000
	v_and_b32_e32 v18, 0xf8, v0
	v_cmp_gt_i32_e32 vcc, s13, v34
	v_bfrev_b32_e32 v0, 0.5
	v_mov_b32_e32 v1, 0xffc
	v_cndmask_b32_e32 v0, v0, v1, vcc
	v_ashrrev_i32_e32 v35, 31, v34
	v_and_b32_e32 v2, v0, v34
	v_lshlrev_b64 v[0:1], 13, v[34:35]
	v_lshl_add_u64 v[0:1], s[70:71], 0, v[0:1]
	v_lshlrev_b32_e32 v32, 1, v18
	v_lshl_add_u64 v[8:9], v[0:1], 0, v[32:33]
	s_movk_i32 s0, 0x2000
	v_add_co_u32_e64 v10, s[8:9], s0, v8
	v_cmp_ne_u32_e64 s[6:7], 0, v2
	s_nop 0
	v_addc_co_u32_e64 v11, s[8:9], 0, v9, s[8:9]
	v_cndmask_b32_e64 v0, 0, -1, s[6:7]
	v_add_co_u32_e64 v12, s[8:9], s13, v8
	v_mov_b32_e32 v1, v0
	s_nop 0
	v_addc_co_u32_e64 v13, s[8:9], 0, v9, s[8:9]
	s_movk_i32 s0, 0x6000
	v_lshlrev_b64 v[0:1], 13, v[0:1]
	v_add_co_u32_e64 v14, s[8:9], s0, v8
	v_lshl_add_u64 v[0:1], v[8:9], 0, v[0:1]
	s_nop 0
	v_addc_co_u32_e64 v15, s[8:9], 0, v9, s[8:9]
	v_cndmask_b32_e64 v122, 0, 1.0, s[6:7]
	s_lshl_b32 s6, s5, 8
	global_load_dwordx4 v[116:119], v[0:1], off offset:2560
	global_load_dwordx4 v[98:101], v[0:1], off offset:3584
	global_load_dwordx4 v[86:89], v[8:9], off offset:2560
	global_load_dwordx4 v[90:93], v[8:9], off offset:3584
	v_or_b32_e32 v0, 3, v2
	v_mov_b32_e32 v1, 0xff
	v_mov_b32_e32 v2, 0xfff
	s_ashr_i32 s7, s6, 31
	s_mul_i32 s8, s5, 0x300
	v_cndmask_b32_e32 v1, v1, v2, vcc
	s_ashr_i32 s9, s8, 31
	s_lshl_b64 s[6:7], s[6:7], 2
	v_cmp_lt_u32_e32 vcc, v0, v1
	v_mov_b32_e32 v0, 0x6000
	v_mov_b32_e32 v1, 0x8000
	s_add_u32 s16, s40, s6
	s_movk_i32 s0, 0x1000
	v_cndmask_b32_e32 v0, v0, v1, vcc
	v_mov_b32_e32 v1, v33
	s_addc_u32 s17, s41, s7
	v_add_co_u32_e64 v16, s[6:7], s0, v8
	v_lshl_add_u64 v[0:1], v[8:9], 0, v[0:1]
	s_nop 0
	v_addc_co_u32_e64 v17, s[6:7], 0, v9, s[6:7]
	s_movk_i32 s0, 0x3000
	global_load_dwordx4 v[102:105], v[10:11], off offset:2560
	global_load_dwordx4 v[94:97], v[10:11], off offset:3584
	global_load_dwordx4 v[74:77], v[12:13], off offset:2560
	global_load_dwordx4 v[70:73], v[12:13], off offset:3584
	global_load_dwordx4 v[58:61], v[14:15], off offset:2560
	global_load_dwordx4 v[54:57], v[14:15], off offset:3584
	global_load_dwordx4 v[4:7], v[0:1], off offset:2560
	s_nop 0
	global_load_dwordx4 v[0:3], v[0:1], off offset:3584
	v_lshlrev_b32_e32 v35, 2, v18
	global_load_dwordx4 v[110:113], v[8:9], off offset:3072
	global_load_dwordx4 v[106:109], v[16:17], off
	global_load_dwordx4 v[82:85], v[10:11], off offset:3072
	v_add_co_u32_e64 v10, s[6:7], s0, v8
	s_movk_i32 s0, 0x5000
	s_nop 0
	v_addc_co_u32_e64 v11, s[6:7], 0, v9, s[6:7]
	global_load_dwordx4 v[78:81], v[10:11], off
	global_load_dwordx4 v[66:69], v[12:13], off offset:3072
	v_add_co_u32_e64 v10, s[6:7], s0, v8
	s_movk_i32 s0, 0x7000
	s_nop 0
	v_addc_co_u32_e64 v11, s[6:7], 0, v9, s[6:7]
	v_add_co_u32_e64 v8, s[6:7], s0, v8
	global_load_dwordx4 v[62:65], v[10:11], off
	global_load_dwordx4 v[28:31], v[14:15], off offset:3072
	v_addc_co_u32_e64 v9, s[6:7], 0, v9, s[6:7]
	s_lshl_b64 s[6:7], s[8:9], 2
	s_add_u32 s6, s38, s6
	global_load_dwordx4 v[24:27], v[8:9], off
	s_addc_u32 s7, s39, s7
	global_load_dwordx4 v[8:11], v35, s[16:17] offset:16
	global_load_dwordx4 v[38:41], v35, s[16:17]
	global_load_dwordx4 v[12:15], v35, s[6:7] offset:16
	global_load_dwordx4 v[42:45], v35, s[6:7]
	global_load_dwordx4 v[16:19], v35, s[6:7] offset:1040
	global_load_dwordx4 v[46:49], v35, s[6:7] offset:1024
	global_load_dwordx4 v[20:23], v35, s[6:7] offset:2064
	global_load_dwordx4 v[50:53], v35, s[6:7] offset:2048
	v_cndmask_b32_e64 v114, 0, 1.0, vcc
	s_waitcnt vmcnt(14)
	v_lshlrev_b32_e32 v132, 16, v106
	v_mul_f32_e32 v35, 0xbfb8aa3b, v132
	v_exp_f32_e32 v35, v35
	v_and_b32_e32 v133, 0xffff0000, v106
	v_lshlrev_b32_e32 v120, 16, v116
	v_and_b32_e32 v121, 0xffff0000, v116
	v_add_f32_e32 v35, 1.0, v35
	v_rcp_f32_e32 v134, v35
	v_mul_f32_e32 v35, 0xbfb8aa3b, v133
	v_exp_f32_e32 v35, v35
	v_lshlrev_b32_e32 v128, 16, v117
	v_and_b32_e32 v129, 0xffff0000, v117
	v_lshlrev_b32_e32 v126, 16, v118
	v_and_b32_e32 v127, 0xffff0000, v118
	v_lshlrev_b32_e32 v124, 16, v119
	v_and_b32_e32 v125, 0xffff0000, v119
	v_lshlrev_b32_e32 v116, 16, v98
	v_and_b32_e32 v117, 0xffff0000, v98
	v_pk_mul_f32 v[118:119], v[122:123], v[120:121] op_sel_hi:[0,1]
	v_pk_mul_f32 v[120:121], v[118:119], v[116:117]
	v_lshlrev_b32_e32 v116, 16, v86
	v_and_b32_e32 v117, 0xffff0000, v86
	v_lshlrev_b32_e32 v118, 16, v90
	v_and_b32_e32 v119, 0xffff0000, v90
	v_pk_mul_f32 v[118:119], v[116:117], v[118:119]
	v_add_f32_e32 v35, 1.0, v35
	v_lshlrev_b32_e32 v116, 16, v102
	v_and_b32_e32 v117, 0xffff0000, v102
	v_lshlrev_b32_e32 v130, 16, v94
	v_and_b32_e32 v131, 0xffff0000, v94
	s_waitcnt vmcnt(2)
	v_pk_mul_f32 v[136:137], v[118:119], v[46:47]
	v_rcp_f32_e32 v135, v35
	v_pk_mul_f32 v[116:117], v[116:117], v[130:131]
	v_pk_fma_f32 v[120:121], v[120:121], v[42:43], v[136:137]
	v_lshlrev_b32_e32 v102, 16, v107
	s_waitcnt vmcnt(0)
	v_pk_fma_f32 v[120:121], v[116:117], v[50:51], v[120:121]
	v_lshlrev_b32_e32 v130, 16, v110
	v_and_b32_e32 v131, 0xffff0000, v110
	v_pk_add_f32 v[120:121], v[38:39], v[120:121]
	v_mul_f32_e32 v35, 0xbfb8aa3b, v102
	v_pk_mul_f32 v[120:121], v[120:121], v[130:131]
	v_pk_mul_f32 v[130:131], v[134:135], v[132:133]
	v_exp_f32_e32 v35, v35
	v_pk_mul_f32 v[120:121], v[130:131], v[120:121]
	v_lshlrev_b32_e32 v98, 16, v99
	v_cvt_pk_bf16_f32 v86, v120, v121
	v_and_b32_e32 v99, 0xffff0000, v99
	v_pk_mul_f32 v[120:121], v[122:123], v[128:129] op_sel_hi:[0,1]
	v_pk_mul_f32 v[98:99], v[120:121], v[98:99]
	v_lshlrev_b32_e32 v120, 16, v87
	v_and_b32_e32 v121, 0xffff0000, v87
	v_lshlrev_b32_e32 v90, 16, v91
	v_and_b32_e32 v91, 0xffff0000, v91
	v_pk_mul_f32 v[120:121], v[120:121], v[90:91]
	v_lshlrev_b32_e32 v90, 16, v103
	v_and_b32_e32 v91, 0xffff0000, v103
	v_and_b32_e32 v103, 0xffff0000, v107
	v_add_f32_e32 v35, 1.0, v35
	v_rcp_f32_e32 v106, v35
	v_mul_f32_e32 v35, 0xbfb8aa3b, v103
	v_exp_f32_e32 v35, v35
	v_lshlrev_b32_e32 v94, 16, v95
	v_and_b32_e32 v95, 0xffff0000, v95
	v_pk_mul_f32 v[94:95], v[90:91], v[94:95]
	v_lshlrev_b32_e32 v90, 16, v111
	v_and_b32_e32 v91, 0xffff0000, v111
	v_pk_mul_f32 v[110:111], v[120:121], v[48:49]
	v_add_f32_e32 v35, 1.0, v35
	v_pk_fma_f32 v[98:99], v[98:99], v[44:45], v[110:111]
	v_lshlrev_b32_e32 v110, 16, v108
	v_rcp_f32_e32 v107, v35
	v_mul_f32_e32 v35, 0xbfb8aa3b, v110
	v_exp_f32_e32 v35, v35
	v_pk_fma_f32 v[98:99], v[94:95], v[52:53], v[98:99]
	v_and_b32_e32 v111, 0xffff0000, v108
	v_pk_add_f32 v[98:99], v[40:41], v[98:99]
	v_add_f32_e32 v35, 1.0, v35
	v_pk_mul_f32 v[90:91], v[98:99], v[90:91]
	v_pk_mul_f32 v[98:99], v[106:107], v[102:103]
	v_lshlrev_b32_e32 v102, 16, v92
	v_pk_mul_f32 v[90:91], v[98:99], v[90:91]
	v_pk_mul_f32 v[98:99], v[122:123], v[126:127] op_sel_hi:[0,1]
	v_rcp_f32_e32 v126, v35
	v_mul_f32_e32 v35, 0xbfb8aa3b, v111
	v_exp_f32_e32 v35, v35
	v_cvt_pk_bf16_f32 v87, v90, v91
	v_lshlrev_b32_e32 v90, 16, v100
	v_and_b32_e32 v91, 0xffff0000, v100
	v_pk_mul_f32 v[90:91], v[98:99], v[90:91]
	v_lshlrev_b32_e32 v98, 16, v88
	v_and_b32_e32 v99, 0xffff0000, v88
	v_and_b32_e32 v103, 0xffff0000, v92
	v_pk_mul_f32 v[102:103], v[98:99], v[102:103]
	v_add_f32_e32 v35, 1.0, v35
	v_lshlrev_b32_e32 v98, 16, v104
	v_and_b32_e32 v99, 0xffff0000, v104
	v_lshlrev_b32_e32 v106, 16, v96
	v_and_b32_e32 v107, 0xffff0000, v96
	v_pk_mul_f32 v[128:129], v[102:103], v[16:17]
	v_rcp_f32_e32 v127, v35
	v_pk_mul_f32 v[98:99], v[98:99], v[106:107]
	v_pk_fma_f32 v[90:91], v[90:91], v[12:13], v[128:129]
	v_lshlrev_b32_e32 v104, 16, v109
	v_pk_fma_f32 v[90:91], v[98:99], v[20:21], v[90:91]
	v_lshlrev_b32_e32 v106, 16, v112
	v_and_b32_e32 v107, 0xffff0000, v112
	v_pk_add_f32 v[90:91], v[8:9], v[90:91]
	v_mul_f32_e32 v35, 0xbfb8aa3b, v104
	v_pk_mul_f32 v[90:91], v[90:91], v[106:107]
	v_pk_mul_f32 v[106:107], v[126:127], v[110:111]
	v_exp_f32_e32 v35, v35
	v_pk_mul_f32 v[90:91], v[106:107], v[90:91]
	v_lshlrev_b32_e32 v92, 16, v93
	v_cvt_pk_bf16_f32 v88, v90, v91
	v_lshlrev_b32_e32 v90, 16, v101
	v_and_b32_e32 v91, 0xffff0000, v101
	v_pk_mul_f32 v[100:101], v[122:123], v[124:125] op_sel_hi:[0,1]
	v_pk_mul_f32 v[90:91], v[100:101], v[90:91]
	v_lshlrev_b32_e32 v100, 16, v89
	v_and_b32_e32 v101, 0xffff0000, v89
	v_and_b32_e32 v93, 0xffff0000, v93
	v_pk_mul_f32 v[100:101], v[100:101], v[92:93]
	v_lshlrev_b32_e32 v92, 16, v105
	v_and_b32_e32 v93, 0xffff0000, v105
	v_and_b32_e32 v105, 0xffff0000, v109
	v_add_f32_e32 v35, 1.0, v35
	v_rcp_f32_e32 v106, v35
	v_mul_f32_e32 v35, 0xbfb8aa3b, v105
	v_exp_f32_e32 v35, v35
	v_lshlrev_b32_e32 v96, 16, v97
	v_and_b32_e32 v97, 0xffff0000, v97
	v_pk_mul_f32 v[108:109], v[100:101], v[18:19]
	v_add_f32_e32 v35, 1.0, v35
	v_rcp_f32_e32 v107, v35
	v_pk_mul_f32 v[92:93], v[92:93], v[96:97]
	v_pk_fma_f32 v[90:91], v[90:91], v[14:15], v[108:109]
	v_lshlrev_b32_e32 v96, 16, v113
	v_pk_fma_f32 v[90:91], v[92:93], v[22:23], v[90:91]
	v_and_b32_e32 v97, 0xffff0000, v113
	v_pk_add_f32 v[90:91], v[10:11], v[90:91]
	s_mov_b32 s0, 0x18c00000
	v_pk_mul_f32 v[90:91], v[90:91], v[96:97]
	v_pk_mul_f32 v[96:97], v[106:107], v[104:105]
	v_pk_mul_f32 v[106:107], v[116:117], v[46:47]
	v_pk_mul_f32 v[90:91], v[96:97], v[90:91]
	v_pk_fma_f32 v[106:107], v[118:119], v[42:43], v[106:107]
	v_cvt_pk_bf16_f32 v89, v90, v91
	v_mov_b64_e32 v[90:91], s[48:49]
	v_mad_i64_i32 v[96:97], s[6:7], v34, s44, v[90:91]
	v_lshl_add_u64 v[96:97], v[96:97], 0, v[32:33]
	v_add_co_u32_e32 v96, vcc, s0, v96
	s_mov_b64 s[76:77], 0
	s_nop 0
	v_addc_co_u32_e32 v97, vcc, 0, v97, vcc
	global_store_dwordx4 v[96:97], v[86:89], off offset:1024 sc1
	v_lshlrev_b32_e32 v96, 16, v78
	v_mul_f32_e32 v35, 0xbfb8aa3b, v96
	v_exp_f32_e32 v35, v35
	v_and_b32_e32 v97, 0xffff0000, v78
	v_lshlrev_b32_e32 v78, 16, v79
	v_lshlrev_b32_e32 v86, 16, v74
	v_add_f32_e32 v35, 1.0, v35
	v_rcp_f32_e32 v104, v35
	v_mul_f32_e32 v35, 0xbfb8aa3b, v97
	v_exp_f32_e32 v35, v35
	v_and_b32_e32 v87, 0xffff0000, v74
	v_lshlrev_b32_e32 v88, 16, v70
	v_and_b32_e32 v89, 0xffff0000, v70
	v_add_f32_e32 v35, 1.0, v35
	v_rcp_f32_e32 v105, v35
	v_mul_f32_e32 v35, 0xbfb8aa3b, v78
	v_exp_f32_e32 v35, v35
	v_and_b32_e32 v79, 0xffff0000, v79
	v_pk_mul_f32 v[88:89], v[86:87], v[88:89]
	v_lshlrev_b32_e32 v86, 16, v82
	v_add_f32_e32 v35, 1.0, v35
	v_and_b32_e32 v87, 0xffff0000, v82
	v_rcp_f32_e32 v82, v35
	v_mul_f32_e32 v35, 0xbfb8aa3b, v79
	v_pk_fma_f32 v[106:107], v[88:89], v[50:51], v[106:107]
	v_exp_f32_e32 v35, v35
	v_pk_add_f32 v[106:107], v[38:39], v[106:107]
	v_pk_mul_f32 v[96:97], v[104:105], v[96:97]
	v_pk_mul_f32 v[86:87], v[106:107], v[86:87]
	v_lshlrev_b32_e32 v74, 16, v75
	v_pk_mul_f32 v[86:87], v[96:97], v[86:87]
	v_and_b32_e32 v75, 0xffff0000, v75
	v_cvt_pk_bf16_f32 v70, v86, v87
	v_lshlrev_b32_e32 v86, 16, v71
	v_and_b32_e32 v87, 0xffff0000, v71
	v_add_f32_e32 v35, 1.0, v35
	v_pk_mul_f32 v[86:87], v[74:75], v[86:87]
	v_lshlrev_b32_e32 v74, 16, v83
	v_and_b32_e32 v75, 0xffff0000, v83
	v_rcp_f32_e32 v83, v35
	v_pk_mul_f32 v[96:97], v[94:95], v[48:49]
	v_pk_mul_f32 v[104:105], v[98:99], v[16:17]
	v_pk_fma_f32 v[96:97], v[120:121], v[44:45], v[96:97]
	v_pk_mul_f32 v[78:79], v[82:83], v[78:79]
	v_lshlrev_b32_e32 v82, 16, v80
	v_mul_f32_e32 v35, 0xbfb8aa3b, v82
	v_exp_f32_e32 v35, v35
	v_pk_fma_f32 v[96:97], v[86:87], v[52:53], v[96:97]
	v_and_b32_e32 v83, 0xffff0000, v80
	v_pk_add_f32 v[96:97], v[40:41], v[96:97]
	v_add_f32_e32 v35, 1.0, v35
	v_pk_mul_f32 v[74:75], v[96:97], v[74:75]
	v_rcp_f32_e32 v96, v35
	v_mul_f32_e32 v35, 0xbfb8aa3b, v83
	v_exp_f32_e32 v35, v35
	v_lshlrev_b32_e32 v80, 16, v81
	v_pk_mul_f32 v[74:75], v[78:79], v[74:75]
	v_lshlrev_b32_e32 v78, 16, v72
	v_add_f32_e32 v35, 1.0, v35
	v_rcp_f32_e32 v97, v35
	v_mul_f32_e32 v35, 0xbfb8aa3b, v80
	v_cvt_pk_bf16_f32 v71, v74, v75
	v_lshlrev_b32_e32 v74, 16, v76
	v_and_b32_e32 v75, 0xffff0000, v76
	v_and_b32_e32 v79, 0xffff0000, v72
	v_exp_f32_e32 v35, v35
	v_pk_mul_f32 v[78:79], v[74:75], v[78:79]
	v_pk_fma_f32 v[102:103], v[102:103], v[12:13], v[104:105]
	v_lshlrev_b32_e32 v74, 16, v84
	v_pk_fma_f32 v[102:103], v[78:79], v[20:21], v[102:103]
	v_and_b32_e32 v75, 0xffff0000, v84
	v_pk_add_f32 v[102:103], v[8:9], v[102:103]
	v_pk_mul_f32 v[82:83], v[96:97], v[82:83]
	v_pk_mul_f32 v[74:75], v[102:103], v[74:75]
	v_and_b32_e32 v81, 0xffff0000, v81
	v_add_f32_e32 v35, 1.0, v35
	v_pk_mul_f32 v[74:75], v[82:83], v[74:75]
	v_rcp_f32_e32 v82, v35
	v_mul_f32_e32 v35, 0xbfb8aa3b, v81
	v_exp_f32_e32 v35, v35
	v_cvt_pk_bf16_f32 v72, v74, v75
	v_lshlrev_b32_e32 v74, 16, v77
	v_and_b32_e32 v75, 0xffff0000, v77
	v_lshlrev_b32_e32 v76, 16, v73
	v_and_b32_e32 v77, 0xffff0000, v73
	v_add_f32_e32 v35, 1.0, v35
	v_pk_mul_f32 v[74:75], v[74:75], v[76:77]
	v_lshlrev_b32_e32 v76, 16, v85
	v_and_b32_e32 v77, 0xffff0000, v85
	v_pk_mul_f32 v[84:85], v[92:93], v[18:19]
	v_rcp_f32_e32 v83, v35
	v_pk_fma_f32 v[84:85], v[100:101], v[14:15], v[84:85]
	v_or_b32_e32 v35, 1, v34
	v_pk_fma_f32 v[84:85], v[74:75], v[22:23], v[84:85]
	v_pk_mul_f32 v[80:81], v[82:83], v[80:81]
	v_pk_add_f32 v[84:85], v[10:11], v[84:85]
	v_pk_mul_f32 v[82:83], v[88:89], v[46:47]
	v_pk_mul_f32 v[76:77], v[84:85], v[76:77]
	v_pk_fma_f32 v[82:83], v[116:117], v[42:43], v[82:83]
	v_pk_mul_f32 v[76:77], v[80:81], v[76:77]
	s_mov_b32 s94, s18
	v_cvt_pk_bf16_f32 v73, v76, v77
	v_mad_i64_i32 v[76:77], s[6:7], v35, s44, v[90:91]
	v_lshl_add_u64 v[76:77], v[76:77], 0, v[32:33]
	v_add_co_u32_e32 v76, vcc, s0, v76
	s_nop 1
	v_addc_co_u32_e32 v77, vcc, 0, v77, vcc
	global_store_dwordx4 v[76:77], v[70:73], off offset:1024 sc1
	v_lshlrev_b32_e32 v76, 16, v62
	v_mul_f32_e32 v35, 0xbfb8aa3b, v76
	v_exp_f32_e32 v35, v35
	v_and_b32_e32 v77, 0xffff0000, v62
	v_lshlrev_b32_e32 v62, 16, v63
	v_lshlrev_b32_e32 v70, 16, v58
	v_add_f32_e32 v35, 1.0, v35
	v_rcp_f32_e32 v80, v35
	v_mul_f32_e32 v35, 0xbfb8aa3b, v77
	v_exp_f32_e32 v35, v35
	v_and_b32_e32 v71, 0xffff0000, v58
	v_lshlrev_b32_e32 v72, 16, v54
	v_and_b32_e32 v73, 0xffff0000, v54
	v_add_f32_e32 v35, 1.0, v35
	v_rcp_f32_e32 v81, v35
	v_mul_f32_e32 v35, 0xbfb8aa3b, v62
	v_exp_f32_e32 v35, v35
	v_and_b32_e32 v63, 0xffff0000, v63
	v_pk_mul_f32 v[72:73], v[70:71], v[72:73]
	v_lshlrev_b32_e32 v70, 16, v66
	v_add_f32_e32 v35, 1.0, v35
	v_and_b32_e32 v71, 0xffff0000, v66
	v_rcp_f32_e32 v66, v35
	v_mul_f32_e32 v35, 0xbfb8aa3b, v63
	v_pk_fma_f32 v[82:83], v[72:73], v[50:51], v[82:83]
	v_exp_f32_e32 v35, v35
	v_pk_add_f32 v[82:83], v[38:39], v[82:83]
	v_pk_mul_f32 v[76:77], v[80:81], v[76:77]
	v_pk_mul_f32 v[70:71], v[82:83], v[70:71]
	v_lshlrev_b32_e32 v58, 16, v59
	v_pk_mul_f32 v[70:71], v[76:77], v[70:71]
	v_and_b32_e32 v59, 0xffff0000, v59
	v_cvt_pk_bf16_f32 v54, v70, v71
	v_lshlrev_b32_e32 v70, 16, v55
	v_and_b32_e32 v71, 0xffff0000, v55
	v_add_f32_e32 v35, 1.0, v35
	v_pk_mul_f32 v[70:71], v[58:59], v[70:71]
	v_lshlrev_b32_e32 v58, 16, v67
	v_and_b32_e32 v59, 0xffff0000, v67
	v_rcp_f32_e32 v67, v35
	v_pk_mul_f32 v[76:77], v[86:87], v[48:49]
	v_pk_mul_f32 v[80:81], v[78:79], v[16:17]
	v_pk_fma_f32 v[76:77], v[94:95], v[44:45], v[76:77]
	v_pk_mul_f32 v[62:63], v[66:67], v[62:63]
	v_lshlrev_b32_e32 v66, 16, v64
	v_mul_f32_e32 v35, 0xbfb8aa3b, v66
	v_exp_f32_e32 v35, v35
	v_pk_fma_f32 v[76:77], v[70:71], v[52:53], v[76:77]
	v_and_b32_e32 v67, 0xffff0000, v64
	v_pk_add_f32 v[76:77], v[40:41], v[76:77]
	v_add_f32_e32 v35, 1.0, v35
	v_pk_mul_f32 v[58:59], v[76:77], v[58:59]
	v_rcp_f32_e32 v76, v35
	v_mul_f32_e32 v35, 0xbfb8aa3b, v67
	v_exp_f32_e32 v35, v35
	v_lshlrev_b32_e32 v64, 16, v65
	v_pk_mul_f32 v[58:59], v[62:63], v[58:59]
	v_lshlrev_b32_e32 v62, 16, v56
	v_add_f32_e32 v35, 1.0, v35
	v_rcp_f32_e32 v77, v35
	v_mul_f32_e32 v35, 0xbfb8aa3b, v64
	v_cvt_pk_bf16_f32 v55, v58, v59
	v_lshlrev_b32_e32 v58, 16, v60
	v_and_b32_e32 v59, 0xffff0000, v60
	v_and_b32_e32 v63, 0xffff0000, v56
	v_exp_f32_e32 v35, v35
	v_pk_mul_f32 v[62:63], v[58:59], v[62:63]
	v_pk_fma_f32 v[80:81], v[98:99], v[12:13], v[80:81]
	v_lshlrev_b32_e32 v58, 16, v68
	v_pk_fma_f32 v[80:81], v[62:63], v[20:21], v[80:81]
	v_and_b32_e32 v59, 0xffff0000, v68
	v_pk_add_f32 v[80:81], v[8:9], v[80:81]
	v_pk_mul_f32 v[66:67], v[76:77], v[66:67]
	v_pk_mul_f32 v[58:59], v[80:81], v[58:59]
	v_and_b32_e32 v65, 0xffff0000, v65
	v_add_f32_e32 v35, 1.0, v35
	v_pk_mul_f32 v[58:59], v[66:67], v[58:59]
	v_rcp_f32_e32 v66, v35
	v_mul_f32_e32 v35, 0xbfb8aa3b, v65
	v_exp_f32_e32 v35, v35
	v_cvt_pk_bf16_f32 v56, v58, v59
	v_lshlrev_b32_e32 v58, 16, v61
	v_and_b32_e32 v59, 0xffff0000, v61
	v_lshlrev_b32_e32 v60, 16, v57
	v_and_b32_e32 v61, 0xffff0000, v57
	v_add_f32_e32 v35, 1.0, v35
	v_pk_mul_f32 v[58:59], v[58:59], v[60:61]
	v_lshlrev_b32_e32 v60, 16, v69
	v_and_b32_e32 v61, 0xffff0000, v69
	v_pk_mul_f32 v[68:69], v[74:75], v[18:19]
	v_rcp_f32_e32 v67, v35
	v_pk_fma_f32 v[68:69], v[92:93], v[14:15], v[68:69]
	v_or_b32_e32 v35, 2, v34
	v_pk_fma_f32 v[68:69], v[58:59], v[22:23], v[68:69]
	v_pk_mul_f32 v[64:65], v[66:67], v[64:65]
	v_pk_add_f32 v[68:69], v[10:11], v[68:69]
	v_pk_mul_f32 v[46:47], v[72:73], v[46:47]
	v_pk_mul_f32 v[60:61], v[68:69], v[60:61]
	v_pk_fma_f32 v[42:43], v[88:89], v[42:43], v[46:47]
	v_pk_mul_f32 v[60:61], v[64:65], v[60:61]
	v_pk_mul_f32 v[16:17], v[62:63], v[16:17]
	v_cvt_pk_bf16_f32 v57, v60, v61
	v_mad_i64_i32 v[60:61], s[6:7], v35, s44, v[90:91]
	v_lshl_add_u64 v[60:61], v[60:61], 0, v[32:33]
	v_add_co_u32_e32 v60, vcc, s0, v60
	v_pk_fma_f32 v[12:13], v[78:79], v[12:13], v[16:17]
	s_nop 0
	v_addc_co_u32_e32 v61, vcc, 0, v61, vcc
	global_store_dwordx4 v[60:61], v[54:57], off offset:1024 sc1
	v_lshlrev_b32_e32 v60, 16, v24
	v_and_b32_e32 v61, 0xffff0000, v24
	v_lshlrev_b32_e32 v56, 16, v0
	v_and_b32_e32 v57, 0xffff0000, v0
	v_mul_f32_e32 v0, 0xbfb8aa3b, v60
	v_exp_f32_e32 v0, v0
	v_lshlrev_b32_e32 v54, 16, v4
	v_and_b32_e32 v55, 0xffff0000, v4
	v_pk_mul_f32 v[54:55], v[114:115], v[54:55] op_sel_hi:[0,1]
	v_add_f32_e32 v0, 1.0, v0
	v_rcp_f32_e32 v64, v0
	v_mul_f32_e32 v0, 0xbfb8aa3b, v61
	v_exp_f32_e32 v0, v0
	v_pk_mul_f32 v[54:55], v[54:55], v[56:57]
	v_lshlrev_b32_e32 v56, 16, v28
	v_pk_fma_f32 v[42:43], v[54:55], v[50:51], v[42:43]
	v_add_f32_e32 v0, 1.0, v0
	v_rcp_f32_e32 v65, v0
	v_and_b32_e32 v57, 0xffff0000, v28
	v_pk_add_f32 v[38:39], v[38:39], v[42:43]
	v_lshlrev_b32_e32 v24, 16, v25
	v_pk_mul_f32 v[38:39], v[38:39], v[56:57]
	v_pk_mul_f32 v[42:43], v[64:65], v[60:61]
	v_lshlrev_b32_e32 v4, 16, v5
	v_pk_mul_f32 v[38:39], v[42:43], v[38:39]
	v_and_b32_e32 v5, 0xffff0000, v5
	v_cvt_pk_bf16_f32 v0, v38, v39
	v_lshlrev_b32_e32 v38, 16, v1
	v_and_b32_e32 v39, 0xffff0000, v1
	v_mul_f32_e32 v1, 0xbfb8aa3b, v24
	v_exp_f32_e32 v1, v1
	v_pk_mul_f32 v[4:5], v[114:115], v[4:5] op_sel_hi:[0,1]
	v_and_b32_e32 v25, 0xffff0000, v25
	v_pk_mul_f32 v[4:5], v[4:5], v[38:39]
	v_add_f32_e32 v1, 1.0, v1
	v_rcp_f32_e32 v38, v1
	v_mul_f32_e32 v1, 0xbfb8aa3b, v25
	v_exp_f32_e32 v1, v1
	v_pk_mul_f32 v[42:43], v[70:71], v[48:49]
	v_lshlrev_b32_e32 v28, 16, v29
	v_pk_fma_f32 v[42:43], v[86:87], v[44:45], v[42:43]
	v_add_f32_e32 v1, 1.0, v1
	v_rcp_f32_e32 v39, v1
	v_pk_fma_f32 v[4:5], v[4:5], v[52:53], v[42:43]
	v_and_b32_e32 v29, 0xffff0000, v29
	v_pk_add_f32 v[4:5], v[40:41], v[4:5]
	v_pk_mul_f32 v[24:25], v[38:39], v[24:25]
	v_pk_mul_f32 v[4:5], v[4:5], v[28:29]
	v_lshlrev_b32_e32 v28, 16, v26
	v_pk_mul_f32 v[4:5], v[24:25], v[4:5]
	v_lshlrev_b32_e32 v24, 16, v2
	v_and_b32_e32 v25, 0xffff0000, v2
	v_mul_f32_e32 v2, 0xbfb8aa3b, v28
	v_exp_f32_e32 v2, v2
	v_and_b32_e32 v29, 0xffff0000, v26
	v_cvt_pk_bf16_f32 v1, v4, v5
	v_lshlrev_b32_e32 v4, 16, v6
	v_add_f32_e32 v2, 1.0, v2
	v_rcp_f32_e32 v38, v2
	v_mul_f32_e32 v2, 0xbfb8aa3b, v29
	v_exp_f32_e32 v2, v2
	v_and_b32_e32 v5, 0xffff0000, v6
	v_pk_mul_f32 v[4:5], v[114:115], v[4:5] op_sel_hi:[0,1]
	v_pk_mul_f32 v[4:5], v[4:5], v[24:25]
	v_add_f32_e32 v2, 1.0, v2
	v_rcp_f32_e32 v39, v2
	v_pk_fma_f32 v[4:5], v[4:5], v[20:21], v[12:13]
	v_lshlrev_b32_e32 v24, 16, v30
	v_and_b32_e32 v25, 0xffff0000, v30
	v_pk_add_f32 v[4:5], v[8:9], v[4:5]
	v_pk_mul_f32 v[8:9], v[38:39], v[28:29]
	v_pk_mul_f32 v[4:5], v[4:5], v[24:25]
	v_lshlrev_b32_e32 v6, 16, v3
	v_pk_mul_f32 v[4:5], v[8:9], v[4:5]
	v_lshlrev_b32_e32 v8, 16, v27
	v_cvt_pk_bf16_f32 v2, v4, v5
	v_lshlrev_b32_e32 v4, 16, v7
	v_and_b32_e32 v5, 0xffff0000, v7
	v_and_b32_e32 v7, 0xffff0000, v3
	v_mul_f32_e32 v3, 0xbfb8aa3b, v8
	v_exp_f32_e32 v3, v3
	v_and_b32_e32 v9, 0xffff0000, v27
	v_pk_mul_f32 v[4:5], v[114:115], v[4:5] op_sel_hi:[0,1]
	v_pk_mul_f32 v[16:17], v[58:59], v[18:19]
	v_add_f32_e32 v3, 1.0, v3
	v_rcp_f32_e32 v12, v3
	v_mul_f32_e32 v3, 0xbfb8aa3b, v9
	v_exp_f32_e32 v3, v3
	v_pk_mul_f32 v[4:5], v[4:5], v[6:7]
	v_pk_fma_f32 v[14:15], v[74:75], v[14:15], v[16:17]
	v_lshlrev_b32_e32 v6, 16, v31
	v_add_f32_e32 v3, 1.0, v3
	v_rcp_f32_e32 v13, v3
	v_pk_fma_f32 v[4:5], v[4:5], v[22:23], v[14:15]
	v_and_b32_e32 v7, 0xffff0000, v31
	v_pk_add_f32 v[4:5], v[10:11], v[4:5]
	s_nop 0
	v_pk_mul_f32 v[4:5], v[4:5], v[6:7]
	v_pk_mul_f32 v[6:7], v[12:13], v[8:9]
	s_nop 0
	v_pk_mul_f32 v[4:5], v[6:7], v[4:5]
	s_nop 0
	v_cvt_pk_bf16_f32 v3, v4, v5
	v_or_b32_e32 v4, 3, v34
	v_mad_i64_i32 v[4:5], s[6:7], v4, s44, v[90:91]
	v_lshl_add_u64 v[4:5], v[4:5], 0, v[32:33]
	v_add_co_u32_e32 v4, vcc, 0x18c00000, v4
	s_nop 1
	v_addc_co_u32_e32 v5, vcc, 0, v5, vcc
	global_store_dwordx4 v[4:5], v[0:3], off offset:1024 sc1

.LBB0_656:
	s_andn2_b64 vcc, exec, s[6:7]
	s_cbranch_vccnz .LBB0_661
	s_cmp_lg_u32 s16, 1
	s_mov_b64 s[10:11], -1
	s_cbranch_scc1 .LBB0_659
	v_ashrrev_i32_e32 v0, 3, v206
	v_and_b32_e32 v0, -4, v0
	v_lshl_add_u32 v34, s13, 6, v0
	v_lshlrev_b32_e32 v0, 3, v206
	s_movk_i32 s10, 0x4000
	v_and_b32_e32 v18, 0xf8, v0
	v_cmp_gt_i32_e32 vcc, s10, v34
	v_bfrev_b32_e32 v0, 0.5
	v_mov_b32_e32 v1, 0xffc
	v_cndmask_b32_e32 v0, v0, v1, vcc
	v_ashrrev_i32_e32 v35, 31, v34
	v_and_b32_e32 v2, v0, v34
	v_lshlrev_b64 v[0:1], 13, v[34:35]
	v_lshl_add_u64 v[0:1], s[70:71], 0, v[0:1]
	v_lshlrev_b32_e32 v32, 1, v18
	v_lshl_add_u64 v[8:9], v[0:1], 0, v[32:33]
	s_movk_i32 s0, 0x2000
	v_add_co_u32_e64 v10, s[8:9], s0, v8
	v_cmp_ne_u32_e64 s[6:7], 0, v2
	s_nop 0
	v_addc_co_u32_e64 v11, s[8:9], 0, v9, s[8:9]
	v_cndmask_b32_e64 v0, 0, -1, s[6:7]
	v_add_co_u32_e64 v12, s[8:9], s10, v8
	v_mov_b32_e32 v1, v0
	s_nop 0
	v_addc_co_u32_e64 v13, s[8:9], 0, v9, s[8:9]
	s_movk_i32 s0, 0x6000
	v_lshlrev_b64 v[0:1], 13, v[0:1]
	v_add_co_u32_e64 v14, s[8:9], s0, v8
	v_lshl_add_u64 v[0:1], v[8:9], 0, v[0:1]
	s_nop 0
	v_addc_co_u32_e64 v15, s[8:9], 0, v9, s[8:9]
	v_cndmask_b32_e64 v122, 0, 1.0, s[6:7]
	s_lshl_b32 s6, s5, 8
	global_load_dwordx4 v[116:119], v[0:1], off offset:2560
	global_load_dwordx4 v[98:101], v[0:1], off offset:3584
	global_load_dwordx4 v[86:89], v[8:9], off offset:2560
	global_load_dwordx4 v[90:93], v[8:9], off offset:3584
	v_or_b32_e32 v0, 3, v2
	v_mov_b32_e32 v1, 0xff
	v_mov_b32_e32 v2, 0xfff
	s_ashr_i32 s7, s6, 31
	s_mul_i32 s8, s5, 0x300
	v_cndmask_b32_e32 v1, v1, v2, vcc
	s_ashr_i32 s9, s8, 31
	s_lshl_b64 s[6:7], s[6:7], 2
	v_cmp_lt_u32_e32 vcc, v0, v1
	v_mov_b32_e32 v0, 0x6000
	v_mov_b32_e32 v1, 0x8000
	s_add_u32 s10, s40, s6
	s_movk_i32 s0, 0x1000
	v_cndmask_b32_e32 v0, v0, v1, vcc
	v_mov_b32_e32 v1, v33
	s_addc_u32 s11, s41, s7
	v_add_co_u32_e64 v16, s[6:7], s0, v8
	v_lshl_add_u64 v[0:1], v[8:9], 0, v[0:1]
	s_nop 0
	v_addc_co_u32_e64 v17, s[6:7], 0, v9, s[6:7]
	s_movk_i32 s0, 0x3000
	global_load_dwordx4 v[102:105], v[10:11], off offset:2560
	global_load_dwordx4 v[94:97], v[10:11], off offset:3584
	global_load_dwordx4 v[74:77], v[12:13], off offset:2560
	global_load_dwordx4 v[70:73], v[12:13], off offset:3584
	global_load_dwordx4 v[58:61], v[14:15], off offset:2560
	global_load_dwordx4 v[54:57], v[14:15], off offset:3584
	global_load_dwordx4 v[4:7], v[0:1], off offset:2560
	s_nop 0
	global_load_dwordx4 v[0:3], v[0:1], off offset:3584
	v_lshlrev_b32_e32 v35, 2, v18
	global_load_dwordx4 v[110:113], v[8:9], off offset:3072
	global_load_dwordx4 v[106:109], v[16:17], off
	global_load_dwordx4 v[82:85], v[10:11], off offset:3072
	v_add_co_u32_e64 v10, s[6:7], s0, v8
	s_movk_i32 s0, 0x5000
	s_nop 0
	v_addc_co_u32_e64 v11, s[6:7], 0, v9, s[6:7]
	global_load_dwordx4 v[78:81], v[10:11], off
	global_load_dwordx4 v[66:69], v[12:13], off offset:3072
	v_add_co_u32_e64 v10, s[6:7], s0, v8
	s_movk_i32 s0, 0x7000
	s_nop 0
	v_addc_co_u32_e64 v11, s[6:7], 0, v9, s[6:7]
	v_add_co_u32_e64 v8, s[6:7], s0, v8
	global_load_dwordx4 v[62:65], v[10:11], off
	global_load_dwordx4 v[28:31], v[14:15], off offset:3072
	v_addc_co_u32_e64 v9, s[6:7], 0, v9, s[6:7]
	s_lshl_b64 s[6:7], s[8:9], 2
	s_add_u32 s6, s38, s6
	global_load_dwordx4 v[24:27], v[8:9], off
	s_addc_u32 s7, s39, s7
	global_load_dwordx4 v[8:11], v35, s[10:11] offset:16
	global_load_dwordx4 v[38:41], v35, s[10:11]
	global_load_dwordx4 v[12:15], v35, s[6:7] offset:16
	global_load_dwordx4 v[42:45], v35, s[6:7]
	global_load_dwordx4 v[16:19], v35, s[6:7] offset:1040
	global_load_dwordx4 v[46:49], v35, s[6:7] offset:1024
	global_load_dwordx4 v[20:23], v35, s[6:7] offset:2064
	global_load_dwordx4 v[50:53], v35, s[6:7] offset:2048
	v_cndmask_b32_e64 v114, 0, 1.0, vcc
	s_waitcnt vmcnt(14)
	v_lshlrev_b32_e32 v132, 16, v106
	v_mul_f32_e32 v35, 0xbfb8aa3b, v132
	v_exp_f32_e32 v35, v35
	v_and_b32_e32 v133, 0xffff0000, v106
	v_lshlrev_b32_e32 v120, 16, v116
	v_and_b32_e32 v121, 0xffff0000, v116
	v_add_f32_e32 v35, 1.0, v35
	v_rcp_f32_e32 v134, v35
	v_mul_f32_e32 v35, 0xbfb8aa3b, v133
	v_exp_f32_e32 v35, v35
	v_lshlrev_b32_e32 v128, 16, v117
	v_and_b32_e32 v129, 0xffff0000, v117
	v_lshlrev_b32_e32 v126, 16, v118
	v_and_b32_e32 v127, 0xffff0000, v118
	v_lshlrev_b32_e32 v124, 16, v119
	v_and_b32_e32 v125, 0xffff0000, v119
	v_lshlrev_b32_e32 v116, 16, v98
	v_and_b32_e32 v117, 0xffff0000, v98
	v_pk_mul_f32 v[118:119], v[122:123], v[120:121] op_sel_hi:[0,1]
	v_pk_mul_f32 v[120:121], v[118:119], v[116:117]
	v_lshlrev_b32_e32 v116, 16, v86
	v_and_b32_e32 v117, 0xffff0000, v86
	v_lshlrev_b32_e32 v118, 16, v90
	v_and_b32_e32 v119, 0xffff0000, v90
	v_pk_mul_f32 v[118:119], v[116:117], v[118:119]
	v_add_f32_e32 v35, 1.0, v35
	v_lshlrev_b32_e32 v116, 16, v102
	v_and_b32_e32 v117, 0xffff0000, v102
	v_lshlrev_b32_e32 v130, 16, v94
	v_and_b32_e32 v131, 0xffff0000, v94
	s_waitcnt vmcnt(2)
	v_pk_mul_f32 v[136:137], v[118:119], v[46:47]
	v_rcp_f32_e32 v135, v35
	v_pk_mul_f32 v[116:117], v[116:117], v[130:131]
	v_pk_fma_f32 v[120:121], v[120:121], v[42:43], v[136:137]
	v_lshlrev_b32_e32 v102, 16, v107
	s_waitcnt vmcnt(0)
	v_pk_fma_f32 v[120:121], v[116:117], v[50:51], v[120:121]
	v_lshlrev_b32_e32 v130, 16, v110
	v_and_b32_e32 v131, 0xffff0000, v110
	v_pk_add_f32 v[120:121], v[38:39], v[120:121]
	v_mul_f32_e32 v35, 0xbfb8aa3b, v102
	v_pk_mul_f32 v[120:121], v[120:121], v[130:131]
	v_pk_mul_f32 v[130:131], v[134:135], v[132:133]
	v_exp_f32_e32 v35, v35
	v_pk_mul_f32 v[120:121], v[130:131], v[120:121]
	v_lshlrev_b32_e32 v98, 16, v99
	v_cvt_pk_bf16_f32 v86, v120, v121
	v_and_b32_e32 v99, 0xffff0000, v99
	v_pk_mul_f32 v[120:121], v[122:123], v[128:129] op_sel_hi:[0,1]
	v_pk_mul_f32 v[98:99], v[120:121], v[98:99]
	v_lshlrev_b32_e32 v120, 16, v87
	v_and_b32_e32 v121, 0xffff0000, v87
	v_lshlrev_b32_e32 v90, 16, v91
	v_and_b32_e32 v91, 0xffff0000, v91
	v_pk_mul_f32 v[120:121], v[120:121], v[90:91]
	v_lshlrev_b32_e32 v90, 16, v103
	v_and_b32_e32 v91, 0xffff0000, v103
	v_and_b32_e32 v103, 0xffff0000, v107
	v_add_f32_e32 v35, 1.0, v35
	v_rcp_f32_e32 v106, v35
	v_mul_f32_e32 v35, 0xbfb8aa3b, v103
	v_exp_f32_e32 v35, v35
	v_lshlrev_b32_e32 v94, 16, v95
	v_and_b32_e32 v95, 0xffff0000, v95
	v_pk_mul_f32 v[94:95], v[90:91], v[94:95]
	v_lshlrev_b32_e32 v90, 16, v111
	v_and_b32_e32 v91, 0xffff0000, v111
	v_pk_mul_f32 v[110:111], v[120:121], v[48:49]
	v_add_f32_e32 v35, 1.0, v35
	v_pk_fma_f32 v[98:99], v[98:99], v[44:45], v[110:111]
	v_lshlrev_b32_e32 v110, 16, v108
	v_rcp_f32_e32 v107, v35
	v_mul_f32_e32 v35, 0xbfb8aa3b, v110
	v_exp_f32_e32 v35, v35
	v_pk_fma_f32 v[98:99], v[94:95], v[52:53], v[98:99]
	v_and_b32_e32 v111, 0xffff0000, v108
	v_pk_add_f32 v[98:99], v[40:41], v[98:99]
	v_add_f32_e32 v35, 1.0, v35
	v_pk_mul_f32 v[90:91], v[98:99], v[90:91]
	v_pk_mul_f32 v[98:99], v[106:107], v[102:103]
	v_lshlrev_b32_e32 v102, 16, v92
	v_pk_mul_f32 v[90:91], v[98:99], v[90:91]
	v_pk_mul_f32 v[98:99], v[122:123], v[126:127] op_sel_hi:[0,1]
	v_rcp_f32_e32 v126, v35
	v_mul_f32_e32 v35, 0xbfb8aa3b, v111
	v_exp_f32_e32 v35, v35
	v_cvt_pk_bf16_f32 v87, v90, v91
	v_lshlrev_b32_e32 v90, 16, v100
	v_and_b32_e32 v91, 0xffff0000, v100
	v_pk_mul_f32 v[90:91], v[98:99], v[90:91]
	v_lshlrev_b32_e32 v98, 16, v88
	v_and_b32_e32 v99, 0xffff0000, v88
	v_and_b32_e32 v103, 0xffff0000, v92
	v_pk_mul_f32 v[102:103], v[98:99], v[102:103]
	v_add_f32_e32 v35, 1.0, v35
	v_lshlrev_b32_e32 v98, 16, v104
	v_and_b32_e32 v99, 0xffff0000, v104
	v_lshlrev_b32_e32 v106, 16, v96
	v_and_b32_e32 v107, 0xffff0000, v96
	v_pk_mul_f32 v[128:129], v[102:103], v[16:17]
	v_rcp_f32_e32 v127, v35
	v_pk_mul_f32 v[98:99], v[98:99], v[106:107]
	v_pk_fma_f32 v[90:91], v[90:91], v[12:13], v[128:129]
	v_lshlrev_b32_e32 v104, 16, v109
	v_pk_fma_f32 v[90:91], v[98:99], v[20:21], v[90:91]
	v_lshlrev_b32_e32 v106, 16, v112
	v_and_b32_e32 v107, 0xffff0000, v112
	v_pk_add_f32 v[90:91], v[8:9], v[90:91]
	v_mul_f32_e32 v35, 0xbfb8aa3b, v104
	v_pk_mul_f32 v[90:91], v[90:91], v[106:107]
	v_pk_mul_f32 v[106:107], v[126:127], v[110:111]
	v_exp_f32_e32 v35, v35
	v_pk_mul_f32 v[90:91], v[106:107], v[90:91]
	v_lshlrev_b32_e32 v92, 16, v93
	v_cvt_pk_bf16_f32 v88, v90, v91
	v_lshlrev_b32_e32 v90, 16, v101
	v_and_b32_e32 v91, 0xffff0000, v101
	v_pk_mul_f32 v[100:101], v[122:123], v[124:125] op_sel_hi:[0,1]
	v_pk_mul_f32 v[90:91], v[100:101], v[90:91]
	v_lshlrev_b32_e32 v100, 16, v89
	v_and_b32_e32 v101, 0xffff0000, v89
	v_and_b32_e32 v93, 0xffff0000, v93
	v_pk_mul_f32 v[100:101], v[100:101], v[92:93]
	v_lshlrev_b32_e32 v92, 16, v105
	v_and_b32_e32 v93, 0xffff0000, v105
	v_and_b32_e32 v105, 0xffff0000, v109
	v_add_f32_e32 v35, 1.0, v35
	v_rcp_f32_e32 v106, v35
	v_mul_f32_e32 v35, 0xbfb8aa3b, v105
	v_exp_f32_e32 v35, v35
	v_lshlrev_b32_e32 v96, 16, v97
	v_and_b32_e32 v97, 0xffff0000, v97
	v_pk_mul_f32 v[108:109], v[100:101], v[18:19]
	v_add_f32_e32 v35, 1.0, v35
	v_rcp_f32_e32 v107, v35
	v_pk_mul_f32 v[92:93], v[92:93], v[96:97]
	v_pk_fma_f32 v[90:91], v[90:91], v[14:15], v[108:109]
	v_lshlrev_b32_e32 v96, 16, v113
	v_pk_fma_f32 v[90:91], v[92:93], v[22:23], v[90:91]
	v_and_b32_e32 v97, 0xffff0000, v113
	v_pk_add_f32 v[90:91], v[10:11], v[90:91]
	s_mov_b32 s0, 0x18c00000
	v_pk_mul_f32 v[90:91], v[90:91], v[96:97]
	v_pk_mul_f32 v[96:97], v[106:107], v[104:105]
	v_pk_mul_f32 v[106:107], v[116:117], v[46:47]
	v_pk_mul_f32 v[90:91], v[96:97], v[90:91]
	v_pk_fma_f32 v[106:107], v[118:119], v[42:43], v[106:107]
	v_cvt_pk_bf16_f32 v89, v90, v91
	v_mov_b64_e32 v[90:91], s[48:49]
	v_mad_i64_i32 v[96:97], s[6:7], v34, s44, v[90:91]
	v_lshl_add_u64 v[96:97], v[96:97], 0, v[32:33]
	v_add_co_u32_e32 v96, vcc, s0, v96
	s_mov_b64 s[10:11], 0
	s_nop 0
	v_addc_co_u32_e32 v97, vcc, 0, v97, vcc
	global_store_dwordx4 v[96:97], v[86:89], off offset:1024 sc1
	v_lshlrev_b32_e32 v96, 16, v78
	v_mul_f32_e32 v35, 0xbfb8aa3b, v96
	v_exp_f32_e32 v35, v35
	v_and_b32_e32 v97, 0xffff0000, v78
	v_lshlrev_b32_e32 v78, 16, v79
	v_lshlrev_b32_e32 v86, 16, v74
	v_add_f32_e32 v35, 1.0, v35
	v_rcp_f32_e32 v104, v35
	v_mul_f32_e32 v35, 0xbfb8aa3b, v97
	v_exp_f32_e32 v35, v35
	v_and_b32_e32 v87, 0xffff0000, v74
	v_lshlrev_b32_e32 v88, 16, v70
	v_and_b32_e32 v89, 0xffff0000, v70
	v_add_f32_e32 v35, 1.0, v35
	v_rcp_f32_e32 v105, v35
	v_mul_f32_e32 v35, 0xbfb8aa3b, v78
	v_exp_f32_e32 v35, v35
	v_and_b32_e32 v79, 0xffff0000, v79
	v_pk_mul_f32 v[88:89], v[86:87], v[88:89]
	v_lshlrev_b32_e32 v86, 16, v82
	v_add_f32_e32 v35, 1.0, v35
	v_and_b32_e32 v87, 0xffff0000, v82
	v_rcp_f32_e32 v82, v35
	v_mul_f32_e32 v35, 0xbfb8aa3b, v79
	v_pk_fma_f32 v[106:107], v[88:89], v[50:51], v[106:107]
	v_exp_f32_e32 v35, v35
	v_pk_add_f32 v[106:107], v[38:39], v[106:107]
	v_pk_mul_f32 v[96:97], v[104:105], v[96:97]
	v_pk_mul_f32 v[86:87], v[106:107], v[86:87]
	v_lshlrev_b32_e32 v74, 16, v75
	v_pk_mul_f32 v[86:87], v[96:97], v[86:87]
	v_and_b32_e32 v75, 0xffff0000, v75
	v_cvt_pk_bf16_f32 v70, v86, v87
	v_lshlrev_b32_e32 v86, 16, v71
	v_and_b32_e32 v87, 0xffff0000, v71
	v_add_f32_e32 v35, 1.0, v35
	v_pk_mul_f32 v[86:87], v[74:75], v[86:87]
	v_lshlrev_b32_e32 v74, 16, v83
	v_and_b32_e32 v75, 0xffff0000, v83
	v_rcp_f32_e32 v83, v35
	v_pk_mul_f32 v[96:97], v[94:95], v[48:49]
	v_pk_mul_f32 v[104:105], v[98:99], v[16:17]
	v_pk_fma_f32 v[96:97], v[120:121], v[44:45], v[96:97]
	v_pk_mul_f32 v[78:79], v[82:83], v[78:79]
	v_lshlrev_b32_e32 v82, 16, v80
	v_mul_f32_e32 v35, 0xbfb8aa3b, v82
	v_exp_f32_e32 v35, v35
	v_pk_fma_f32 v[96:97], v[86:87], v[52:53], v[96:97]
	v_and_b32_e32 v83, 0xffff0000, v80
	v_pk_add_f32 v[96:97], v[40:41], v[96:97]
	v_add_f32_e32 v35, 1.0, v35
	v_pk_mul_f32 v[74:75], v[96:97], v[74:75]
	v_rcp_f32_e32 v96, v35
	v_mul_f32_e32 v35, 0xbfb8aa3b, v83
	v_exp_f32_e32 v35, v35
	v_lshlrev_b32_e32 v80, 16, v81
	v_pk_mul_f32 v[74:75], v[78:79], v[74:75]
	v_lshlrev_b32_e32 v78, 16, v72
	v_add_f32_e32 v35, 1.0, v35
	v_rcp_f32_e32 v97, v35
	v_mul_f32_e32 v35, 0xbfb8aa3b, v80
	v_cvt_pk_bf16_f32 v71, v74, v75
	v_lshlrev_b32_e32 v74, 16, v76
	v_and_b32_e32 v75, 0xffff0000, v76
	v_and_b32_e32 v79, 0xffff0000, v72
	v_exp_f32_e32 v35, v35
	v_pk_mul_f32 v[78:79], v[74:75], v[78:79]
	v_pk_fma_f32 v[102:103], v[102:103], v[12:13], v[104:105]
	v_lshlrev_b32_e32 v74, 16, v84
	v_pk_fma_f32 v[102:103], v[78:79], v[20:21], v[102:103]
	v_and_b32_e32 v75, 0xffff0000, v84
	v_pk_add_f32 v[102:103], v[8:9], v[102:103]
	v_pk_mul_f32 v[82:83], v[96:97], v[82:83]
	v_pk_mul_f32 v[74:75], v[102:103], v[74:75]
	v_and_b32_e32 v81, 0xffff0000, v81
	v_add_f32_e32 v35, 1.0, v35
	v_pk_mul_f32 v[74:75], v[82:83], v[74:75]
	v_rcp_f32_e32 v82, v35
	v_mul_f32_e32 v35, 0xbfb8aa3b, v81
	v_exp_f32_e32 v35, v35
	v_cvt_pk_bf16_f32 v72, v74, v75
	v_lshlrev_b32_e32 v74, 16, v77
	v_and_b32_e32 v75, 0xffff0000, v77
	v_lshlrev_b32_e32 v76, 16, v73
	v_and_b32_e32 v77, 0xffff0000, v73
	v_add_f32_e32 v35, 1.0, v35
	v_pk_mul_f32 v[74:75], v[74:75], v[76:77]
	v_lshlrev_b32_e32 v76, 16, v85
	v_and_b32_e32 v77, 0xffff0000, v85
	v_pk_mul_f32 v[84:85], v[92:93], v[18:19]
	v_rcp_f32_e32 v83, v35
	v_pk_fma_f32 v[84:85], v[100:101], v[14:15], v[84:85]
	v_or_b32_e32 v35, 1, v34
	v_pk_fma_f32 v[84:85], v[74:75], v[22:23], v[84:85]
	v_pk_mul_f32 v[80:81], v[82:83], v[80:81]
	v_pk_add_f32 v[84:85], v[10:11], v[84:85]
	v_pk_mul_f32 v[82:83], v[88:89], v[46:47]
	v_pk_mul_f32 v[76:77], v[84:85], v[76:77]
	v_pk_fma_f32 v[82:83], v[116:117], v[42:43], v[82:83]
	v_pk_mul_f32 v[76:77], v[80:81], v[76:77]
	s_nop 0
	v_cvt_pk_bf16_f32 v73, v76, v77
	v_mad_i64_i32 v[76:77], s[6:7], v35, s44, v[90:91]
	v_lshl_add_u64 v[76:77], v[76:77], 0, v[32:33]
	v_add_co_u32_e32 v76, vcc, s0, v76
	s_nop 1
	v_addc_co_u32_e32 v77, vcc, 0, v77, vcc
	global_store_dwordx4 v[76:77], v[70:73], off offset:1024 sc1
	v_lshlrev_b32_e32 v76, 16, v62
	v_mul_f32_e32 v35, 0xbfb8aa3b, v76
	v_exp_f32_e32 v35, v35
	v_and_b32_e32 v77, 0xffff0000, v62
	v_lshlrev_b32_e32 v62, 16, v63
	v_lshlrev_b32_e32 v70, 16, v58
	v_add_f32_e32 v35, 1.0, v35
	v_rcp_f32_e32 v80, v35
	v_mul_f32_e32 v35, 0xbfb8aa3b, v77
	v_exp_f32_e32 v35, v35
	v_and_b32_e32 v71, 0xffff0000, v58
	v_lshlrev_b32_e32 v72, 16, v54
	v_and_b32_e32 v73, 0xffff0000, v54
	v_add_f32_e32 v35, 1.0, v35
	v_rcp_f32_e32 v81, v35
	v_mul_f32_e32 v35, 0xbfb8aa3b, v62
	v_exp_f32_e32 v35, v35
	v_and_b32_e32 v63, 0xffff0000, v63
	v_pk_mul_f32 v[72:73], v[70:71], v[72:73]
	v_lshlrev_b32_e32 v70, 16, v66
	v_add_f32_e32 v35, 1.0, v35
	v_and_b32_e32 v71, 0xffff0000, v66
	v_rcp_f32_e32 v66, v35
	v_mul_f32_e32 v35, 0xbfb8aa3b, v63
	v_pk_fma_f32 v[82:83], v[72:73], v[50:51], v[82:83]
	v_exp_f32_e32 v35, v35
	v_pk_add_f32 v[82:83], v[38:39], v[82:83]
	v_pk_mul_f32 v[76:77], v[80:81], v[76:77]
	v_pk_mul_f32 v[70:71], v[82:83], v[70:71]
	v_lshlrev_b32_e32 v58, 16, v59
	v_pk_mul_f32 v[70:71], v[76:77], v[70:71]
	v_and_b32_e32 v59, 0xffff0000, v59
	v_cvt_pk_bf16_f32 v54, v70, v71
	v_lshlrev_b32_e32 v70, 16, v55
	v_and_b32_e32 v71, 0xffff0000, v55
	v_add_f32_e32 v35, 1.0, v35
	v_pk_mul_f32 v[70:71], v[58:59], v[70:71]
	v_lshlrev_b32_e32 v58, 16, v67
	v_and_b32_e32 v59, 0xffff0000, v67
	v_rcp_f32_e32 v67, v35
	v_pk_mul_f32 v[76:77], v[86:87], v[48:49]
	v_pk_mul_f32 v[80:81], v[78:79], v[16:17]
	v_pk_fma_f32 v[76:77], v[94:95], v[44:45], v[76:77]
	v_pk_mul_f32 v[62:63], v[66:67], v[62:63]
	v_lshlrev_b32_e32 v66, 16, v64
	v_mul_f32_e32 v35, 0xbfb8aa3b, v66
	v_exp_f32_e32 v35, v35
	v_pk_fma_f32 v[76:77], v[70:71], v[52:53], v[76:77]
	v_and_b32_e32 v67, 0xffff0000, v64
	v_pk_add_f32 v[76:77], v[40:41], v[76:77]
	v_add_f32_e32 v35, 1.0, v35
	v_pk_mul_f32 v[58:59], v[76:77], v[58:59]
	v_rcp_f32_e32 v76, v35
	v_mul_f32_e32 v35, 0xbfb8aa3b, v67
	v_exp_f32_e32 v35, v35
	v_lshlrev_b32_e32 v64, 16, v65
	v_pk_mul_f32 v[58:59], v[62:63], v[58:59]
	v_lshlrev_b32_e32 v62, 16, v56
	v_add_f32_e32 v35, 1.0, v35
	v_rcp_f32_e32 v77, v35
	v_mul_f32_e32 v35, 0xbfb8aa3b, v64
	v_cvt_pk_bf16_f32 v55, v58, v59
	v_lshlrev_b32_e32 v58, 16, v60
	v_and_b32_e32 v59, 0xffff0000, v60
	v_and_b32_e32 v63, 0xffff0000, v56
	v_exp_f32_e32 v35, v35
	v_pk_mul_f32 v[62:63], v[58:59], v[62:63]
	v_pk_fma_f32 v[80:81], v[98:99], v[12:13], v[80:81]
	v_lshlrev_b32_e32 v58, 16, v68
	v_pk_fma_f32 v[80:81], v[62:63], v[20:21], v[80:81]
	v_and_b32_e32 v59, 0xffff0000, v68
	v_pk_add_f32 v[80:81], v[8:9], v[80:81]
	v_pk_mul_f32 v[66:67], v[76:77], v[66:67]
	v_pk_mul_f32 v[58:59], v[80:81], v[58:59]
	v_and_b32_e32 v65, 0xffff0000, v65
	v_add_f32_e32 v35, 1.0, v35
	v_pk_mul_f32 v[58:59], v[66:67], v[58:59]
	v_rcp_f32_e32 v66, v35
	v_mul_f32_e32 v35, 0xbfb8aa3b, v65
	v_exp_f32_e32 v35, v35
	v_cvt_pk_bf16_f32 v56, v58, v59
	v_lshlrev_b32_e32 v58, 16, v61
	v_and_b32_e32 v59, 0xffff0000, v61
	v_lshlrev_b32_e32 v60, 16, v57
	v_and_b32_e32 v61, 0xffff0000, v57
	v_add_f32_e32 v35, 1.0, v35
	v_pk_mul_f32 v[58:59], v[58:59], v[60:61]
	v_lshlrev_b32_e32 v60, 16, v69
	v_and_b32_e32 v61, 0xffff0000, v69
	v_pk_mul_f32 v[68:69], v[74:75], v[18:19]
	v_rcp_f32_e32 v67, v35
	v_pk_fma_f32 v[68:69], v[92:93], v[14:15], v[68:69]
	v_or_b32_e32 v35, 2, v34
	v_pk_fma_f32 v[68:69], v[58:59], v[22:23], v[68:69]
	v_pk_mul_f32 v[64:65], v[66:67], v[64:65]
	v_pk_add_f32 v[68:69], v[10:11], v[68:69]
	v_pk_mul_f32 v[46:47], v[72:73], v[46:47]
	v_pk_mul_f32 v[60:61], v[68:69], v[60:61]
	v_pk_fma_f32 v[42:43], v[88:89], v[42:43], v[46:47]
	v_pk_mul_f32 v[60:61], v[64:65], v[60:61]
	v_pk_mul_f32 v[16:17], v[62:63], v[16:17]
	v_cvt_pk_bf16_f32 v57, v60, v61
	v_mad_i64_i32 v[60:61], s[6:7], v35, s44, v[90:91]
	v_lshl_add_u64 v[60:61], v[60:61], 0, v[32:33]
	v_add_co_u32_e32 v60, vcc, s0, v60
	v_pk_fma_f32 v[12:13], v[78:79], v[12:13], v[16:17]
	s_nop 0
	v_addc_co_u32_e32 v61, vcc, 0, v61, vcc
	global_store_dwordx4 v[60:61], v[54:57], off offset:1024 sc1
	v_lshlrev_b32_e32 v60, 16, v24
	v_and_b32_e32 v61, 0xffff0000, v24
	v_lshlrev_b32_e32 v56, 16, v0
	v_and_b32_e32 v57, 0xffff0000, v0
	v_mul_f32_e32 v0, 0xbfb8aa3b, v60
	v_exp_f32_e32 v0, v0
	v_lshlrev_b32_e32 v54, 16, v4
	v_and_b32_e32 v55, 0xffff0000, v4
	v_pk_mul_f32 v[54:55], v[114:115], v[54:55] op_sel_hi:[0,1]
	v_add_f32_e32 v0, 1.0, v0
	v_rcp_f32_e32 v64, v0
	v_mul_f32_e32 v0, 0xbfb8aa3b, v61
	v_exp_f32_e32 v0, v0
	v_pk_mul_f32 v[54:55], v[54:55], v[56:57]
	v_lshlrev_b32_e32 v56, 16, v28
	v_pk_fma_f32 v[42:43], v[54:55], v[50:51], v[42:43]
	v_add_f32_e32 v0, 1.0, v0
	v_rcp_f32_e32 v65, v0
	v_and_b32_e32 v57, 0xffff0000, v28
	v_pk_add_f32 v[38:39], v[38:39], v[42:43]
	v_lshlrev_b32_e32 v24, 16, v25
	v_pk_mul_f32 v[38:39], v[38:39], v[56:57]
	v_pk_mul_f32 v[42:43], v[64:65], v[60:61]
	v_lshlrev_b32_e32 v4, 16, v5
	v_pk_mul_f32 v[38:39], v[42:43], v[38:39]
	v_and_b32_e32 v5, 0xffff0000, v5
	v_cvt_pk_bf16_f32 v0, v38, v39
	v_lshlrev_b32_e32 v38, 16, v1
	v_and_b32_e32 v39, 0xffff0000, v1
	v_mul_f32_e32 v1, 0xbfb8aa3b, v24
	v_exp_f32_e32 v1, v1
	v_pk_mul_f32 v[4:5], v[114:115], v[4:5] op_sel_hi:[0,1]
	v_and_b32_e32 v25, 0xffff0000, v25
	v_pk_mul_f32 v[4:5], v[4:5], v[38:39]
	v_add_f32_e32 v1, 1.0, v1
	v_rcp_f32_e32 v38, v1
	v_mul_f32_e32 v1, 0xbfb8aa3b, v25
	v_exp_f32_e32 v1, v1
	v_pk_mul_f32 v[42:43], v[70:71], v[48:49]
	v_lshlrev_b32_e32 v28, 16, v29
	v_pk_fma_f32 v[42:43], v[86:87], v[44:45], v[42:43]
	v_add_f32_e32 v1, 1.0, v1
	v_rcp_f32_e32 v39, v1
	v_pk_fma_f32 v[4:5], v[4:5], v[52:53], v[42:43]
	v_and_b32_e32 v29, 0xffff0000, v29
	v_pk_add_f32 v[4:5], v[40:41], v[4:5]
	v_pk_mul_f32 v[24:25], v[38:39], v[24:25]
	v_pk_mul_f32 v[4:5], v[4:5], v[28:29]
	v_lshlrev_b32_e32 v28, 16, v26
	v_pk_mul_f32 v[4:5], v[24:25], v[4:5]
	v_lshlrev_b32_e32 v24, 16, v2
	v_and_b32_e32 v25, 0xffff0000, v2
	v_mul_f32_e32 v2, 0xbfb8aa3b, v28
	v_exp_f32_e32 v2, v2
	v_and_b32_e32 v29, 0xffff0000, v26
	v_cvt_pk_bf16_f32 v1, v4, v5
	v_lshlrev_b32_e32 v4, 16, v6
	v_add_f32_e32 v2, 1.0, v2
	v_rcp_f32_e32 v38, v2
	v_mul_f32_e32 v2, 0xbfb8aa3b, v29
	v_exp_f32_e32 v2, v2
	v_and_b32_e32 v5, 0xffff0000, v6
	v_pk_mul_f32 v[4:5], v[114:115], v[4:5] op_sel_hi:[0,1]
	v_pk_mul_f32 v[4:5], v[4:5], v[24:25]
	v_add_f32_e32 v2, 1.0, v2
	v_rcp_f32_e32 v39, v2
	v_pk_fma_f32 v[4:5], v[4:5], v[20:21], v[12:13]
	v_lshlrev_b32_e32 v24, 16, v30
	v_and_b32_e32 v25, 0xffff0000, v30
	v_pk_add_f32 v[4:5], v[8:9], v[4:5]
	v_pk_mul_f32 v[8:9], v[38:39], v[28:29]
	v_pk_mul_f32 v[4:5], v[4:5], v[24:25]
	v_lshlrev_b32_e32 v6, 16, v3
	v_pk_mul_f32 v[4:5], v[8:9], v[4:5]
	v_lshlrev_b32_e32 v8, 16, v27
	v_cvt_pk_bf16_f32 v2, v4, v5
	v_lshlrev_b32_e32 v4, 16, v7
	v_and_b32_e32 v5, 0xffff0000, v7
	v_and_b32_e32 v7, 0xffff0000, v3
	v_mul_f32_e32 v3, 0xbfb8aa3b, v8
	v_exp_f32_e32 v3, v3
	v_and_b32_e32 v9, 0xffff0000, v27
	v_pk_mul_f32 v[4:5], v[114:115], v[4:5] op_sel_hi:[0,1]
	v_pk_mul_f32 v[16:17], v[58:59], v[18:19]
	v_add_f32_e32 v3, 1.0, v3
	v_rcp_f32_e32 v12, v3
	v_mul_f32_e32 v3, 0xbfb8aa3b, v9
	v_exp_f32_e32 v3, v3
	v_pk_mul_f32 v[4:5], v[4:5], v[6:7]
	v_pk_fma_f32 v[14:15], v[74:75], v[14:15], v[16:17]
	v_lshlrev_b32_e32 v6, 16, v31
	v_add_f32_e32 v3, 1.0, v3
	v_rcp_f32_e32 v13, v3
	v_pk_fma_f32 v[4:5], v[4:5], v[22:23], v[14:15]
	v_and_b32_e32 v7, 0xffff0000, v31
	v_pk_add_f32 v[4:5], v[10:11], v[4:5]
	s_nop 0
	v_pk_mul_f32 v[4:5], v[4:5], v[6:7]
	v_pk_mul_f32 v[6:7], v[12:13], v[8:9]
	s_nop 0
	v_pk_mul_f32 v[4:5], v[6:7], v[4:5]
	s_nop 0
	v_cvt_pk_bf16_f32 v3, v4, v5
	v_or_b32_e32 v4, 3, v34
	v_mad_i64_i32 v[4:5], s[6:7], v4, s44, v[90:91]
	v_lshl_add_u64 v[4:5], v[4:5], 0, v[32:33]
	v_add_co_u32_e32 v4, vcc, 0x18c00000, v4
	s_nop 1
	v_addc_co_u32_e32 v5, vcc, 0, v5, vcc
	global_store_dwordx4 v[4:5], v[0:3], off offset:1024 sc1
	s_branch .LBB0_660

.LBB0_694:
	s_or_b64 exec, exec, s[6:7]
	v_readlane_b32 s6, v254, 52
	s_movk_i32 s13, 0x48
	v_or_b32_e32 v21, 32, v38
	v_or_b32_e32 v69, s6, v37
	v_mad_u64_u32 v[0:1], s[6:7], v69, s13, v[38:39]
	v_lshl_add_u32 v70, v0, 1, 0
	v_mad_u32_u24 v0, v37, s13, v38
	v_lshl_add_u32 v71, v0, 1, 0
	v_mov_b32_e32 v0, 0x480
	v_mad_u32_u24 v4, v37, s13, v0
	v_add_u32_e32 v0, v38, v4
	v_lshl_add_u32 v72, v0, 1, 0
	v_mov_b32_e32 v0, 0x900
	v_mad_u32_u24 v5, v37, s13, v0
	v_add_u32_e32 v0, v38, v5
	v_lshl_add_u32 v74, v0, 1, 0
	v_mov_b32_e32 v0, 0xd80
	v_mad_u32_u24 v6, v37, s13, v0
	v_add_u32_e32 v0, v38, v6
	v_lshl_add_u32 v76, v0, 1, 0
	v_mov_b32_e32 v0, 0x1200
	v_mad_u32_u24 v7, v37, s13, v0
	v_add_u32_e32 v0, v38, v7
	v_lshl_add_u32 v73, v0, 1, 0
	v_mov_b32_e32 v0, 0x1680
	v_mad_u32_u24 v8, v37, s13, v0
	v_add_u32_e32 v0, v38, v8
	v_lshl_add_u32 v75, v0, 1, 0
	v_mov_b32_e32 v0, 0x1b00
	v_mad_u32_u24 v9, v37, s13, v0
	v_add_u32_e32 v0, v38, v9
	v_lshl_add_u32 v77, v0, 1, 0
	v_mov_b32_e32 v0, 0x1f80
	v_add_u32_e32 v4, v21, v4
	v_mad_u32_u24 v20, v37, s13, v0
	v_lshl_add_u32 v80, v4, 1, 0
	v_add_u32_e32 v4, v21, v5
	v_add_u32_e32 v0, v38, v20
	v_lshl_add_u32 v82, v4, 1, 0
	v_add_u32_e32 v4, v21, v6
	v_add_u32_e32 v8, v21, v8
	v_lshl_add_u32 v78, v0, 1, 0
	v_mad_u32_u24 v10, v37, s13, v21
	v_lshl_add_u32 v118, v4, 1, 0
	v_add_u32_e32 v4, v21, v7
	v_lshl_add_u32 v83, v8, 1, 0
	v_add_u32_e32 v8, v21, v9
	v_add_u32_e32 v20, v21, v20
	v_lshlrev_b32_e32 v68, 2, v41
	s_waitcnt lgkmcnt(0)
	s_barrier
	ds_read_b128 v[46:49], v70 offset:18432
	ds_read_b128 v[24:27], v71 offset:55296
	ds_read_b128 v[28:31], v72 offset:55296
	ds_read_b128 v[54:57], v73 offset:55296
	ds_read_b128 v[40:43], v74 offset:55296
	ds_read_b128 v[58:61], v75 offset:55296
	ds_read_b128 v[50:53], v76 offset:55296
	ds_read_b128 v[84:87], v77 offset:55296
	ds_read_b128 v[88:91], v78 offset:55296
	ds_read_b128 v[0:3], v70 offset:18496
	v_lshl_add_u32 v79, v10, 1, 0
	v_lshl_add_u32 v81, v4, 1, 0
	v_lshl_add_u32 v119, v8, 1, 0
	v_lshl_add_u32 v120, v20, 1, 0
	ds_read_b128 v[92:95], v79 offset:55296
	ds_read_b128 v[96:99], v80 offset:55296
	ds_read_b128 v[100:103], v82 offset:55296
	ds_read_b128 v[4:7], v81 offset:55296
	ds_read_b128 v[12:15], v118 offset:55296
	ds_read_b128 v[16:19], v83 offset:55296
	ds_read_b128 v[8:11], v119 offset:55296
	ds_read_b128 v[20:23], v120 offset:55296
	s_waitcnt lgkmcnt(14)
	v_mfma_f32_16x16x32_bf16 v[104:107], v[24:27], v[46:49], 0
	v_add_u32_e32 v24, 1, v69
	v_cvt_f32_i32_e32 v24, v24
	s_add_i32 s6, 0, 0x17000
	s_waitcnt lgkmcnt(13)
	v_mfma_f32_16x16x32_bf16 v[112:115], v[40:43], v[46:49], 0
	v_sub_u32_e32 v42, v69, v68
	v_mul_f32_e64 v24, v24, -v39
	v_lshl_add_u32 v121, v42, 2, s6
	v_lshrrev_b32_e32 v42, 2, v37
	v_exp_f32_e32 v32, v24
	s_waitcnt lgkmcnt(11)
	v_mfma_f32_16x16x32_bf16 v[24:27], v[50:53], v[46:49], 0
	v_or_b32_e32 v50, v68, v42
	v_lshlrev_b32_e32 v37, 2, v37
	v_mul_u32_u24_e32 v50, 0x50, v50
	v_mfma_f32_16x16x32_bf16 v[108:111], v[28:31], v[46:49], 0
	v_not_b32_e32 v28, v68
	v_lshlrev_b32_e32 v38, 2, v69
	v_lshlrev_b32_e32 v39, 2, v28
	v_and_or_b32 v37, v37, 12, v50
	v_mfma_f32_16x16x32_bf16 v[28:31], v[54:57], v[46:49], 0
	v_add3_u32 v38, s6, v38, v39
	v_lshlrev_b32_e32 v37, 1, v37
	v_readlane_b32 s6, v254, 11
	v_readlane_b32 s7, v254, 12
	v_readlane_b32 s13, v254, 13
	v_add_u32_e32 v50, s0, v37
	v_add_u32_e32 v52, s6, v37
	v_add_u32_e32 v54, s7, v37
	v_add_u32_e32 v55, s13, v37
	ds_read2_b32 v[116:117], v38 offset0:127 offset1:128
	v_mfma_f32_16x16x32_bf16 v[38:41], v[58:61], v[46:49], 0
	ds_read_b64_tr_b16 v[58:59], v50
	ds_read_b64_tr_b16 v[60:61], v50 offset:2560
	ds_read_b64_tr_b16 v[50:51], v52
	ds_read_b64_tr_b16 v[52:53], v52 offset:2560
	s_waitcnt lgkmcnt(14)
	v_mfma_f32_16x16x32_bf16 v[42:45], v[84:87], v[46:49], 0
	v_mfma_f32_16x16x32_bf16 v[46:49], v[88:91], v[46:49], 0
	s_waitcnt lgkmcnt(12)
	v_mfma_f32_16x16x32_bf16 v[84:87], v[92:95], v[0:3], v[104:107]
	s_waitcnt lgkmcnt(11)
	v_mfma_f32_16x16x32_bf16 v[88:91], v[96:99], v[0:3], v[108:111]
	ds_read_b64_tr_b16 v[92:93], v54
	ds_read_b64_tr_b16 v[94:95], v54 offset:2560
	ds_read_b64_tr_b16 v[96:97], v55
	ds_read_b64_tr_b16 v[98:99], v55 offset:2560
	s_waitcnt lgkmcnt(8)
	v_pk_mul_f32 v[106:107], v[32:33], v[116:117] op_sel:[0,1] op_sel_hi:[0,0]
	v_mfma_f32_16x16x32_bf16 v[54:57], v[100:103], v[0:3], v[112:115]
	ds_read2_b32 v[100:101], v121 offset0:28 offset1:29
	ds_read2_b32 v[102:103], v121 offset0:14 offset1:15
	ds_read2_b32 v[104:105], v121 offset0:12 offset1:13
	v_mfma_f32_16x16x32_bf16 v[12:15], v[12:15], v[0:3], v[24:27]
	s_nop 2
	ds_read2_b32 v[26:27], v121 offset0:124 offset1:125
	v_mfma_f32_16x16x32_bf16 v[4:7], v[4:7], v[0:3], v[28:31]
	v_mul_f32_e64 v24, v84, v106
	v_mul_f32_e64 v25, v85, v107
	ds_read2_b32 v[84:85], v121 offset0:94 offset1:95
	v_cvt_pk_bf16_f32 v24, v24, v25
	ds_read2_b32 v[28:29], v121 offset0:110 offset1:111
	ds_read2_b32 v[30:31], v121 offset0:108 offset1:109
	s_waitcnt lgkmcnt(3)
	v_pk_mul_f32 v[26:27], v[32:33], v[26:27] op_sel_hi:[0,1]
	v_pk_mul_f32 v[26:27], v[86:87], v[26:27] op_sel:[0,1] op_sel_hi:[1,0]
	v_mfma_f32_16x16x32_bf16 v[16:19], v[16:19], v[0:3], v[38:41]
	v_cvt_pk_bf16_f32 v25, v26, v27
	s_waitcnt lgkmcnt(1)
	v_pk_mul_f32 v[26:27], v[32:33], v[28:29] op_sel_hi:[0,1]
	v_pk_mul_f32 v[26:27], v[88:89], v[26:27] op_sel:[0,1] op_sel_hi:[1,0]
	v_mfma_f32_16x16x32_bf16 v[8:11], v[8:11], v[0:3], v[42:45]
	v_cvt_pk_bf16_f32 v26, v26, v27
	v_pk_mul_f32 v[84:85], v[32:33], v[84:85] op_sel_hi:[0,1]
	v_pk_mul_f32 v[54:55], v[54:55], v[84:85] op_sel:[0,1] op_sel_hi:[1,0]
	v_mfma_f32_16x16x32_bf16 v[0:3], v[20:23], v[0:3], v[46:49]
	s_waitcnt lgkmcnt(0)
	v_pk_mul_f32 v[20:21], v[32:33], v[30:31] op_sel_hi:[0,1]
	v_pk_mul_f32 v[20:21], v[90:91], v[20:21] op_sel:[0,1] op_sel_hi:[1,0]
	v_cvt_pk_bf16_f32 v54, v54, v55
	v_cvt_pk_bf16_f32 v27, v20, v21
	v_add_u32_e32 v46, 0x1400, v37
	v_add_u32_e32 v40, s0, v46
	v_mfma_f32_16x16x32_bf16 v[20:23], v[58:61], v[24:27], 0
	v_add_u32_e32 v44, s6, v46
	v_add_u32_e32 v60, s13, v46
	ds_read_b64_tr_b16 v[38:39], v40
	ds_read_b64_tr_b16 v[40:41], v40 offset:2560
	ds_read_b64_tr_b16 v[42:43], v44
	ds_read_b64_tr_b16 v[44:45], v44 offset:2560
	v_mfma_f32_16x16x32_bf16 v[28:31], v[50:53], v[24:27], 0
	v_add_u32_e32 v52, s7, v46
	ds_read_b64_tr_b16 v[50:51], v52
	ds_read_b64_tr_b16 v[52:53], v52 offset:2560
	ds_read_b64_tr_b16 v[58:59], v60
	ds_read_b64_tr_b16 v[60:61], v60 offset:2560
	ds_read2_b32 v[86:87], v121 offset0:92 offset1:93
	ds_read2_b32 v[84:85], v121 offset0:78 offset1:79
	v_mfma_f32_16x16x32_bf16 v[46:49], v[92:95], v[24:27], 0
	s_waitcnt lgkmcnt(1)
	v_pk_mul_f32 v[86:87], v[32:33], v[86:87] op_sel_hi:[0,1]
	v_pk_mul_f32 v[56:57], v[56:57], v[86:87] op_sel:[0,1] op_sel_hi:[1,0]
	ds_read2_b32 v[86:87], v121 offset0:76 offset1:77
	v_cvt_pk_bf16_f32 v55, v56, v57
	s_waitcnt lgkmcnt(1)
	v_pk_mul_f32 v[56:57], v[32:33], v[84:85] op_sel_hi:[0,1]
	v_pk_mul_f32 v[12:13], v[12:13], v[56:57] op_sel:[0,1] op_sel_hi:[1,0]
	v_mfma_f32_16x16x32_bf16 v[24:27], v[96:99], v[24:27], 0
	v_cvt_pk_bf16_f32 v56, v12, v13
	ds_read2_b32 v[84:85], v121 offset0:62 offset1:63
	s_waitcnt lgkmcnt(1)
	v_pk_mul_f32 v[12:13], v[32:33], v[86:87] op_sel_hi:[0,1]
	v_pk_mul_f32 v[12:13], v[14:15], v[12:13] op_sel:[0,1] op_sel_hi:[1,0]
	v_add_u32_e32 v86, 0x2800, v37
	v_cvt_pk_bf16_f32 v57, v12, v13
	v_add_u32_e32 v87, s7, v86
	v_add_u32_e32 v37, 0x3c00, v37
	v_mfma_f32_16x16x32_bf16 v[12:15], v[38:41], v[54:57], v[20:23]
	v_add_u32_e32 v38, s0, v86
	v_add_u32_e32 v40, s6, v86
	v_add_u32_e32 v86, s13, v86
	v_mfma_f32_16x16x32_bf16 v[20:23], v[42:45], v[54:57], v[28:31]
	s_nop 2
	ds_read_b64_tr_b16 v[28:29], v38
	ds_read_b64_tr_b16 v[30:31], v38 offset:2560
	ds_read_b64_tr_b16 v[38:39], v40
	ds_read_b64_tr_b16 v[40:41], v40 offset:2560
	v_mfma_f32_16x16x32_bf16 v[42:45], v[50:53], v[54:57], v[46:49]
	s_nop 2
	ds_read_b64_tr_b16 v[46:47], v87
	ds_read_b64_tr_b16 v[48:49], v87 offset:2560
	ds_read_b64_tr_b16 v[50:51], v86
	ds_read_b64_tr_b16 v[52:53], v86 offset:2560
	v_mfma_f32_16x16x32_bf16 v[24:27], v[58:61], v[54:57], v[24:27]
	ds_read2_b32 v[54:55], v121 offset0:60 offset1:61
	s_waitcnt lgkmcnt(9)
	v_pk_mul_f32 v[56:57], v[32:33], v[84:85] op_sel_hi:[0,1]
	v_pk_mul_f32 v[4:5], v[4:5], v[56:57] op_sel:[0,1] op_sel_hi:[1,0]
	ds_read2_b32 v[56:57], v121 offset0:46 offset1:47
	v_cvt_pk_bf16_f32 v4, v4, v5
	s_waitcnt lgkmcnt(1)
	v_pk_mul_f32 v[54:55], v[32:33], v[54:55] op_sel_hi:[0,1]
	v_pk_mul_f32 v[6:7], v[6:7], v[54:55] op_sel:[0,1] op_sel_hi:[1,0]
	ds_read2_b32 v[54:55], v121 offset0:44 offset1:45
	v_cvt_pk_bf16_f32 v5, v6, v7
	s_waitcnt lgkmcnt(1)
	v_pk_mul_f32 v[6:7], v[32:33], v[56:57] op_sel_hi:[0,1]
	v_pk_mul_f32 v[6:7], v[16:17], v[6:7] op_sel:[0,1] op_sel_hi:[1,0]
	ds_read2_b32 v[56:57], v121 offset0:30 offset1:31
	s_waitcnt lgkmcnt(1)
	v_pk_mul_f32 v[16:17], v[32:33], v[54:55] op_sel_hi:[0,1]
	v_pk_mul_f32 v[16:17], v[18:19], v[16:17] op_sel:[0,1] op_sel_hi:[1,0]
	v_cvt_pk_bf16_f32 v6, v6, v7
	v_cvt_pk_bf16_f32 v7, v16, v17
	v_add_u32_e32 v54, s7, v37
	s_nop 0
	v_mfma_f32_16x16x32_bf16 v[12:15], v[28:31], v[4:7], v[12:15]
	v_add_u32_e32 v28, s0, v37
	v_add_u32_e32 v30, s6, v37
	v_add_u32_e32 v37, s13, v37
	v_mfma_f32_16x16x32_bf16 v[16:19], v[38:41], v[4:7], v[20:23]
	s_nop 2
	ds_read_b64_tr_b16 v[20:21], v28
	ds_read_b64_tr_b16 v[22:23], v28 offset:2560
	ds_read_b64_tr_b16 v[28:29], v30
	ds_read_b64_tr_b16 v[30:31], v30 offset:2560
	v_mfma_f32_16x16x32_bf16 v[38:41], v[46:49], v[4:7], v[42:45]
	s_nop 2
	ds_read_b64_tr_b16 v[42:43], v54
	ds_read_b64_tr_b16 v[44:45], v54 offset:2560
	ds_read_b64_tr_b16 v[46:47], v37
	ds_read_b64_tr_b16 v[48:49], v37 offset:2560
	v_mfma_f32_16x16x32_bf16 v[4:7], v[50:53], v[4:7], v[24:27]
	s_waitcnt lgkmcnt(8)
	s_nop 1
	v_pk_mul_f32 v[24:25], v[32:33], v[56:57] op_sel_hi:[0,1]
	v_pk_mul_f32 v[8:9], v[8:9], v[24:25] op_sel:[0,1] op_sel_hi:[1,0]
	v_pk_mul_f32 v[24:25], v[32:33], v[100:101] op_sel_hi:[0,1]
	v_pk_mul_f32 v[10:11], v[10:11], v[24:25] op_sel:[0,1] op_sel_hi:[1,0]
	v_cvt_pk_bf16_f32 v8, v8, v9
	v_cvt_pk_bf16_f32 v9, v10, v11
	v_pk_mul_f32 v[10:11], v[32:33], v[102:103] op_sel_hi:[0,1]
	v_pk_mul_f32 v[0:1], v[0:1], v[10:11] op_sel:[0,1] op_sel_hi:[1,0]
	s_nop 0
	v_cvt_pk_bf16_f32 v10, v0, v1
	v_pk_mul_f32 v[0:1], v[32:33], v[104:105] op_sel_hi:[0,1]
	v_pk_mul_f32 v[0:1], v[2:3], v[0:1] op_sel:[0,1] op_sel_hi:[1,0]
	s_nop 0
	v_cvt_pk_bf16_f32 v11, v0, v1
	s_waitcnt lgkmcnt(6)
	s_nop 0
	v_mfma_f32_16x16x32_bf16 v[0:3], v[20:23], v[8:11], v[12:15]
	s_waitcnt lgkmcnt(4)
	v_mfma_f32_16x16x32_bf16 v[12:15], v[28:31], v[8:11], v[16:19]
	s_waitcnt lgkmcnt(2)
	v_mfma_f32_16x16x32_bf16 v[16:19], v[42:45], v[8:11], v[38:41]
	s_waitcnt lgkmcnt(0)
	v_mfma_f32_16x16x32_bf16 v[4:7], v[46:49], v[8:11], v[4:7]
	ds_read_b128 v[8:11], v70 offset:18432
	ds_read_b128 v[20:23], v71
	ds_read_b128 v[24:27], v72
	ds_read_b128 v[28:31], v74
	ds_read_b128 v[38:41], v76
	ds_read_b128 v[42:45], v70 offset:18496
	ds_read_b128 v[46:49], v79
	ds_read_b128 v[50:53], v80
	ds_read_b128 v[54:57], v82
	ds_read_b128 v[58:61], v118
	ds_read_b128 v[84:87], v70 offset:36864
	ds_read_b128 v[88:91], v73
	ds_read_b128 v[72:75], v75
	ds_read_b128 v[92:95], v77
	ds_read_b128 v[76:79], v78
	ds_read_b128 v[96:99], v70 offset:36928
	ds_read_b128 v[100:103], v81
	ds_read_b128 v[80:83], v83
	ds_read_b128 v[104:107], v119
	ds_read_b128 v[108:111], v120
	s_waitcnt lgkmcnt(14)
	v_mfma_f32_16x16x32_bf16 v[0:3], v[20:23], v[8:11], v[0:3]
	s_mov_b32 s0, 0x800000
	v_mfma_f32_16x16x32_bf16 v[12:15], v[24:27], v[8:11], v[12:15]
	s_waitcnt lgkmcnt(13)
	v_mfma_f32_16x16x32_bf16 v[0:3], v[46:49], v[42:45], v[0:3]
	v_mfma_f32_16x16x32_bf16 v[16:19], v[28:31], v[8:11], v[16:19]
	v_or_b32_e32 v28, s12, v68
	v_lshlrev_b32_e32 v32, 1, v28
	v_mfma_f32_16x16x32_bf16 v[4:7], v[38:41], v[8:11], v[4:7]
	s_waitcnt lgkmcnt(12)
	v_mfma_f32_16x16x32_bf16 v[8:11], v[50:53], v[42:45], v[12:15]
	s_waitcnt lgkmcnt(8)
	v_mfma_f32_16x16x32_bf16 v[0:3], v[88:91], v[84:87], v[0:3]
	s_waitcnt lgkmcnt(7)
	v_mfma_f32_16x16x32_bf16 v[8:11], v[72:75], v[84:87], v[8:11]
	v_mfma_f32_16x16x32_bf16 v[12:15], v[54:57], v[42:45], v[16:19]
	v_mfma_f32_16x16x32_bf16 v[4:7], v[58:61], v[42:45], v[4:7]
	s_waitcnt lgkmcnt(3)
	v_mfma_f32_16x16x32_bf16 v[16:19], v[100:103], v[96:99], v[0:3]
	s_waitcnt lgkmcnt(2)
	v_mfma_f32_16x16x32_bf16 v[8:11], v[80:83], v[96:99], v[8:11]
	v_mfma_f32_16x16x32_bf16 v[0:3], v[92:95], v[84:87], v[12:15]
	s_nop 4
	v_mov_b32_e32 v20, v17
	v_mov_b32_e32 v21, v18
	v_mov_b32_e32 v22, v16
	v_mov_b32_e32 v23, v19
	v_mfma_f32_16x16x32_bf16 v[4:7], v[76:79], v[84:87], v[4:7]
	v_add_f32_e64 v12, v20, v22
	v_add_f32_e64 v13, v21, v23
	v_mov_b32_e32 v14, v8
	v_add_f32_e32 v12, v12, v13
	v_add_f32_e32 v20, 0, v12
	v_mov_b32_e32 v12, v9
	v_mov_b32_e32 v13, v10
	v_mov_b32_e32 v15, v11
	v_pk_add_f32 v[22:23], v[12:13], v[14:15]
	s_waitcnt lgkmcnt(1)
	v_mfma_f32_16x16x32_bf16 v[12:15], v[104:107], v[96:99], v[0:3]
	v_pk_add_f32 v[22:23], v[22:23], v[22:23] op_sel:[0,1] op_sel_hi:[1,0]
	s_waitcnt lgkmcnt(0)
	v_mfma_f32_16x16x32_bf16 v[0:3], v[108:111], v[96:99], v[4:7]
	s_nop 4
	v_add_f32_e32 v24, v12, v13
	v_add_f32_e32 v26, v14, v15
	s_nop 0
	v_mov_b32_e32 v21, v0
	v_mov_b32_e32 v23, v1
	v_mov_b32_e32 v25, v2
	v_mov_b32_e32 v27, v3
	v_pk_add_f32 v[4:5], v[20:21], v[22:23]
	v_pk_add_f32 v[6:7], v[24:25], v[26:27]
	v_and_b32_e32 v25, 0xffff0000, v67
	v_pk_add_f32 v[4:5], v[4:5], v[6:7]
	s_nop 0
	v_add_f32_e32 v4, v4, v5
	v_mov_b32_e32 v5, v4
	s_nop 1
	v_permlane16_swap_b32 v4, v5
	s_nop 1
	s_nop 0
	v_add_f32_e32 v4, v4, v5
	v_mov_b32_e32 v5, v4
	s_nop 1
	v_permlane32_swap_b32 v4, v5
	s_nop 1
	s_nop 0
	v_add_f32_e32 v24, v4, v5
	v_fmamk_f32 v5, v24, 0xbc800000, v17
	v_fmamk_f32 v4, v24, 0xbc800000, v16
	v_fmamk_f32 v19, v24, 0xbc800000, v19
	v_fmac_f32_e32 v18, 0xbc800000, v24
	v_pk_mul_f32 v[6:7], v[18:19], v[18:19]
	v_pk_mul_f32 v[16:17], v[4:5], v[4:5]
	v_fmamk_f32 v9, v24, 0xbc800000, v9
	v_pk_mov_b32 v[20:21], v[16:17], v[6:7] op_sel:[1,0]
	v_mov_b32_e32 v17, v7
	v_pk_add_f32 v[6:7], v[20:21], v[16:17]
	v_fmamk_f32 v8, v24, 0xbc800000, v8
	v_fmamk_f32 v11, v24, 0xbc800000, v11
	v_fmac_f32_e32 v10, 0xbc800000, v24
	v_pk_add_f32 v[6:7], v[6:7], v[6:7] op_sel_hi:[0,1]
	v_pk_mul_f32 v[16:17], v[10:11], v[10:11]
	v_pk_mul_f32 v[20:21], v[8:9], v[8:9]
	v_fmamk_f32 v12, v24, 0xbc800000, v12
	v_pk_mov_b32 v[22:23], v[20:21], v[16:17] op_sel:[1,0]
	v_mov_b32_e32 v21, v17
	v_fmamk_f32 v13, v24, 0xbc800000, v13
	v_fmac_f32_e32 v14, 0xbc800000, v24
	v_mul_f32_e32 v6, v12, v12
	v_pk_add_f32 v[16:17], v[22:23], v[20:21]
	v_fmamk_f32 v15, v24, 0xbc800000, v15
	v_pk_fma_f32 v[20:21], v[12:13], v[12:13], v[6:7] op_sel_hi:[1,1,0]
	v_mul_f32_e32 v6, v14, v14
	v_pk_add_f32 v[16:17], v[16:17], v[16:17] op_sel_hi:[0,1]
	v_pk_fma_f32 v[22:23], v[14:15], v[14:15], v[6:7] op_sel_hi:[1,1,0]
	v_fmamk_f32 v3, v24, 0xbc800000, v3
	v_fmamk_f32 v2, v24, 0xbc800000, v2
	v_fmamk_f32 v1, v24, 0xbc800000, v1
	v_fmac_f32_e32 v0, 0xbc800000, v24
	v_mul_f32_e32 v20, v0, v0
	v_mul_f32_e32 v22, v1, v1
	v_mul_f32_e32 v6, v2, v2
	v_mul_f32_e32 v16, v3, v3
	v_pk_add_f32 v[20:21], v[20:21], v[22:23]
	v_pk_add_f32 v[6:7], v[6:7], v[16:17]
	v_mov_b64_e32 v[16:17], s[48:49]
	v_pk_add_f32 v[6:7], v[20:21], v[6:7]
	v_lshlrev_b32_e32 v20, 16, v66
	v_add_f32_e32 v6, v6, v7
	v_mov_b32_e32 v7, v6
	s_nop 1
	v_permlane16_swap_b32 v6, v7
	s_nop 1
	v_and_b32_e32 v21, 0xffff0000, v66
	v_add_f32_e32 v6, v6, v7
	v_mov_b32_e32 v7, v6
	s_nop 1
	v_permlane32_swap_b32 v6, v7
	s_nop 1
	v_mul_f32_e32 v22, 0xbfb8aa3b, v21
	v_add_f32_e32 v6, v6, v7
	v_fmamk_f32 v6, v6, 0x3c800000, v239
	v_mul_f32_e32 v7, 0x4b800000, v6
	v_cmp_gt_f32_e32 vcc, s0, v6
	v_exp_f32_e32 v23, v22
	v_lshlrev_b32_e32 v24, 16, v67
	v_cndmask_b32_e32 v6, v6, v7, vcc
	v_rsq_f32_e32 v6, v6
	s_mov_b32 s0, 0x18c00000
	v_mul_f32_e32 v7, 0x45800000, v6
	v_cndmask_b32_e32 v6, v6, v7, vcc
	v_add_u32_e32 v7, s8, v69
	v_mad_i64_i32 v[16:17], s[6:7], v7, s44, v[16:17]
	v_pk_mul_f32 v[18:19], v[18:19], v[6:7] op_sel_hi:[1,0]
	v_mul_f32_e32 v7, 0xbfb8aa3b, v20
	v_exp_f32_e32 v7, v7
	v_lshl_add_u64 v[16:17], v[16:17], 0, v[32:33]
	s_mov_b64 s[6:7], 0x18c00600
	v_pk_mul_f32 v[4:5], v[4:5], v[6:7] op_sel_hi:[1,0]
	v_add_f32_e32 v7, 1.0, v7
	v_rcp_f32_e32 v22, v7
	v_add_f32_e32 v7, 1.0, v23
	v_mul_f32_e32 v23, 0xbfb8aa3b, v24
	v_exp_f32_e32 v26, v23
	v_mul_f32_e32 v23, 0xbfb8aa3b, v25
	v_exp_f32_e32 v27, v23
	v_rcp_f32_e32 v23, v7
	v_add_f32_e32 v7, 1.0, v26
	v_rcp_f32_e32 v26, v7
	v_add_f32_e32 v7, 1.0, v27
	v_rcp_f32_e32 v27, v7
	v_pk_mul_f32 v[20:21], v[22:23], v[20:21]
	s_nop 0
	v_pk_mul_f32 v[4:5], v[20:21], v[4:5]
	v_pk_mul_f32 v[20:21], v[26:27], v[24:25]
	v_cvt_pk_bf16_f32 v4, v4, v5
	v_pk_mul_f32 v[18:19], v[20:21], v[18:19]
	v_lshlrev_b32_e32 v20, 16, v65
	v_cvt_pk_bf16_f32 v5, v18, v19
	v_lshl_add_u64 v[18:19], v[16:17], 0, s[6:7]
	v_add_co_u32_e32 v16, vcc, s0, v16
	v_and_b32_e32 v21, 0xffff0000, v65
	s_nop 0
	v_addc_co_u32_e32 v17, vcc, 0, v17, vcc
	global_store_dwordx2 v[16:17], v[4:5], off offset:1536 sc1
	v_pk_mul_f32 v[4:5], v[10:11], v[6:7] op_sel_hi:[1,0]
	v_lshlrev_b32_e32 v10, 16, v64
	v_and_b32_e32 v11, 0xffff0000, v64
	v_mul_f32_e32 v7, 0xbfb8aa3b, v10
	v_exp_f32_e32 v7, v7
	v_mul_f32_e32 v16, 0xbfb8aa3b, v11
	v_exp_f32_e32 v17, v16
	v_pk_mul_f32 v[8:9], v[8:9], v[6:7] op_sel_hi:[1,0]
	v_add_f32_e32 v7, 1.0, v7
	v_rcp_f32_e32 v16, v7
	v_add_f32_e32 v7, 1.0, v17
	v_mul_f32_e32 v17, 0xbfb8aa3b, v20
	v_exp_f32_e32 v22, v17
	v_mul_f32_e32 v17, 0xbfb8aa3b, v21
	v_exp_f32_e32 v23, v17
	v_rcp_f32_e32 v17, v7
	v_add_f32_e32 v7, 1.0, v22
	v_rcp_f32_e32 v22, v7
	v_add_f32_e32 v7, 1.0, v23
	v_rcp_f32_e32 v23, v7
	v_pk_mul_f32 v[10:11], v[16:17], v[10:11]
	s_nop 0
	v_pk_mul_f32 v[8:9], v[10:11], v[8:9]
	v_pk_mul_f32 v[10:11], v[22:23], v[20:21]
	v_cvt_pk_bf16_f32 v8, v8, v9
	v_pk_mul_f32 v[4:5], v[10:11], v[4:5]
	s_nop 0
	v_cvt_pk_bf16_f32 v9, v4, v5
	global_store_dwordx2 v[18:19], v[8:9], off offset:32 sc1
	v_lshlrev_b32_e32 v8, 16, v62
	v_pk_mul_f32 v[4:5], v[14:15], v[6:7] op_sel_hi:[1,0]
	v_and_b32_e32 v9, 0xffff0000, v62
	v_mul_f32_e32 v7, 0xbfb8aa3b, v8
	v_exp_f32_e32 v7, v7
	v_mul_f32_e32 v10, 0xbfb8aa3b, v9
	v_exp_f32_e32 v14, v10
	v_and_b32_e32 v15, 0xffff0000, v63
	v_pk_mul_f32 v[10:11], v[12:13], v[6:7] op_sel_hi:[1,0]
	v_add_f32_e32 v7, 1.0, v7
	v_rcp_f32_e32 v12, v7
	v_add_f32_e32 v7, 1.0, v14
	v_lshlrev_b32_e32 v14, 16, v63
	v_mul_f32_e32 v13, 0xbfb8aa3b, v14
	v_exp_f32_e32 v16, v13
	v_mul_f32_e32 v13, 0xbfb8aa3b, v15
	v_exp_f32_e32 v17, v13
	v_rcp_f32_e32 v13, v7
	v_add_f32_e32 v7, 1.0, v16
	v_rcp_f32_e32 v16, v7
	v_add_f32_e32 v7, 1.0, v17
	v_rcp_f32_e32 v17, v7
	v_pk_mul_f32 v[8:9], v[12:13], v[8:9]
	v_pk_mul_f32 v[2:3], v[2:3], v[6:7] op_sel_hi:[1,0]
	v_pk_mul_f32 v[8:9], v[8:9], v[10:11]
	v_pk_mul_f32 v[10:11], v[16:17], v[14:15]
	v_cvt_pk_bf16_f32 v8, v8, v9
	v_pk_mul_f32 v[4:5], v[10:11], v[4:5]
	s_nop 0
	v_cvt_pk_bf16_f32 v9, v4, v5
	v_lshlrev_b32_e32 v4, 16, v34
	v_and_b32_e32 v5, 0xffff0000, v34
	global_store_dwordx2 v[18:19], v[8:9], off offset:64 sc1
	v_mul_f32_e32 v7, 0xbfb8aa3b, v4
	v_mul_f32_e32 v8, 0xbfb8aa3b, v5
	v_exp_f32_e32 v7, v7
	v_exp_f32_e32 v8, v8
	v_and_b32_e32 v9, 0xffff0000, v35
	v_mul_f32_e32 v11, 0xbfb8aa3b, v9
	v_pk_mul_f32 v[0:1], v[0:1], v[6:7] op_sel_hi:[1,0]
	v_add_f32_e32 v6, 1.0, v7
	v_add_f32_e32 v7, 1.0, v8
	v_lshlrev_b32_e32 v8, 16, v35
	v_mul_f32_e32 v10, 0xbfb8aa3b, v8
	v_exp_f32_e32 v10, v10
	v_exp_f32_e32 v11, v11
	v_rcp_f32_e32 v6, v6
	v_rcp_f32_e32 v7, v7
	v_add_f32_e32 v10, 1.0, v10
	v_add_f32_e32 v11, 1.0, v11
	v_rcp_f32_e32 v10, v10
	v_rcp_f32_e32 v11, v11
	v_pk_mul_f32 v[4:5], v[6:7], v[4:5]
	s_nop 0
	v_pk_mul_f32 v[0:1], v[4:5], v[0:1]
	v_pk_mul_f32 v[4:5], v[10:11], v[8:9]
	v_cvt_pk_bf16_f32 v0, v0, v1
	v_pk_mul_f32 v[2:3], v[4:5], v[2:3]
	s_nop 0
	v_cvt_pk_bf16_f32 v1, v2, v3
	global_store_dwordx2 v[18:19], v[0:1], off offset:96 sc1

.LBB0_711:
	s_or_b64 exec, exec, s[6:7]
	s_lshl_b32 s6, s8, 16
	v_readlane_b32 s16, v254, 23
	v_add_u32_e32 v17, 0x200, v206
	s_add_u32 s6, s16, s6
	v_readlane_b32 s7, v255, 3
	v_ashrrev_i32_e32 v24, 5, v206
	v_ashrrev_i32_e32 v22, 5, v17
	s_addc_u32 s7, s7, 0
	v_ashrrev_i32_e32 v25, 31, v24
	v_ashrrev_i32_e32 v23, 31, v22
	v_lshl_add_u64 v[30:31], s[6:7], 0, v[32:33]
	v_lshlrev_b64 v[18:19], 9, v[24:25]
	v_lshlrev_b64 v[20:21], 9, v[22:23]
	v_lshl_add_u64 v[18:19], v[30:31], 0, v[18:19]
	v_lshl_add_u64 v[20:21], v[30:31], 0, v[20:21]
	v_add_u32_e32 v17, 0x400, v206
	s_barrier
	global_load_dwordx4 v[26:29], v[18:19], off
	global_load_dwordx4 v[38:41], v[20:21], off
	v_ashrrev_i32_e32 v20, 5, v17
	v_ashrrev_i32_e32 v21, 31, v20
	v_lshlrev_b64 v[18:19], 9, v[20:21]
	v_add_u32_e32 v17, 0x600, v206
	v_lshl_add_u64 v[34:35], v[30:31], 0, v[18:19]
	v_ashrrev_i32_e32 v18, 5, v17
	v_ashrrev_i32_e32 v19, 31, v18
	v_lshlrev_b64 v[42:43], 9, v[18:19]
	v_lshl_add_u64 v[46:47], v[30:31], 0, v[42:43]
	v_add_u32_e32 v17, 0x800, v206
	global_load_dwordx4 v[42:45], v[34:35], off
	s_nop 0
	global_load_dwordx4 v[46:49], v[46:47], off
	v_ashrrev_i32_e32 v34, 5, v17
	v_add_u32_e32 v17, 0xa00, v206
	v_ashrrev_i32_e32 v66, 5, v17
	v_add_u32_e32 v17, 0xc00, v206
	v_ashrrev_i32_e32 v68, 5, v17
	v_add_u32_e32 v17, 0xe00, v206
	v_ashrrev_i32_e32 v35, 31, v34
	v_ashrrev_i32_e32 v67, 31, v66
	v_ashrrev_i32_e32 v69, 31, v68
	v_ashrrev_i32_e32 v70, 5, v17
	v_lshlrev_b64 v[50:51], 9, v[34:35]
	v_lshlrev_b64 v[52:53], 9, v[66:67]
	v_lshlrev_b64 v[58:59], 9, v[68:69]
	v_ashrrev_i32_e32 v71, 31, v70
	v_lshl_add_u64 v[50:51], v[30:31], 0, v[50:51]
	v_lshl_add_u64 v[54:55], v[30:31], 0, v[52:53]
	v_lshl_add_u64 v[58:59], v[30:31], 0, v[58:59]
	v_lshlrev_b64 v[60:61], 9, v[70:71]
	global_load_dwordx4 v[50:53], v[50:51], off
	s_nop 0
	global_load_dwordx4 v[54:57], v[54:55], off
	v_lshl_add_u64 v[30:31], v[30:31], 0, v[60:61]
	global_load_dwordx4 v[58:61], v[58:59], off
	s_nop 0
	global_load_dwordx4 v[62:65], v[30:31], off
	v_readlane_b32 s17, v254, 24
	v_readlane_b32 s18, v254, 25
	v_readlane_b32 s19, v254, 26
	v_and_b32_e32 v17, 15, v206
	v_mad_u64_u32 v[30:31], s[6:7], v24, s33, v[16:17]
	v_lshl_add_u32 v19, v30, 1, 0
	s_waitcnt vmcnt(7)
	ds_write_b128 v19, v[26:29]
	v_mad_u64_u32 v[26:27], s[6:7], v22, s33, v[16:17]
	v_lshl_add_u32 v19, v26, 1, 0
	v_mad_u64_u32 v[26:27], s[6:7], v20, s33, v[16:17]
	s_waitcnt vmcnt(6)
	ds_write_b128 v19, v[38:41]
	v_lshl_add_u32 v19, v26, 1, 0
	v_mad_u64_u32 v[26:27], s[6:7], v18, s33, v[16:17]
	s_waitcnt vmcnt(5)
	ds_write_b128 v19, v[42:45]
	v_lshl_add_u32 v19, v26, 1, 0
	v_mad_u64_u32 v[26:27], s[6:7], v34, s33, v[16:17]
	s_waitcnt vmcnt(4)
	ds_write_b128 v19, v[46:49]
	v_lshl_add_u32 v19, v26, 1, 0
	v_mad_u64_u32 v[26:27], s[6:7], v66, s33, v[16:17]
	s_waitcnt vmcnt(3)
	ds_write_b128 v19, v[50:53]
	v_lshl_add_u32 v19, v26, 1, 0
	v_mad_u64_u32 v[26:27], s[6:7], v68, s33, v[16:17]
	s_waitcnt vmcnt(2)
	ds_write_b128 v19, v[54:57]
	v_lshl_add_u32 v19, v26, 1, 0
	v_mad_u64_u32 v[26:27], s[6:7], v70, s33, v[16:17]
	s_waitcnt vmcnt(1)
	ds_write_b128 v19, v[58:61]
	v_lshl_add_u32 v19, v26, 1, 0
	s_waitcnt vmcnt(0)
	ds_write_b128 v19, v[62:65]
	v_lshrrev_b32_e32 v19, 1, v206
	v_bfe_u32 v21, v206, 2, 2
	v_and_or_b32 v19, v19, 24, v21
	v_mul_u32_u24_e32 v19, 0x110, v19
	v_lshlrev_b32_e32 v21, 2, v206
	v_and_or_b32 v19, v21, 12, v19
	v_lshlrev_b32_e32 v19, 1, v19
	v_add_u32_e32 v19, s65, v19
	v_and_b32_e32 v21, 48, v206
	s_add_i32 s6, 0, 0x1a9d0
	v_mul_u32_u24_e32 v23, 0x110, v17
	s_waitcnt lgkmcnt(0)
	s_barrier
	ds_read_b64_tr_b16 v[28:29], v19 offset:2176
	ds_read_b64_tr_b16 v[26:27], v19
	ds_read_b64_tr_b16 v[40:41], v19 offset:2208
	ds_read_b64_tr_b16 v[38:39], v19 offset:32
	v_add3_u32 v23, s6, v21, v23
	ds_read_b64_tr_b16 v[44:45], v19 offset:19584
	ds_read_b64_tr_b16 v[42:43], v19 offset:17408
	ds_read_b64_tr_b16 v[48:49], v19 offset:19616
	ds_read_b64_tr_b16 v[46:47], v19 offset:17440
	ds_read_b128 v[50:53], v23
	ds_read_b128 v[54:57], v23 offset:64
	ds_read_b128 v[58:61], v23 offset:4352
	ds_read_b128 v[62:65], v23 offset:4416
	ds_read_b128 v[66:69], v23 offset:8704
	ds_read_b128 v[70:73], v23 offset:8768
	ds_read_b128 v[74:77], v23 offset:13056
	ds_read_b128 v[78:81], v23 offset:13120
	s_waitcnt lgkmcnt(7)
	v_mfma_f32_16x16x32_bf16 v[82:85], v[26:29], v[50:53], 0
	v_mfma_f32_16x16x32_bf16 v[50:53], v[38:41], v[50:53], 0
	s_waitcnt lgkmcnt(5)
	v_mfma_f32_16x16x32_bf16 v[86:89], v[26:29], v[58:61], 0
	v_mfma_f32_16x16x32_bf16 v[58:61], v[38:41], v[58:61], 0
	s_waitcnt lgkmcnt(3)
	v_mfma_f32_16x16x32_bf16 v[90:93], v[26:29], v[66:69], 0
	v_mfma_f32_16x16x32_bf16 v[66:69], v[38:41], v[66:69], 0
	s_waitcnt lgkmcnt(1)
	v_mfma_f32_16x16x32_bf16 v[26:29], v[26:29], v[74:77], 0
	v_mfma_f32_16x16x32_bf16 v[38:41], v[38:41], v[74:77], 0
	ds_read_b64_tr_b16 v[76:77], v19 offset:36992
	ds_read_b64_tr_b16 v[74:75], v19 offset:34816
	ds_read_b64_tr_b16 v[96:97], v19 offset:37024
	ds_read_b64_tr_b16 v[94:95], v19 offset:34848
	ds_read_b128 v[98:101], v23 offset:128
	ds_read_b128 v[102:105], v23 offset:4480
	ds_read_b128 v[106:109], v23 offset:8832
	ds_read_b128 v[110:113], v23 offset:13184
	v_mfma_f32_16x16x32_bf16 v[82:85], v[42:45], v[54:57], v[82:85]
	v_mfma_f32_16x16x32_bf16 v[50:53], v[46:49], v[54:57], v[50:53]
	v_mfma_f32_16x16x32_bf16 v[54:57], v[42:45], v[62:65], v[86:89]
	v_mfma_f32_16x16x32_bf16 v[58:61], v[46:49], v[62:65], v[58:61]
	v_mfma_f32_16x16x32_bf16 v[62:65], v[42:45], v[70:73], v[90:93]
	v_mfma_f32_16x16x32_bf16 v[66:69], v[46:49], v[70:73], v[66:69]
	s_waitcnt lgkmcnt(8)
	v_mfma_f32_16x16x32_bf16 v[26:29], v[42:45], v[78:81], v[26:29]
	v_mfma_f32_16x16x32_bf16 v[38:41], v[46:49], v[78:81], v[38:41]
	ds_read_b64_tr_b16 v[44:45], v19 offset:54400
	ds_read_b64_tr_b16 v[42:43], v19 offset:52224
	ds_read_b64_tr_b16 v[48:49], v19 offset:54432
	ds_read_b64_tr_b16 v[46:47], v19 offset:52256
	ds_read_b128 v[70:73], v23 offset:192
	ds_read_b128 v[78:81], v23 offset:4544
	ds_read_b128 v[86:89], v23 offset:8896
	ds_read_b128 v[90:93], v23 offset:13248
	s_waitcnt lgkmcnt(11)
	v_mfma_f32_16x16x32_bf16 v[82:85], v[74:77], v[98:101], v[82:85]
	v_mfma_f32_16x16x32_bf16 v[50:53], v[94:97], v[98:101], v[50:53]
	s_waitcnt lgkmcnt(10)
	v_mfma_f32_16x16x32_bf16 v[54:57], v[74:77], v[102:105], v[54:57]
	v_mfma_f32_16x16x32_bf16 v[58:61], v[94:97], v[102:105], v[58:61]
	s_waitcnt lgkmcnt(9)
	v_mfma_f32_16x16x32_bf16 v[62:65], v[74:77], v[106:109], v[62:65]
	v_mfma_f32_16x16x32_bf16 v[66:69], v[94:97], v[106:109], v[66:69]
	s_waitcnt lgkmcnt(8)
	v_mfma_f32_16x16x32_bf16 v[26:29], v[74:77], v[110:113], v[26:29]
	v_mfma_f32_16x16x32_bf16 v[38:41], v[94:97], v[110:113], v[38:41]
	s_waitcnt lgkmcnt(3)
	v_mfma_f32_16x16x32_bf16 v[74:77], v[42:45], v[70:73], v[82:85]
	v_mfma_f32_16x16x32_bf16 v[50:53], v[46:49], v[70:73], v[50:53]
	s_waitcnt lgkmcnt(2)
	v_mfma_f32_16x16x32_bf16 v[54:57], v[42:45], v[78:81], v[54:57]
	v_mfma_f32_16x16x32_bf16 v[58:61], v[46:49], v[78:81], v[58:61]
	s_waitcnt lgkmcnt(1)
	v_mfma_f32_16x16x32_bf16 v[62:65], v[42:45], v[86:89], v[62:65]
	v_mfma_f32_16x16x32_bf16 v[66:69], v[46:49], v[86:89], v[66:69]
	s_waitcnt lgkmcnt(0)
	v_mfma_f32_16x16x32_bf16 v[26:29], v[42:45], v[90:93], v[26:29]
	v_mfma_f32_16x16x32_bf16 v[38:41], v[46:49], v[90:93], v[38:41]
	s_mov_b32 s6, 0x3b000000
	v_mul_u32_u24_e32 v17, 0x420, v17
	v_pk_mul_f32 v[44:45], v[76:77], s[6:7] op_sel_hi:[1,0]
	v_pk_mul_f32 v[42:43], v[74:75], s[6:7] op_sel_hi:[1,0]
	v_readlane_b32 s7, v255, 4
	s_barrier
	s_nop 0
	v_add3_u32 v17, s7, v21, v17
	ds_write_b128 v17, v[42:45]
	v_pk_mul_f32 v[44:45], v[52:53], s[6:7] op_sel_hi:[1,0]
	v_pk_mul_f32 v[42:43], v[50:51], s[6:7] op_sel_hi:[1,0]
	v_and_b32_e32 v31, 0xffff0000, v12
	ds_write_b128 v17, v[42:45] offset:64
	v_pk_mul_f32 v[44:45], v[56:57], s[6:7] op_sel_hi:[1,0]
	v_pk_mul_f32 v[42:43], v[54:55], s[6:7] op_sel_hi:[1,0]
	v_mul_f32_e32 v19, 0xbfb8aa3b, v31
	ds_write_b128 v17, v[42:45] offset:16896
	v_pk_mul_f32 v[44:45], v[60:61], s[6:7] op_sel_hi:[1,0]
	v_pk_mul_f32 v[42:43], v[58:59], s[6:7] op_sel_hi:[1,0]
	v_pk_mul_f32 v[28:29], v[28:29], s[6:7] op_sel_hi:[1,0]
	v_pk_mul_f32 v[26:27], v[26:27], s[6:7] op_sel_hi:[1,0]
	v_exp_f32_e32 v19, v19
	ds_write_b128 v17, v[42:45] offset:16960
	v_pk_mul_f32 v[44:45], v[64:65], s[6:7] op_sel_hi:[1,0]
	v_pk_mul_f32 v[42:43], v[62:63], s[6:7] op_sel_hi:[1,0]
	ds_write_b128 v17, v[26:29] offset:50688
	v_pk_mul_f32 v[28:29], v[40:41], s[6:7] op_sel_hi:[1,0]
	v_pk_mul_f32 v[26:27], v[38:39], s[6:7] op_sel_hi:[1,0]
	s_movk_i32 s8, 0x108
	v_lshlrev_b32_e32 v30, 16, v12
	ds_write_b128 v17, v[42:45] offset:33792
	v_pk_mul_f32 v[44:45], v[68:69], s[6:7] op_sel_hi:[1,0]
	v_pk_mul_f32 v[42:43], v[66:67], s[6:7] op_sel_hi:[1,0]
	ds_write_b128 v17, v[26:29] offset:50752
	v_mad_u64_u32 v[26:27], s[6:7], v24, s8, v[16:17]
	v_mul_f32_e32 v12, 0xbfb8aa3b, v30
	v_lshlrev_b32_e32 v34, 16, v13
	ds_write_b128 v17, v[42:45] offset:33856
	v_lshl_add_u32 v17, v26, 2, 0
	v_exp_f32_e32 v12, v12
	v_and_b32_e32 v35, 0xffff0000, v13
	v_mul_f32_e32 v13, 0xbfb8aa3b, v34
	s_waitcnt lgkmcnt(0)
	s_barrier
	ds_read_b128 v[26:29], v17
	ds_read_b128 v[38:41], v17 offset:16
	v_add_f32_e32 v17, 1.0, v19
	v_exp_f32_e32 v19, v13
	v_mul_f32_e32 v13, 0xbfb8aa3b, v35
	v_exp_f32_e32 v21, v13
	v_add_f32_e32 v12, 1.0, v12
	v_rcp_f32_e32 v12, v12
	v_rcp_f32_e32 v13, v17
	v_add_f32_e32 v17, 1.0, v19
	v_rcp_f32_e32 v42, v17
	v_add_f32_e32 v17, 1.0, v21
	v_rcp_f32_e32 v43, v17
	v_pk_mul_f32 v[12:13], v[12:13], v[30:31]
	s_mov_b32 s12, 0x18c00000
	s_waitcnt lgkmcnt(1)
	v_pk_mul_f32 v[12:13], v[12:13], v[26:27]
	s_nop 0
	v_cvt_pk_bf16_f32 v26, v12, v13
	v_pk_mul_f32 v[12:13], v[42:43], v[34:35]
	v_lshlrev_b32_e32 v34, 16, v9
	v_pk_mul_f32 v[12:13], v[12:13], v[28:29]
	v_lshlrev_b32_e32 v28, 16, v14
	v_and_b32_e32 v29, 0xffff0000, v14
	v_mul_f32_e32 v14, 0xbfb8aa3b, v28
	v_exp_f32_e32 v14, v14
	v_mul_f32_e32 v17, 0xbfb8aa3b, v29
	v_exp_f32_e32 v17, v17
	v_cvt_pk_bf16_f32 v27, v12, v13
	v_add_f32_e32 v12, 1.0, v14
	v_lshlrev_b32_e32 v14, 16, v15
	v_add_f32_e32 v13, 1.0, v17
	v_and_b32_e32 v15, 0xffff0000, v15
	v_mul_f32_e32 v17, 0xbfb8aa3b, v14
	v_exp_f32_e32 v17, v17
	v_mul_f32_e32 v19, 0xbfb8aa3b, v15
	v_exp_f32_e32 v19, v19
	v_rcp_f32_e32 v12, v12
	v_rcp_f32_e32 v13, v13
	v_add_f32_e32 v17, 1.0, v17
	v_rcp_f32_e32 v30, v17
	v_add_f32_e32 v17, 1.0, v19
	v_rcp_f32_e32 v31, v17
	v_pk_mul_f32 v[12:13], v[12:13], v[28:29]
	v_and_b32_e32 v35, 0xffff0000, v9
	s_waitcnt lgkmcnt(0)
	v_pk_mul_f32 v[12:13], v[12:13], v[38:39]
	v_mul_f32_e32 v9, 0xbfb8aa3b, v34
	v_cvt_pk_bf16_f32 v28, v12, v13
	v_pk_mul_f32 v[12:13], v[30:31], v[14:15]
	v_lshl_add_u32 v14, v24, 6, s0
	v_pk_mul_f32 v[12:13], v[12:13], v[40:41]
	s_nop 0
	v_cvt_pk_bf16_f32 v29, v12, v13
	v_mov_b64_e32 v[12:13], s[48:49]
	v_mad_i64_i32 v[14:15], s[6:7], v14, s44, v[12:13]
	v_lshl_add_u64 v[14:15], v[14:15], 0, v[32:33]
	v_add_co_u32_e32 v14, vcc, s12, v14
	s_nop 1
	v_addc_co_u32_e32 v15, vcc, 0, v15, vcc
	global_store_dwordx4 v[14:15], v[26:29], off offset:2048 sc1
	v_mad_u64_u32 v[14:15], s[6:7], v22, s8, v[16:17]
	v_and_b32_e32 v15, 0xffff0000, v8
	v_mul_f32_e32 v19, 0xbfb8aa3b, v15
	v_exp_f32_e32 v19, v19
	v_lshl_add_u32 v17, v14, 2, 0
	v_lshlrev_b32_e32 v14, 16, v8
	v_mul_f32_e32 v8, 0xbfb8aa3b, v14
	v_exp_f32_e32 v8, v8
	ds_read_b128 v[24:27], v17
	ds_read_b128 v[28:31], v17 offset:16
	v_add_f32_e32 v17, 1.0, v19
	v_exp_f32_e32 v19, v9
	v_mul_f32_e32 v9, 0xbfb8aa3b, v35
	v_exp_f32_e32 v21, v9
	v_add_f32_e32 v8, 1.0, v8
	v_rcp_f32_e32 v8, v8
	v_rcp_f32_e32 v9, v17
	v_add_f32_e32 v17, 1.0, v19
	v_rcp_f32_e32 v38, v17
	v_add_f32_e32 v17, 1.0, v21
	v_rcp_f32_e32 v39, v17
	v_pk_mul_f32 v[8:9], v[8:9], v[14:15]
	v_pk_mul_f32 v[14:15], v[38:39], v[34:35]
	s_waitcnt lgkmcnt(1)
	v_pk_mul_f32 v[8:9], v[8:9], v[24:25]
	v_lshlrev_b32_e32 v24, 16, v10
	v_cvt_pk_bf16_f32 v8, v8, v9
	v_and_b32_e32 v25, 0xffff0000, v10
	v_mul_f32_e32 v9, 0xbfb8aa3b, v24
	v_pk_mul_f32 v[14:15], v[14:15], v[26:27]
	v_exp_f32_e32 v10, v9
	v_mul_f32_e32 v9, 0xbfb8aa3b, v25
	v_exp_f32_e32 v17, v9
	v_cvt_pk_bf16_f32 v9, v14, v15
	v_lshlrev_b32_e32 v14, 16, v11
	v_and_b32_e32 v15, 0xffff0000, v11
	v_mul_f32_e32 v11, 0xbfb8aa3b, v14
	v_exp_f32_e32 v19, v11
	v_mul_f32_e32 v11, 0xbfb8aa3b, v15
	v_exp_f32_e32 v21, v11
	v_add_f32_e32 v17, 1.0, v17
	v_rcp_f32_e32 v11, v17
	v_add_f32_e32 v17, 1.0, v19
	v_add_f32_e32 v10, 1.0, v10
	v_rcp_f32_e32 v26, v17
	v_add_f32_e32 v17, 1.0, v21
	v_rcp_f32_e32 v10, v10
	v_rcp_f32_e32 v27, v17
	v_pk_mul_f32 v[10:11], v[10:11], v[24:25]
	v_pk_mul_f32 v[14:15], v[26:27], v[14:15]
	s_waitcnt lgkmcnt(0)
	v_pk_mul_f32 v[10:11], v[10:11], v[28:29]
	v_pk_mul_f32 v[14:15], v[14:15], v[30:31]
	v_cvt_pk_bf16_f32 v10, v10, v11
	v_cvt_pk_bf16_f32 v11, v14, v15
	v_lshl_add_u32 v14, v22, 6, s0
	v_mad_i64_i32 v[14:15], s[6:7], v14, s44, v[12:13]
	v_lshl_add_u64 v[14:15], v[14:15], 0, v[32:33]
	v_add_co_u32_e32 v14, vcc, s12, v14
	v_lshlrev_b32_e32 v26, 16, v5
	s_nop 0
	v_addc_co_u32_e32 v15, vcc, 0, v15, vcc
	global_store_dwordx4 v[14:15], v[8:11], off offset:2048 sc1
	v_and_b32_e32 v15, 0xffff0000, v4
	v_lshlrev_b32_e32 v14, 16, v4
	v_mad_u64_u32 v[8:9], s[6:7], v20, s8, v[16:17]
	v_lshl_add_u32 v17, v8, 2, 0
	v_mul_f32_e32 v8, 0xbfb8aa3b, v15
	v_exp_f32_e32 v19, v8
	v_mul_f32_e32 v4, 0xbfb8aa3b, v14
	v_and_b32_e32 v27, 0xffff0000, v5
	v_mul_f32_e32 v5, 0xbfb8aa3b, v26
	v_exp_f32_e32 v4, v4
	ds_read_b128 v[8:11], v17
	ds_read_b128 v[22:25], v17 offset:16
	v_add_f32_e32 v17, 1.0, v19
	v_exp_f32_e32 v19, v5
	v_mul_f32_e32 v5, 0xbfb8aa3b, v27
	v_exp_f32_e32 v21, v5
	v_add_f32_e32 v4, 1.0, v4
	v_rcp_f32_e32 v5, v17
	v_add_f32_e32 v17, 1.0, v19
	v_rcp_f32_e32 v4, v4
	v_rcp_f32_e32 v28, v17
	v_add_f32_e32 v17, 1.0, v21
	v_rcp_f32_e32 v29, v17
	v_pk_mul_f32 v[4:5], v[4:5], v[14:15]
	s_waitcnt lgkmcnt(1)
	v_pk_mul_f32 v[4:5], v[4:5], v[8:9]
	v_pk_mul_f32 v[8:9], v[28:29], v[26:27]
	v_cvt_pk_bf16_f32 v4, v4, v5
	v_pk_mul_f32 v[8:9], v[8:9], v[10:11]
	v_lshlrev_b32_e32 v10, 16, v6
	v_and_b32_e32 v11, 0xffff0000, v6
	v_mul_f32_e32 v5, 0xbfb8aa3b, v10
	v_exp_f32_e32 v6, v5
	v_mul_f32_e32 v5, 0xbfb8aa3b, v11
	v_exp_f32_e32 v14, v5
	v_cvt_pk_bf16_f32 v5, v8, v9
	v_lshlrev_b32_e32 v8, 16, v7
	v_and_b32_e32 v9, 0xffff0000, v7
	v_mul_f32_e32 v7, 0xbfb8aa3b, v8
	v_exp_f32_e32 v15, v7
	v_mul_f32_e32 v7, 0xbfb8aa3b, v9
	v_exp_f32_e32 v17, v7
	v_add_f32_e32 v14, 1.0, v14
	v_add_f32_e32 v6, 1.0, v6
	v_rcp_f32_e32 v7, v14
	v_add_f32_e32 v14, 1.0, v15
	v_add_f32_e32 v15, 1.0, v17
	v_rcp_f32_e32 v6, v6
	v_rcp_f32_e32 v14, v14
	v_rcp_f32_e32 v15, v15
	v_pk_mul_f32 v[6:7], v[6:7], v[10:11]
	s_waitcnt lgkmcnt(0)
	v_pk_mul_f32 v[6:7], v[6:7], v[22:23]
	v_pk_mul_f32 v[8:9], v[14:15], v[8:9]
	v_cvt_pk_bf16_f32 v6, v6, v7
	v_pk_mul_f32 v[8:9], v[8:9], v[24:25]
	v_and_b32_e32 v15, 0xffff0000, v0
	v_cvt_pk_bf16_f32 v7, v8, v9
	v_lshl_add_u32 v8, v20, 6, s0
	v_mad_i64_i32 v[8:9], s[6:7], v8, s44, v[12:13]
	v_lshl_add_u64 v[8:9], v[8:9], 0, v[32:33]
	v_add_co_u32_e32 v8, vcc, s12, v8
	v_lshlrev_b32_e32 v14, 16, v0
	s_nop 0
	v_addc_co_u32_e32 v9, vcc, 0, v9, vcc
	global_store_dwordx4 v[8:9], v[4:7], off offset:2048 sc1
	v_mul_f32_e32 v0, 0xbfb8aa3b, v14
	v_exp_f32_e32 v0, v0
	v_mad_u64_u32 v[4:5], s[6:7], v18, s8, v[16:17]
	v_lshl_add_u32 v8, v4, 2, 0
	v_mul_f32_e32 v4, 0xbfb8aa3b, v15
	v_exp_f32_e32 v16, v4
	v_and_b32_e32 v17, 0xffff0000, v1
	v_add_f32_e32 v0, 1.0, v0
	v_rcp_f32_e32 v0, v0
	v_add_f32_e32 v19, 1.0, v16
	v_lshlrev_b32_e32 v16, 16, v1
	v_mul_f32_e32 v1, 0xbfb8aa3b, v16
	v_exp_f32_e32 v20, v1
	v_mul_f32_e32 v1, 0xbfb8aa3b, v17
	v_exp_f32_e32 v21, v1
	v_rcp_f32_e32 v1, v19
	v_add_f32_e32 v19, 1.0, v20
	v_rcp_f32_e32 v20, v19
	v_add_f32_e32 v19, 1.0, v21
	ds_read_b128 v[4:7], v8
	ds_read_b128 v[8:11], v8 offset:16
	v_rcp_f32_e32 v21, v19
	v_pk_mul_f32 v[0:1], v[0:1], v[14:15]
	s_waitcnt lgkmcnt(1)
	v_pk_mul_f32 v[0:1], v[0:1], v[4:5]
	v_pk_mul_f32 v[4:5], v[20:21], v[16:17]
	v_cvt_pk_bf16_f32 v0, v0, v1
	v_pk_mul_f32 v[4:5], v[4:5], v[6:7]
	v_lshlrev_b32_e32 v6, 16, v2
	v_and_b32_e32 v7, 0xffff0000, v2
	v_mul_f32_e32 v1, 0xbfb8aa3b, v6
	v_exp_f32_e32 v2, v1
	v_mul_f32_e32 v1, 0xbfb8aa3b, v7
	v_exp_f32_e32 v14, v1
	v_cvt_pk_bf16_f32 v1, v4, v5
	v_lshlrev_b32_e32 v4, 16, v3
	v_and_b32_e32 v5, 0xffff0000, v3
	v_mul_f32_e32 v3, 0xbfb8aa3b, v4
	v_exp_f32_e32 v15, v3
	v_mul_f32_e32 v3, 0xbfb8aa3b, v5
	v_exp_f32_e32 v16, v3
	v_add_f32_e32 v14, 1.0, v14
	v_add_f32_e32 v2, 1.0, v2
	v_rcp_f32_e32 v3, v14
	v_add_f32_e32 v14, 1.0, v15
	v_add_f32_e32 v15, 1.0, v16
	v_rcp_f32_e32 v2, v2
	v_rcp_f32_e32 v14, v14
	v_rcp_f32_e32 v15, v15
	v_pk_mul_f32 v[2:3], v[2:3], v[6:7]
	s_waitcnt lgkmcnt(0)
	v_pk_mul_f32 v[2:3], v[2:3], v[8:9]
	v_pk_mul_f32 v[4:5], v[14:15], v[4:5]
	v_cvt_pk_bf16_f32 v2, v2, v3
	v_pk_mul_f32 v[4:5], v[4:5], v[10:11]
	s_nop 0
	v_cvt_pk_bf16_f32 v3, v4, v5
	v_lshl_add_u32 v4, v18, 6, s0
	v_mad_i64_i32 v[4:5], s[6:7], v4, s44, v[12:13]
	v_lshl_add_u64 v[4:5], v[4:5], 0, v[32:33]
	v_add_co_u32_e32 v4, vcc, 0x18c00000, v4
	s_nop 1
	v_addc_co_u32_e32 v5, vcc, 0, v5, vcc
	global_store_dwordx4 v[4:5], v[0:3], off offset:2048 sc1

.LBB0_739:
	s_and_b32 s6, s18, 0xf0
	v_or_b32_e32 v8, s6, v35
	v_or_b32_e32 v8, s0, v8
	v_or_b32_e32 v12, 0x4000, v8
	v_lshrrev_b32_e32 v8, 2, v206
	v_lshlrev_b32_e32 v32, 13, v12
	v_and_b32_e32 v20, 12, v8
	v_lshl_add_u64 v[8:9], s[70:71], 0, v[32:33]
	s_mov_b64 s[6:7], 0x1e00
	v_lshl_add_u64 v[10:11], v[8:9], 0, s[6:7]
	v_mov_b64_e32 v[8:9], s[48:49]
	v_readlane_b32 s0, v254, 50
	v_mad_u64_u32 v[8:9], s[6:7], v12, s44, v[8:9]
	s_nop 0
	v_or_b32_e32 v12, s0, v20
	v_ashrrev_i32_e32 v13, 31, v12
	v_lshlrev_b64 v[12:13], 1, v[12:13]
	v_lshl_add_u64 v[14:15], v[10:11], 0, v[12:13]
	global_load_dwordx2 v[14:15], v[14:15], off
	s_brev_b32 s0, 60
	v_pk_mul_f32 v[4:5], v[4:5], s[0:1] op_sel_hi:[1,0]
	s_mov_b64 s[6:7], 0x18c00800
	v_pk_mul_f32 v[6:7], v[6:7], s[0:1] op_sel_hi:[1,0]
	v_lshl_add_u64 v[8:9], v[8:9], 0, s[6:7]
	v_readlane_b32 s6, v254, 51
	v_pk_mul_f32 v[0:1], v[0:1], s[0:1] op_sel_hi:[1,0]
	v_pk_mul_f32 v[2:3], v[2:3], s[0:1] op_sel_hi:[1,0]
	s_mov_b32 s18, s94
	s_waitcnt vmcnt(0)
	v_lshlrev_b32_e32 v16, 16, v14
	v_and_b32_e32 v17, 0xffff0000, v14
	v_mul_f32_e32 v14, 0xbfb8aa3b, v16
	v_exp_f32_e32 v14, v14
	s_nop 0
	v_add_f32_e32 v14, 1.0, v14
	v_rcp_f32_e32 v18, v14
	v_mul_f32_e32 v14, 0xbfb8aa3b, v17
	v_exp_f32_e32 v14, v14
	s_nop 0
	v_add_f32_e32 v14, 1.0, v14
	v_rcp_f32_e32 v19, v14
	v_lshlrev_b32_e32 v14, 16, v15
	v_and_b32_e32 v15, 0xffff0000, v15
	v_pk_mul_f32 v[16:17], v[18:19], v[16:17]
	s_nop 0
	v_pk_mul_f32 v[4:5], v[4:5], v[16:17]
	s_nop 0
	v_cvt_pk_bf16_f32 v4, v4, v5
	v_mul_f32_e32 v5, 0xbfb8aa3b, v14
	v_exp_f32_e32 v5, v5
	s_nop 0
	v_add_f32_e32 v5, 1.0, v5
	v_rcp_f32_e32 v16, v5
	v_mul_f32_e32 v5, 0xbfb8aa3b, v15
	v_exp_f32_e32 v5, v5
	s_nop 0
	v_add_f32_e32 v5, 1.0, v5
	v_rcp_f32_e32 v17, v5
	s_nop 0
	v_pk_mul_f32 v[14:15], v[16:17], v[14:15]
	s_nop 0
	v_pk_mul_f32 v[6:7], v[6:7], v[14:15]
	s_nop 0
	v_cvt_pk_bf16_f32 v5, v6, v7
	v_lshl_add_u64 v[6:7], v[8:9], 0, v[12:13]
	global_store_dwordx2 v[6:7], v[4:5], off sc1
	v_or_b32_e32 v4, s6, v20
	v_ashrrev_i32_e32 v5, 31, v4
	v_lshlrev_b64 v[4:5], 1, v[4:5]
	v_lshl_add_u64 v[6:7], v[10:11], 0, v[4:5]
	global_load_dwordx2 v[6:7], v[6:7], off
	s_mov_b64 s[6:7], s[76:77]
	s_waitcnt vmcnt(0)
	v_lshlrev_b32_e32 v10, 16, v6
	v_and_b32_e32 v11, 0xffff0000, v6
	v_mul_f32_e32 v6, 0xbfb8aa3b, v10
	v_exp_f32_e32 v6, v6
	s_nop 0
	v_add_f32_e32 v6, 1.0, v6
	v_rcp_f32_e32 v12, v6
	v_mul_f32_e32 v6, 0xbfb8aa3b, v11
	v_exp_f32_e32 v6, v6
	s_nop 0
	v_add_f32_e32 v6, 1.0, v6
	v_rcp_f32_e32 v13, v6
	v_lshlrev_b32_e32 v6, 16, v7
	v_and_b32_e32 v7, 0xffff0000, v7
	v_pk_mul_f32 v[10:11], v[12:13], v[10:11]
	s_nop 0
	v_pk_mul_f32 v[0:1], v[0:1], v[10:11]
	s_nop 0
	v_cvt_pk_bf16_f32 v0, v0, v1
	v_mul_f32_e32 v1, 0xbfb8aa3b, v6
	v_exp_f32_e32 v1, v1
	s_nop 0
	v_add_f32_e32 v1, 1.0, v1
	v_rcp_f32_e32 v10, v1
	v_mul_f32_e32 v1, 0xbfb8aa3b, v7
	v_exp_f32_e32 v1, v1
	s_nop 0
	v_add_f32_e32 v1, 1.0, v1
	v_rcp_f32_e32 v11, v1
	s_nop 0
	v_pk_mul_f32 v[6:7], v[10:11], v[6:7]
	s_nop 0
	v_pk_mul_f32 v[2:3], v[2:3], v[6:7]
	s_nop 0
	v_cvt_pk_bf16_f32 v1, v2, v3
	v_lshl_add_u64 v[2:3], v[8:9], 0, v[4:5]
	global_store_dwordx2 v[2:3], v[0:1], off sc1

.LBB0_760:
	v_lshrrev_b32_e32 v17, 3, v207
	s_waitcnt vmcnt(3)
	v_or_b32_e32 v122, s9, v17
	v_lshlrev_b32_e32 v18, 3, v207
	v_ashrrev_i32_e32 v123, 31, v122
	v_or_b32_e32 v120, 8, v122
	v_and_b32_e32 v37, 56, v18
	v_lshlrev_b64 v[18:19], 13, v[122:123]
	v_ashrrev_i32_e32 v121, 31, v120
	v_lshl_add_u64 v[18:19], s[70:71], 0, v[18:19]
	s_lshl_b32 s92, s8, 1
	v_lshlrev_b64 v[34:35], 13, v[120:121]
	v_lshl_add_u64 v[18:19], v[18:19], 0, s[92:93]
	v_lshlrev_b32_e32 v32, 1, v37
	v_lshl_add_u64 v[34:35], s[70:71], 0, v[34:35]
	v_lshl_add_u64 v[18:19], v[18:19], 0, v[32:33]
	v_lshl_add_u64 v[34:35], v[34:35], 0, s[92:93]
	v_lshl_add_u64 v[34:35], v[34:35], 0, v[32:33]
	global_load_dwordx4 v[114:117], v[18:19], off offset:1536
	global_load_dwordx4 v[110:113], v[34:35], off offset:1536
	v_or_b32_e32 v118, 16, v122
	v_or_b32_e32 v74, 24, v122
	v_ashrrev_i32_e32 v119, 31, v118
	v_ashrrev_i32_e32 v75, 31, v74
	v_lshlrev_b64 v[18:19], 13, v[118:119]
	v_lshlrev_b64 v[34:35], 13, v[74:75]
	v_lshl_add_u64 v[18:19], s[70:71], 0, v[18:19]
	v_lshl_add_u64 v[34:35], s[70:71], 0, v[34:35]
	v_lshl_add_u64 v[18:19], v[18:19], 0, s[92:93]
	v_lshl_add_u64 v[34:35], v[34:35], 0, s[92:93]
	v_or_b32_e32 v46, 32, v122
	v_or_b32_e32 v38, 40, v122
	v_lshl_add_u64 v[18:19], v[18:19], 0, v[32:33]
	v_lshl_add_u64 v[34:35], v[34:35], 0, v[32:33]
	v_ashrrev_i32_e32 v47, 31, v46
	v_ashrrev_i32_e32 v39, 31, v38
	global_load_dwordx4 v[104:107], v[18:19], off offset:1536
	global_load_dwordx4 v[100:103], v[34:35], off offset:1536
	v_lshlrev_b64 v[18:19], 13, v[46:47]
	v_lshlrev_b64 v[34:35], 13, v[38:39]
	v_lshl_add_u64 v[18:19], s[70:71], 0, v[18:19]
	v_lshl_add_u64 v[34:35], s[70:71], 0, v[34:35]
	v_lshl_add_u64 v[18:19], v[18:19], 0, s[92:93]
	v_lshl_add_u64 v[34:35], v[34:35], 0, s[92:93]
	v_lshl_add_u64 v[18:19], v[18:19], 0, v[32:33]
	v_lshl_add_u64 v[34:35], v[34:35], 0, v[32:33]
	global_load_dwordx4 v[96:99], v[18:19], off offset:1536
	global_load_dwordx4 v[92:95], v[34:35], off offset:1536
	v_or_b32_e32 v34, 48, v122
	v_ashrrev_i32_e32 v35, 31, v34
	v_lshlrev_b64 v[18:19], 13, v[34:35]
	v_lshl_add_u64 v[18:19], s[70:71], 0, v[18:19]
	v_lshl_add_u64 v[18:19], v[18:19], 0, s[92:93]
	v_lshl_add_u64 v[66:67], v[18:19], 0, v[32:33]
	v_or_b32_e32 v18, 56, v122
	v_ashrrev_i32_e32 v19, 31, v18
	v_lshlrev_b64 v[68:69], 13, v[18:19]
	v_div_scale_f32 v19, s[6:7], v108, v108, 1.0
	v_rcp_f32_e32 v35, v19
	v_lshl_add_u64 v[68:69], s[70:71], 0, v[68:69]
	v_readlane_b32 s8, v254, 45
	v_lshl_add_u64 v[68:69], v[68:69], 0, s[92:93]
	v_fma_f32 v39, -v19, v35, 1.0
	v_fmac_f32_e32 v35, v39, v35
	v_div_scale_f32 v39, vcc, 1.0, v108, 1.0
	v_mul_f32_e32 v45, v39, v35
	v_fma_f32 v47, -v19, v45, v39
	v_fmac_f32_e32 v45, v47, v35
	v_fma_f32 v19, -v19, v45, v39
	v_div_fmas_f32 v19, v19, v35, v45
	v_div_scale_f32 v35, s[6:7], v64, v64, 1.0
	v_rcp_f32_e32 v39, v35
	v_div_fixup_f32 v108, v19, v108, 1.0
	v_add3_u32 v19, s8, v208, v209
	v_lshl_add_u64 v[68:69], v[68:69], 0, v[32:33]
	v_fma_f32 v45, -v35, v39, 1.0
	v_fmac_f32_e32 v39, v45, v39
	v_div_scale_f32 v45, vcc, 1.0, v64, 1.0
	v_mul_f32_e32 v47, v45, v39
	v_fma_f32 v65, -v35, v47, v45
	v_fmac_f32_e32 v47, v65, v39
	v_fma_f32 v35, -v35, v47, v45
	v_div_fmas_f32 v35, v35, v39, v47
	v_div_fixup_f32 v64, v35, v64, 1.0
	v_pk_mul_f32 v[62:63], v[64:65], v[62:63] op_sel_hi:[0,1]
	v_pk_mul_f32 v[60:61], v[64:65], v[60:61] op_sel_hi:[0,1]
	v_pk_mul_f32 v[50:51], v[64:65], v[50:51] op_sel_hi:[0,1]
	v_pk_mul_f32 v[48:49], v[64:65], v[48:49] op_sel_hi:[0,1]
	v_div_scale_f32 v39, s[6:7], v44, v44, 1.0
	v_cvt_pk_bf16_f32 v60, v60, v61
	v_cvt_pk_bf16_f32 v61, v62, v63
	v_cvt_pk_bf16_f32 v48, v48, v49
	v_cvt_pk_bf16_f32 v49, v50, v51
	v_add_u32_e32 v35, 0x800, v19
	v_rcp_f32_e32 v45, v39
	global_load_dwordx4 v[70:73], v[66:67], off offset:1536
	s_nop 0
	global_load_dwordx4 v[66:69], v[68:69], off offset:1536
	s_barrier
	ds_write2_b64 v35, v[60:61], v[48:49] offset0:32 offset1:36
	v_pk_mul_f32 v[48:49], v[64:65], v[58:59] op_sel_hi:[0,1]
	v_pk_mul_f32 v[50:51], v[64:65], v[56:57] op_sel_hi:[0,1]
	v_cvt_pk_bf16_f32 v50, v50, v51
	v_cvt_pk_bf16_f32 v51, v48, v49
	v_pk_mul_f32 v[48:49], v[64:65], v[54:55] op_sel_hi:[0,1]
	v_pk_mul_f32 v[52:53], v[64:65], v[52:53] op_sel_hi:[0,1]
	v_cvt_pk_bf16_f32 v52, v52, v53
	v_cvt_pk_bf16_f32 v53, v48, v49
	ds_write2_b64 v35, v[50:51], v[52:53] offset0:40 offset1:44
	v_fma_f32 v35, -v39, v45, 1.0
	v_fmac_f32_e32 v45, v35, v45
	v_div_scale_f32 v35, vcc, 1.0, v44, 1.0
	v_mul_f32_e32 v47, v35, v45
	v_fma_f32 v48, -v39, v47, v35
	v_fmac_f32_e32 v47, v48, v45
	v_fma_f32 v35, -v39, v47, v35
	v_div_fmas_f32 v35, v35, v45, v47
	v_div_fixup_f32 v44, v35, v44, 1.0
	v_pk_mul_f32 v[42:43], v[44:45], v[42:43] op_sel_hi:[0,1]
	v_pk_mul_f32 v[40:41], v[44:45], v[40:41] op_sel_hi:[0,1]
	v_pk_mul_f32 v[22:23], v[44:45], v[22:23] op_sel_hi:[0,1]
	v_pk_mul_f32 v[20:21], v[44:45], v[20:21] op_sel_hi:[0,1]
	v_cvt_pk_bf16_f32 v40, v40, v41
	v_cvt_pk_bf16_f32 v41, v42, v43
	v_cvt_pk_bf16_f32 v20, v20, v21
	v_cvt_pk_bf16_f32 v21, v22, v23
	v_add_u32_e32 v35, 0x1000, v19
	ds_write2_b64 v35, v[40:41], v[20:21] offset0:64 offset1:68
	v_pk_mul_f32 v[20:21], v[44:45], v[30:31] op_sel_hi:[0,1]
	v_pk_mul_f32 v[22:23], v[44:45], v[28:29] op_sel_hi:[0,1]
	v_cvt_pk_bf16_f32 v22, v22, v23
	v_cvt_pk_bf16_f32 v23, v20, v21
	v_pk_mul_f32 v[20:21], v[44:45], v[26:27] op_sel_hi:[0,1]
	v_div_scale_f32 v26, s[6:7], v16, v16, 1.0
	v_rcp_f32_e32 v27, v26
	v_pk_mul_f32 v[24:25], v[44:45], v[24:25] op_sel_hi:[0,1]
	v_cvt_pk_bf16_f32 v24, v24, v25
	v_cvt_pk_bf16_f32 v25, v20, v21
	v_fma_f32 v20, -v26, v27, 1.0
	v_fmac_f32_e32 v27, v20, v27
	v_div_scale_f32 v20, vcc, 1.0, v16, 1.0
	v_mul_f32_e32 v21, v20, v27
	ds_write2_b64 v35, v[22:23], v[24:25] offset0:72 offset1:76
	v_fma_f32 v22, -v26, v21, v20
	v_fmac_f32_e32 v21, v22, v27
	v_fma_f32 v20, -v26, v21, v20
	v_div_fmas_f32 v20, v20, v27, v21
	v_div_fixup_f32 v16, v20, v16, 1.0
	v_pk_mul_f32 v[10:11], v[16:17], v[10:11] op_sel_hi:[0,1]
	v_pk_mul_f32 v[8:9], v[16:17], v[8:9] op_sel_hi:[0,1]
	v_pk_mul_f32 v[2:3], v[16:17], v[2:3] op_sel_hi:[0,1]
	v_pk_mul_f32 v[0:1], v[16:17], v[0:1] op_sel_hi:[0,1]
	v_cvt_pk_bf16_f32 v8, v8, v9
	v_cvt_pk_bf16_f32 v9, v10, v11
	v_cvt_pk_bf16_f32 v0, v0, v1
	v_cvt_pk_bf16_f32 v1, v2, v3
	v_add_u32_e32 v10, 0x1800, v19
	v_readlane_b32 s0, v254, 46
	ds_write2_b64 v10, v[8:9], v[0:1] offset0:96 offset1:100
	v_pk_mul_f32 v[0:1], v[16:17], v[14:15] op_sel_hi:[0,1]
	v_pk_mul_f32 v[2:3], v[16:17], v[12:13] op_sel_hi:[0,1]
	s_add_u32 s6, s0, s92
	v_readlane_b32 s0, v254, 47
	v_cvt_pk_bf16_f32 v2, v2, v3
	v_cvt_pk_bf16_f32 v3, v0, v1
	v_pk_mul_f32 v[0:1], v[16:17], v[6:7] op_sel_hi:[0,1]
	v_pk_mul_f32 v[4:5], v[16:17], v[4:5] op_sel_hi:[0,1]
	s_addc_u32 s7, s0, 0
	s_movk_i32 s0, 0x48
	v_cvt_pk_bf16_f32 v4, v4, v5
	v_cvt_pk_bf16_f32 v5, v0, v1
	v_mad_u32_u24 v0, v17, s0, v37
	ds_write2_b64 v10, v[2:3], v[4:5] offset0:104 offset1:108
	v_lshl_add_u32 v2, v0, 1, s8
	s_waitcnt vmcnt(7)
	v_lshlrev_b32_e32 v0, 16, v114
	v_and_b32_e32 v1, 0xffff0000, v114
	v_mul_f32_e32 v3, 0xbfb8aa3b, v0
	v_pk_mul_f32 v[90:91], v[108:109], v[90:91] op_sel_hi:[0,1]
	v_pk_mul_f32 v[88:89], v[108:109], v[88:89] op_sel_hi:[0,1]
	v_pk_mul_f32 v[78:79], v[108:109], v[78:79] op_sel_hi:[0,1]
	v_pk_mul_f32 v[76:77], v[108:109], v[76:77] op_sel_hi:[0,1]
	v_exp_f32_e32 v3, v3
	v_mul_f32_e32 v4, 0xbfb8aa3b, v1
	v_cvt_pk_bf16_f32 v88, v88, v89
	v_cvt_pk_bf16_f32 v89, v90, v91
	v_cvt_pk_bf16_f32 v76, v76, v77
	v_cvt_pk_bf16_f32 v77, v78, v79
	v_exp_f32_e32 v8, v4
	ds_write2_b64 v19, v[88:89], v[76:77] offset1:4
	v_pk_mul_f32 v[76:77], v[108:109], v[86:87] op_sel_hi:[0,1]
	v_pk_mul_f32 v[78:79], v[108:109], v[84:85] op_sel_hi:[0,1]
	v_cvt_pk_bf16_f32 v78, v78, v79
	v_cvt_pk_bf16_f32 v79, v76, v77
	v_pk_mul_f32 v[76:77], v[108:109], v[82:83] op_sel_hi:[0,1]
	v_pk_mul_f32 v[80:81], v[108:109], v[80:81] op_sel_hi:[0,1]
	v_cvt_pk_bf16_f32 v80, v80, v81
	v_cvt_pk_bf16_f32 v81, v76, v77
	v_add_f32_e32 v3, 1.0, v3
	ds_write2_b64 v19, v[78:79], v[80:81] offset0:8 offset1:12
	v_rcp_f32_e32 v12, v3
	v_add_f32_e32 v3, 1.0, v8
	s_waitcnt lgkmcnt(0)
	v_rcp_f32_e32 v13, v3
	ds_read_b128 v[4:7], v2
	ds_read_b128 v[8:11], v2 offset:1152
	s_mov_b32 s18, s94
	v_pk_mul_f32 v[0:1], v[12:13], v[0:1]
	v_lshlrev_b32_e32 v12, 16, v115
	v_and_b32_e32 v13, 0xffff0000, v115
	v_mul_f32_e32 v3, 0xbfb8aa3b, v12
	s_waitcnt lgkmcnt(1)
	v_lshlrev_b32_e32 v14, 16, v4
	v_and_b32_e32 v15, 0xffff0000, v4
	v_exp_f32_e32 v3, v3
	v_mul_f32_e32 v4, 0xbfb8aa3b, v13
	v_exp_f32_e32 v4, v4
	v_pk_mul_f32 v[0:1], v[0:1], v[14:15]
	v_add_f32_e32 v3, 1.0, v3
	v_rcp_f32_e32 v14, v3
	v_add_f32_e32 v3, 1.0, v4
	v_rcp_f32_e32 v15, v3
	v_cvt_pk_bf16_f32 v4, v0, v1
	v_lshlrev_b32_e32 v0, 16, v5
	v_and_b32_e32 v1, 0xffff0000, v5
	v_pk_mul_f32 v[12:13], v[14:15], v[12:13]
	v_lshlrev_b32_e32 v14, 16, v116
	v_and_b32_e32 v15, 0xffff0000, v116
	v_mul_f32_e32 v3, 0xbfb8aa3b, v14
	v_exp_f32_e32 v3, v3
	v_mul_f32_e32 v5, 0xbfb8aa3b, v15
	v_exp_f32_e32 v5, v5
	v_pk_mul_f32 v[0:1], v[12:13], v[0:1]
	v_add_f32_e32 v3, 1.0, v3
	v_rcp_f32_e32 v12, v3
	v_add_f32_e32 v3, 1.0, v5
	v_rcp_f32_e32 v13, v3
	v_cvt_pk_bf16_f32 v5, v0, v1
	v_lshlrev_b32_e32 v0, 16, v6
	v_and_b32_e32 v1, 0xffff0000, v6
	v_pk_mul_f32 v[12:13], v[12:13], v[14:15]
	v_lshlrev_b32_e32 v14, 16, v117
	v_and_b32_e32 v15, 0xffff0000, v117
	v_mul_f32_e32 v3, 0xbfb8aa3b, v14
	v_exp_f32_e32 v3, v3
	v_mul_f32_e32 v6, 0xbfb8aa3b, v15
	v_exp_f32_e32 v6, v6
	v_pk_mul_f32 v[0:1], v[12:13], v[0:1]
	v_add_f32_e32 v3, 1.0, v3
	v_rcp_f32_e32 v12, v3
	v_add_f32_e32 v3, 1.0, v6
	v_rcp_f32_e32 v13, v3
	v_cvt_pk_bf16_f32 v6, v0, v1
	v_lshlrev_b32_e32 v0, 16, v7
	v_and_b32_e32 v1, 0xffff0000, v7
	v_pk_mul_f32 v[12:13], v[12:13], v[14:15]
	s_waitcnt vmcnt(6)
	v_lshlrev_b32_e32 v14, 16, v110
	v_and_b32_e32 v15, 0xffff0000, v110
	v_mul_f32_e32 v3, 0xbfb8aa3b, v14
	v_exp_f32_e32 v3, v3
	v_mul_f32_e32 v16, 0xbfb8aa3b, v15
	v_pk_mul_f32 v[0:1], v[12:13], v[0:1]
	v_exp_f32_e32 v17, v16
	v_cvt_pk_bf16_f32 v7, v0, v1
	v_mov_b64_e32 v[0:1], s[6:7]
	v_mad_i64_i32 v[12:13], s[6:7], v122, s44, v[0:1]
	v_lshl_add_u64 v[12:13], v[12:13], 0, v[32:33]
	v_add_f32_e32 v3, 1.0, v3
	v_rcp_f32_e32 v16, v3
	v_add_f32_e32 v3, 1.0, v17
	global_store_dwordx4 v[12:13], v[4:7], off sc1
	v_lshlrev_b32_e32 v12, 16, v111
	v_rcp_f32_e32 v17, v3
	v_and_b32_e32 v13, 0xffff0000, v111
	v_mul_f32_e32 v3, 0xbfb8aa3b, v12
	s_waitcnt lgkmcnt(0)
	v_lshlrev_b32_e32 v4, 16, v8
	v_and_b32_e32 v5, 0xffff0000, v8
	v_exp_f32_e32 v3, v3
	v_mul_f32_e32 v8, 0xbfb8aa3b, v13
	v_exp_f32_e32 v8, v8
	v_pk_mul_f32 v[6:7], v[16:17], v[14:15]
	v_add_f32_e32 v3, 1.0, v3
	v_pk_mul_f32 v[4:5], v[6:7], v[4:5]
	v_rcp_f32_e32 v6, v3
	v_add_f32_e32 v3, 1.0, v8
	v_rcp_f32_e32 v7, v3
	v_cvt_pk_bf16_f32 v4, v4, v5
	v_lshlrev_b32_e32 v8, 16, v9
	v_and_b32_e32 v9, 0xffff0000, v9
	v_pk_mul_f32 v[6:7], v[6:7], v[12:13]
	v_lshlrev_b32_e32 v12, 16, v112
	v_and_b32_e32 v13, 0xffff0000, v112
	v_mul_f32_e32 v3, 0xbfb8aa3b, v12
	v_exp_f32_e32 v3, v3
	v_mul_f32_e32 v5, 0xbfb8aa3b, v13
	v_exp_f32_e32 v5, v5
	v_pk_mul_f32 v[6:7], v[6:7], v[8:9]
	v_add_f32_e32 v3, 1.0, v3
	v_rcp_f32_e32 v8, v3
	v_add_f32_e32 v3, 1.0, v5
	v_rcp_f32_e32 v9, v3
	v_cvt_pk_bf16_f32 v5, v6, v7
	v_lshlrev_b32_e32 v6, 16, v10
	v_and_b32_e32 v7, 0xffff0000, v10
	v_pk_mul_f32 v[8:9], v[8:9], v[12:13]
	v_lshlrev_b32_e32 v12, 16, v113
	v_and_b32_e32 v13, 0xffff0000, v113
	v_mul_f32_e32 v3, 0xbfb8aa3b, v12
	v_exp_f32_e32 v3, v3
	v_mul_f32_e32 v10, 0xbfb8aa3b, v13
	v_exp_f32_e32 v10, v10
	v_pk_mul_f32 v[6:7], v[8:9], v[6:7]
	v_add_f32_e32 v3, 1.0, v3
	v_rcp_f32_e32 v8, v3
	v_add_f32_e32 v3, 1.0, v10
	v_rcp_f32_e32 v9, v3
	v_lshlrev_b32_e32 v10, 16, v11
	v_and_b32_e32 v11, 0xffff0000, v11
	v_cvt_pk_bf16_f32 v6, v6, v7
	v_pk_mul_f32 v[8:9], v[8:9], v[12:13]
	s_waitcnt vmcnt(6)
	v_lshlrev_b32_e32 v12, 16, v104
	v_pk_mul_f32 v[8:9], v[8:9], v[10:11]
	v_and_b32_e32 v13, 0xffff0000, v104
	v_cvt_pk_bf16_f32 v7, v8, v9
	v_mad_i64_i32 v[8:9], s[6:7], v120, s44, v[0:1]
	v_lshl_add_u64 v[8:9], v[8:9], 0, v[32:33]
	v_mul_f32_e32 v3, 0xbfb8aa3b, v12
	global_store_dwordx4 v[8:9], v[4:7], off sc1
	v_exp_f32_e32 v3, v3
	s_nop 0
	v_mul_f32_e32 v4, 0xbfb8aa3b, v13
	v_exp_f32_e32 v8, v4
	v_add_f32_e32 v3, 1.0, v3
	v_rcp_f32_e32 v14, v3
	ds_read_b128 v[4:7], v2 offset:2304
	v_add_f32_e32 v3, 1.0, v8
	v_rcp_f32_e32 v15, v3
	ds_read_b128 v[8:11], v2 offset:3456
	s_waitcnt lgkmcnt(1)
	v_lshlrev_b32_e32 v16, 16, v4
	v_pk_mul_f32 v[12:13], v[14:15], v[12:13]
	v_lshlrev_b32_e32 v14, 16, v105
	v_and_b32_e32 v15, 0xffff0000, v105
	v_mul_f32_e32 v3, 0xbfb8aa3b, v14
	v_and_b32_e32 v17, 0xffff0000, v4
	v_exp_f32_e32 v3, v3
	v_mul_f32_e32 v4, 0xbfb8aa3b, v15
	v_exp_f32_e32 v4, v4
	v_pk_mul_f32 v[12:13], v[12:13], v[16:17]
	v_add_f32_e32 v3, 1.0, v3
	v_rcp_f32_e32 v16, v3
	v_add_f32_e32 v3, 1.0, v4
	v_rcp_f32_e32 v17, v3
	v_cvt_pk_bf16_f32 v4, v12, v13
	v_lshlrev_b32_e32 v12, 16, v5
	v_and_b32_e32 v13, 0xffff0000, v5
	v_pk_mul_f32 v[14:15], v[16:17], v[14:15]
	v_lshlrev_b32_e32 v16, 16, v106
	v_and_b32_e32 v17, 0xffff0000, v106
	v_mul_f32_e32 v3, 0xbfb8aa3b, v16
	v_exp_f32_e32 v3, v3
	v_mul_f32_e32 v5, 0xbfb8aa3b, v17
	v_exp_f32_e32 v5, v5
	v_pk_mul_f32 v[12:13], v[14:15], v[12:13]
	v_add_f32_e32 v3, 1.0, v3
	v_rcp_f32_e32 v14, v3
	v_add_f32_e32 v3, 1.0, v5
	v_rcp_f32_e32 v15, v3
	v_cvt_pk_bf16_f32 v5, v12, v13
	v_lshlrev_b32_e32 v12, 16, v6
	v_and_b32_e32 v13, 0xffff0000, v6
	v_pk_mul_f32 v[14:15], v[14:15], v[16:17]
	v_lshlrev_b32_e32 v16, 16, v107
	v_and_b32_e32 v17, 0xffff0000, v107
	v_mul_f32_e32 v3, 0xbfb8aa3b, v16
	v_exp_f32_e32 v3, v3
	v_mul_f32_e32 v6, 0xbfb8aa3b, v17
	v_exp_f32_e32 v6, v6
	v_pk_mul_f32 v[12:13], v[14:15], v[12:13]
	v_add_f32_e32 v3, 1.0, v3
	v_rcp_f32_e32 v14, v3
	v_add_f32_e32 v3, 1.0, v6
	v_rcp_f32_e32 v15, v3
	v_cvt_pk_bf16_f32 v6, v12, v13
	v_lshlrev_b32_e32 v12, 16, v7
	v_and_b32_e32 v13, 0xffff0000, v7
	v_pk_mul_f32 v[14:15], v[14:15], v[16:17]
	s_nop 0
	v_pk_mul_f32 v[12:13], v[14:15], v[12:13]
	s_waitcnt vmcnt(6)
	v_lshlrev_b32_e32 v14, 16, v100
	v_and_b32_e32 v15, 0xffff0000, v100
	v_mul_f32_e32 v3, 0xbfb8aa3b, v14
	v_exp_f32_e32 v3, v3
	v_mul_f32_e32 v16, 0xbfb8aa3b, v15
	v_exp_f32_e32 v17, v16
	v_cvt_pk_bf16_f32 v7, v12, v13
	v_mad_i64_i32 v[12:13], s[6:7], v118, s44, v[0:1]
	v_lshl_add_u64 v[12:13], v[12:13], 0, v[32:33]
	v_add_f32_e32 v3, 1.0, v3
	v_rcp_f32_e32 v16, v3
	v_add_f32_e32 v3, 1.0, v17
	global_store_dwordx4 v[12:13], v[4:7], off sc1
	v_lshlrev_b32_e32 v12, 16, v101
	v_rcp_f32_e32 v17, v3
	v_and_b32_e32 v13, 0xffff0000, v101
	v_mul_f32_e32 v3, 0xbfb8aa3b, v12
	s_waitcnt lgkmcnt(0)
	v_lshlrev_b32_e32 v4, 16, v8
	v_and_b32_e32 v5, 0xffff0000, v8
	v_exp_f32_e32 v3, v3
	v_mul_f32_e32 v8, 0xbfb8aa3b, v13
	v_exp_f32_e32 v8, v8
	v_pk_mul_f32 v[6:7], v[16:17], v[14:15]
	v_add_f32_e32 v3, 1.0, v3
	v_pk_mul_f32 v[4:5], v[6:7], v[4:5]
	v_rcp_f32_e32 v6, v3
	v_add_f32_e32 v3, 1.0, v8
	v_rcp_f32_e32 v7, v3
	v_cvt_pk_bf16_f32 v4, v4, v5
	v_lshlrev_b32_e32 v8, 16, v9
	v_and_b32_e32 v9, 0xffff0000, v9
	v_pk_mul_f32 v[6:7], v[6:7], v[12:13]
	v_lshlrev_b32_e32 v12, 16, v102
	v_and_b32_e32 v13, 0xffff0000, v102
	v_mul_f32_e32 v3, 0xbfb8aa3b, v12
	v_exp_f32_e32 v3, v3
	v_mul_f32_e32 v5, 0xbfb8aa3b, v13
	v_exp_f32_e32 v5, v5
	v_pk_mul_f32 v[6:7], v[6:7], v[8:9]
	v_add_f32_e32 v3, 1.0, v3
	v_rcp_f32_e32 v8, v3
	v_add_f32_e32 v3, 1.0, v5
	v_rcp_f32_e32 v9, v3
	v_cvt_pk_bf16_f32 v5, v6, v7
	v_lshlrev_b32_e32 v6, 16, v10
	v_and_b32_e32 v7, 0xffff0000, v10
	v_pk_mul_f32 v[8:9], v[8:9], v[12:13]
	v_lshlrev_b32_e32 v12, 16, v103
	v_and_b32_e32 v13, 0xffff0000, v103
	v_mul_f32_e32 v3, 0xbfb8aa3b, v12
	v_exp_f32_e32 v3, v3
	v_mul_f32_e32 v10, 0xbfb8aa3b, v13
	v_exp_f32_e32 v10, v10
	v_pk_mul_f32 v[6:7], v[8:9], v[6:7]
	v_add_f32_e32 v3, 1.0, v3
	v_rcp_f32_e32 v8, v3
	v_add_f32_e32 v3, 1.0, v10
	v_rcp_f32_e32 v9, v3
	v_lshlrev_b32_e32 v10, 16, v11
	v_and_b32_e32 v11, 0xffff0000, v11
	v_cvt_pk_bf16_f32 v6, v6, v7
	v_pk_mul_f32 v[8:9], v[8:9], v[12:13]
	s_waitcnt vmcnt(6)
	v_lshlrev_b32_e32 v12, 16, v96
	v_pk_mul_f32 v[8:9], v[8:9], v[10:11]
	v_and_b32_e32 v13, 0xffff0000, v96
	v_cvt_pk_bf16_f32 v7, v8, v9
	v_mad_i64_i32 v[8:9], s[6:7], v74, s44, v[0:1]
	v_lshl_add_u64 v[8:9], v[8:9], 0, v[32:33]
	v_mul_f32_e32 v3, 0xbfb8aa3b, v12
	global_store_dwordx4 v[8:9], v[4:7], off sc1
	v_exp_f32_e32 v3, v3
	s_nop 0
	v_mul_f32_e32 v4, 0xbfb8aa3b, v13
	v_exp_f32_e32 v8, v4
	v_add_f32_e32 v3, 1.0, v3
	v_rcp_f32_e32 v14, v3
	ds_read_b128 v[4:7], v2 offset:4608
	v_add_f32_e32 v3, 1.0, v8
	v_rcp_f32_e32 v15, v3
	ds_read_b128 v[8:11], v2 offset:5760
	s_waitcnt lgkmcnt(1)
	v_lshlrev_b32_e32 v16, 16, v4
	v_pk_mul_f32 v[12:13], v[14:15], v[12:13]
	v_lshlrev_b32_e32 v14, 16, v97
	v_and_b32_e32 v15, 0xffff0000, v97
	v_mul_f32_e32 v3, 0xbfb8aa3b, v14
	v_and_b32_e32 v17, 0xffff0000, v4
	v_exp_f32_e32 v3, v3
	v_mul_f32_e32 v4, 0xbfb8aa3b, v15
	v_exp_f32_e32 v4, v4
	v_pk_mul_f32 v[12:13], v[12:13], v[16:17]
	v_add_f32_e32 v3, 1.0, v3
	v_rcp_f32_e32 v16, v3
	v_add_f32_e32 v3, 1.0, v4
	v_rcp_f32_e32 v17, v3
	v_cvt_pk_bf16_f32 v4, v12, v13
	v_lshlrev_b32_e32 v12, 16, v5
	v_and_b32_e32 v13, 0xffff0000, v5
	v_pk_mul_f32 v[14:15], v[16:17], v[14:15]
	v_lshlrev_b32_e32 v16, 16, v98
	v_and_b32_e32 v17, 0xffff0000, v98
	v_mul_f32_e32 v3, 0xbfb8aa3b, v16
	v_exp_f32_e32 v3, v3
	v_mul_f32_e32 v5, 0xbfb8aa3b, v17
	v_exp_f32_e32 v5, v5
	v_pk_mul_f32 v[12:13], v[14:15], v[12:13]
	v_add_f32_e32 v3, 1.0, v3
	v_rcp_f32_e32 v14, v3
	v_add_f32_e32 v3, 1.0, v5
	v_rcp_f32_e32 v15, v3
	v_cvt_pk_bf16_f32 v5, v12, v13
	v_lshlrev_b32_e32 v12, 16, v6
	v_and_b32_e32 v13, 0xffff0000, v6
	v_pk_mul_f32 v[14:15], v[14:15], v[16:17]
	v_lshlrev_b32_e32 v16, 16, v99
	v_and_b32_e32 v17, 0xffff0000, v99
	v_mul_f32_e32 v3, 0xbfb8aa3b, v16
	v_exp_f32_e32 v3, v3
	v_mul_f32_e32 v6, 0xbfb8aa3b, v17
	v_exp_f32_e32 v6, v6
	v_pk_mul_f32 v[12:13], v[14:15], v[12:13]
	v_add_f32_e32 v3, 1.0, v3
	v_rcp_f32_e32 v14, v3
	v_add_f32_e32 v3, 1.0, v6
	v_rcp_f32_e32 v15, v3
	v_cvt_pk_bf16_f32 v6, v12, v13
	v_lshlrev_b32_e32 v12, 16, v7
	v_and_b32_e32 v13, 0xffff0000, v7
	v_pk_mul_f32 v[14:15], v[14:15], v[16:17]
	s_nop 0
	v_pk_mul_f32 v[12:13], v[14:15], v[12:13]
	s_waitcnt vmcnt(6)
	v_lshlrev_b32_e32 v14, 16, v92
	v_and_b32_e32 v15, 0xffff0000, v92
	v_mul_f32_e32 v3, 0xbfb8aa3b, v14
	v_exp_f32_e32 v3, v3
	v_mul_f32_e32 v16, 0xbfb8aa3b, v15
	v_exp_f32_e32 v17, v16
	v_cvt_pk_bf16_f32 v7, v12, v13
	v_mad_i64_i32 v[12:13], s[6:7], v46, s44, v[0:1]
	v_lshl_add_u64 v[12:13], v[12:13], 0, v[32:33]
	v_add_f32_e32 v3, 1.0, v3
	v_rcp_f32_e32 v16, v3
	v_add_f32_e32 v3, 1.0, v17
	global_store_dwordx4 v[12:13], v[4:7], off sc1
	v_lshlrev_b32_e32 v12, 16, v93
	v_rcp_f32_e32 v17, v3
	v_and_b32_e32 v13, 0xffff0000, v93
	v_mul_f32_e32 v3, 0xbfb8aa3b, v12
	s_waitcnt lgkmcnt(0)
	v_lshlrev_b32_e32 v4, 16, v8
	v_and_b32_e32 v5, 0xffff0000, v8
	v_exp_f32_e32 v3, v3
	v_mul_f32_e32 v8, 0xbfb8aa3b, v13
	v_exp_f32_e32 v8, v8
	v_pk_mul_f32 v[6:7], v[16:17], v[14:15]
	v_add_f32_e32 v3, 1.0, v3
	v_pk_mul_f32 v[4:5], v[6:7], v[4:5]
	v_rcp_f32_e32 v6, v3
	v_add_f32_e32 v3, 1.0, v8
	v_rcp_f32_e32 v7, v3
	v_cvt_pk_bf16_f32 v4, v4, v5
	v_lshlrev_b32_e32 v8, 16, v9
	v_and_b32_e32 v9, 0xffff0000, v9
	v_pk_mul_f32 v[6:7], v[6:7], v[12:13]
	v_lshlrev_b32_e32 v12, 16, v94
	v_and_b32_e32 v13, 0xffff0000, v94
	v_mul_f32_e32 v3, 0xbfb8aa3b, v12
	v_exp_f32_e32 v3, v3
	v_mul_f32_e32 v5, 0xbfb8aa3b, v13
	v_exp_f32_e32 v5, v5
	v_pk_mul_f32 v[6:7], v[6:7], v[8:9]
	v_add_f32_e32 v3, 1.0, v3
	v_rcp_f32_e32 v8, v3
	v_add_f32_e32 v3, 1.0, v5
	v_rcp_f32_e32 v9, v3
	v_cvt_pk_bf16_f32 v5, v6, v7
	v_lshlrev_b32_e32 v6, 16, v10
	v_and_b32_e32 v7, 0xffff0000, v10
	v_pk_mul_f32 v[8:9], v[8:9], v[12:13]
	v_lshlrev_b32_e32 v12, 16, v95
	v_and_b32_e32 v13, 0xffff0000, v95
	v_mul_f32_e32 v3, 0xbfb8aa3b, v12
	v_exp_f32_e32 v3, v3
	v_mul_f32_e32 v10, 0xbfb8aa3b, v13
	v_exp_f32_e32 v10, v10
	v_pk_mul_f32 v[6:7], v[8:9], v[6:7]
	v_add_f32_e32 v3, 1.0, v3
	v_rcp_f32_e32 v8, v3
	v_add_f32_e32 v3, 1.0, v10
	v_rcp_f32_e32 v9, v3
	v_lshlrev_b32_e32 v10, 16, v11
	v_and_b32_e32 v11, 0xffff0000, v11
	v_cvt_pk_bf16_f32 v6, v6, v7
	v_pk_mul_f32 v[8:9], v[8:9], v[12:13]
	s_waitcnt vmcnt(6)
	v_lshlrev_b32_e32 v12, 16, v70
	v_pk_mul_f32 v[8:9], v[8:9], v[10:11]
	v_and_b32_e32 v13, 0xffff0000, v70
	v_cvt_pk_bf16_f32 v7, v8, v9
	v_mad_i64_i32 v[8:9], s[6:7], v38, s44, v[0:1]
	v_lshl_add_u64 v[8:9], v[8:9], 0, v[32:33]
	v_mul_f32_e32 v3, 0xbfb8aa3b, v12
	global_store_dwordx4 v[8:9], v[4:7], off sc1
	v_exp_f32_e32 v3, v3
	s_nop 0
	v_mul_f32_e32 v4, 0xbfb8aa3b, v13
	v_exp_f32_e32 v8, v4
	v_add_f32_e32 v3, 1.0, v3
	v_rcp_f32_e32 v14, v3
	ds_read_b128 v[4:7], v2 offset:6912
	v_add_f32_e32 v3, 1.0, v8
	v_rcp_f32_e32 v15, v3
	ds_read_b128 v[8:11], v2 offset:8064
	s_waitcnt lgkmcnt(1)
	v_lshlrev_b32_e32 v2, 16, v4
	v_pk_mul_f32 v[12:13], v[14:15], v[12:13]
	v_lshlrev_b32_e32 v14, 16, v71
	v_and_b32_e32 v3, 0xffff0000, v4
	v_and_b32_e32 v15, 0xffff0000, v71
	v_mul_f32_e32 v4, 0xbfb8aa3b, v14
	v_exp_f32_e32 v4, v4
	v_mul_f32_e32 v16, 0xbfb8aa3b, v15
	v_exp_f32_e32 v16, v16
	v_pk_mul_f32 v[2:3], v[12:13], v[2:3]
	v_add_f32_e32 v4, 1.0, v4
	v_rcp_f32_e32 v12, v4
	v_add_f32_e32 v4, 1.0, v16
	v_rcp_f32_e32 v13, v4
	v_cvt_pk_bf16_f32 v2, v2, v3
	v_lshlrev_b32_e32 v4, 16, v5
	v_and_b32_e32 v5, 0xffff0000, v5
	v_pk_mul_f32 v[12:13], v[12:13], v[14:15]
	v_lshlrev_b32_e32 v14, 16, v72
	v_and_b32_e32 v15, 0xffff0000, v72
	v_mul_f32_e32 v3, 0xbfb8aa3b, v14
	v_exp_f32_e32 v3, v3
	v_mul_f32_e32 v16, 0xbfb8aa3b, v15
	v_exp_f32_e32 v16, v16
	v_pk_mul_f32 v[4:5], v[12:13], v[4:5]
	v_add_f32_e32 v3, 1.0, v3
	v_rcp_f32_e32 v12, v3
	v_add_f32_e32 v3, 1.0, v16
	v_rcp_f32_e32 v13, v3
	v_cvt_pk_bf16_f32 v3, v4, v5
	v_lshlrev_b32_e32 v4, 16, v6
	v_and_b32_e32 v5, 0xffff0000, v6
	v_pk_mul_f32 v[12:13], v[12:13], v[14:15]
	v_lshlrev_b32_e32 v14, 16, v73
	v_and_b32_e32 v15, 0xffff0000, v73
	v_mul_f32_e32 v6, 0xbfb8aa3b, v14
	v_exp_f32_e32 v6, v6
	v_mul_f32_e32 v16, 0xbfb8aa3b, v15
	v_exp_f32_e32 v16, v16
	v_pk_mul_f32 v[4:5], v[12:13], v[4:5]
	v_add_f32_e32 v6, 1.0, v6
	v_rcp_f32_e32 v12, v6
	v_add_f32_e32 v6, 1.0, v16
	v_rcp_f32_e32 v13, v6
	v_lshlrev_b32_e32 v6, 16, v7
	v_and_b32_e32 v7, 0xffff0000, v7
	v_cvt_pk_bf16_f32 v4, v4, v5
	v_pk_mul_f32 v[12:13], v[12:13], v[14:15]
	s_nop 0
	v_pk_mul_f32 v[6:7], v[12:13], v[6:7]
	s_waitcnt vmcnt(6)
	v_lshlrev_b32_e32 v12, 16, v66
	v_and_b32_e32 v13, 0xffff0000, v66
	v_mul_f32_e32 v14, 0xbfb8aa3b, v12
	v_mul_f32_e32 v15, 0xbfb8aa3b, v13
	v_exp_f32_e32 v14, v14
	v_exp_f32_e32 v15, v15
	v_cvt_pk_bf16_f32 v5, v6, v7
	v_mad_i64_i32 v[6:7], s[6:7], v34, s44, v[0:1]
	v_add_f32_e32 v14, 1.0, v14
	v_add_f32_e32 v15, 1.0, v15
	v_rcp_f32_e32 v14, v14
	v_rcp_f32_e32 v15, v15
	v_lshl_add_u64 v[6:7], v[6:7], 0, v[32:33]
	global_store_dwordx4 v[6:7], v[2:5], off sc1
	v_lshlrev_b32_e32 v6, 16, v67
	v_and_b32_e32 v7, 0xffff0000, v67
	s_waitcnt lgkmcnt(0)
	v_lshlrev_b32_e32 v2, 16, v8
	v_and_b32_e32 v3, 0xffff0000, v8
	v_pk_mul_f32 v[4:5], v[14:15], v[12:13]
	v_mul_f32_e32 v8, 0xbfb8aa3b, v6
	v_mul_f32_e32 v12, 0xbfb8aa3b, v7
	v_exp_f32_e32 v8, v8
	v_exp_f32_e32 v12, v12
	v_pk_mul_f32 v[2:3], v[4:5], v[2:3]
	v_mad_i64_i32 v[0:1], s[6:7], v18, s44, v[0:1]
	v_add_f32_e32 v4, 1.0, v8
	v_add_f32_e32 v5, 1.0, v12
	v_rcp_f32_e32 v4, v4
	v_rcp_f32_e32 v5, v5
	v_cvt_pk_bf16_f32 v2, v2, v3
	v_lshlrev_b32_e32 v8, 16, v9
	v_and_b32_e32 v9, 0xffff0000, v9
	v_pk_mul_f32 v[4:5], v[4:5], v[6:7]
	v_lshlrev_b32_e32 v6, 16, v68
	v_and_b32_e32 v7, 0xffff0000, v68
	v_mul_f32_e32 v3, 0xbfb8aa3b, v6
	v_exp_f32_e32 v3, v3
	v_mul_f32_e32 v12, 0xbfb8aa3b, v7
	v_exp_f32_e32 v12, v12
	v_pk_mul_f32 v[4:5], v[4:5], v[8:9]
	v_add_f32_e32 v3, 1.0, v3
	v_rcp_f32_e32 v8, v3
	v_add_f32_e32 v3, 1.0, v12
	v_rcp_f32_e32 v9, v3
	v_cvt_pk_bf16_f32 v3, v4, v5
	v_lshlrev_b32_e32 v4, 16, v10
	v_and_b32_e32 v5, 0xffff0000, v10
	v_pk_mul_f32 v[6:7], v[8:9], v[6:7]
	v_lshlrev_b32_e32 v8, 16, v69
	v_and_b32_e32 v9, 0xffff0000, v69
	v_mul_f32_e32 v10, 0xbfb8aa3b, v8
	v_mul_f32_e32 v12, 0xbfb8aa3b, v9
	v_exp_f32_e32 v10, v10
	v_exp_f32_e32 v12, v12
	v_pk_mul_f32 v[4:5], v[6:7], v[4:5]
	v_lshl_add_u64 v[0:1], v[0:1], 0, v[32:33]
	v_add_f32_e32 v6, 1.0, v10
	v_add_f32_e32 v7, 1.0, v12
	v_rcp_f32_e32 v6, v6
	v_rcp_f32_e32 v7, v7
	v_lshlrev_b32_e32 v10, 16, v11
	v_and_b32_e32 v11, 0xffff0000, v11
	v_cvt_pk_bf16_f32 v4, v4, v5
	v_pk_mul_f32 v[6:7], v[6:7], v[8:9]
	s_mov_b64 s[6:7], s[76:77]
	v_pk_mul_f32 v[6:7], v[6:7], v[10:11]
	s_nop 0
	v_cvt_pk_bf16_f32 v5, v6, v7
	global_store_dwordx4 v[0:1], v[2:5], off sc1

.LBB0_803:
	v_lshrrev_b32_e32 v17, 3, v207
	s_waitcnt vmcnt(3)
	v_or_b32_e32 v122, s82, v17
	v_lshlrev_b32_e32 v18, 3, v207
	v_ashrrev_i32_e32 v123, 31, v122
	v_or_b32_e32 v120, 8, v122
	v_and_b32_e32 v37, 56, v18
	v_lshlrev_b64 v[18:19], 13, v[122:123]
	v_ashrrev_i32_e32 v121, 31, v120
	v_lshl_add_u64 v[18:19], s[70:71], 0, v[18:19]
	s_lshl_b32 s92, s57, 1
	v_lshlrev_b64 v[34:35], 13, v[120:121]
	v_lshl_add_u64 v[18:19], v[18:19], 0, s[92:93]
	v_lshlrev_b32_e32 v32, 1, v37
	v_lshl_add_u64 v[34:35], s[70:71], 0, v[34:35]
	v_lshl_add_u64 v[18:19], v[18:19], 0, v[32:33]
	v_lshl_add_u64 v[34:35], v[34:35], 0, s[92:93]
	v_lshl_add_u64 v[34:35], v[34:35], 0, v[32:33]
	global_load_dwordx4 v[112:115], v[18:19], off offset:1536
	global_load_dwordx4 v[108:111], v[34:35], off offset:1536
	v_or_b32_e32 v118, 16, v122
	v_or_b32_e32 v66, 24, v122
	v_ashrrev_i32_e32 v119, 31, v118
	v_ashrrev_i32_e32 v67, 31, v66
	v_lshlrev_b64 v[18:19], 13, v[118:119]
	v_lshlrev_b64 v[34:35], 13, v[66:67]
	v_lshl_add_u64 v[18:19], s[70:71], 0, v[18:19]
	v_lshl_add_u64 v[34:35], s[70:71], 0, v[34:35]
	v_lshl_add_u64 v[18:19], v[18:19], 0, s[92:93]
	v_lshl_add_u64 v[34:35], v[34:35], 0, s[92:93]
	v_or_b32_e32 v46, 32, v122
	v_or_b32_e32 v38, 40, v122
	v_lshl_add_u64 v[18:19], v[18:19], 0, v[32:33]
	v_lshl_add_u64 v[34:35], v[34:35], 0, v[32:33]
	v_ashrrev_i32_e32 v47, 31, v46
	v_ashrrev_i32_e32 v39, 31, v38
	global_load_dwordx4 v[104:107], v[18:19], off offset:1536
	global_load_dwordx4 v[100:103], v[34:35], off offset:1536
	v_lshlrev_b64 v[18:19], 13, v[46:47]
	v_lshlrev_b64 v[34:35], 13, v[38:39]
	v_lshl_add_u64 v[18:19], s[70:71], 0, v[18:19]
	v_lshl_add_u64 v[34:35], s[70:71], 0, v[34:35]
	v_lshl_add_u64 v[18:19], v[18:19], 0, s[92:93]
	v_lshl_add_u64 v[34:35], v[34:35], 0, s[92:93]
	v_lshl_add_u64 v[18:19], v[18:19], 0, v[32:33]
	v_lshl_add_u64 v[34:35], v[34:35], 0, v[32:33]
	global_load_dwordx4 v[88:91], v[18:19], off offset:1536
	global_load_dwordx4 v[84:87], v[34:35], off offset:1536
	v_or_b32_e32 v34, 48, v122
	v_ashrrev_i32_e32 v35, 31, v34
	v_lshlrev_b64 v[18:19], 13, v[34:35]
	v_lshl_add_u64 v[18:19], s[70:71], 0, v[18:19]
	v_lshl_add_u64 v[18:19], v[18:19], 0, s[92:93]
	v_lshl_add_u64 v[72:73], v[18:19], 0, v[32:33]
	v_or_b32_e32 v18, 56, v122
	v_ashrrev_i32_e32 v19, 31, v18
	v_lshlrev_b64 v[74:75], 13, v[18:19]
	v_div_scale_f32 v19, s[6:7], v116, v116, 1.0
	v_rcp_f32_e32 v35, v19
	v_lshl_add_u64 v[74:75], s[70:71], 0, v[74:75]
	v_readlane_b32 s5, v254, 45
	v_lshl_add_u64 v[74:75], v[74:75], 0, s[92:93]
	v_fma_f32 v39, -v19, v35, 1.0
	v_fmac_f32_e32 v35, v39, v35
	v_div_scale_f32 v39, vcc, 1.0, v116, 1.0
	v_mul_f32_e32 v45, v39, v35
	v_fma_f32 v47, -v19, v45, v39
	v_fmac_f32_e32 v45, v47, v35
	v_fma_f32 v19, -v19, v45, v39
	v_div_fmas_f32 v19, v19, v35, v45
	v_div_scale_f32 v35, s[6:7], v64, v64, 1.0
	v_rcp_f32_e32 v39, v35
	v_div_fixup_f32 v116, v19, v116, 1.0
	v_mul_u32_u24_e32 v19, 0x90, v201
	v_add3_u32 v19, s5, v204, v19
	v_fma_f32 v45, -v35, v39, 1.0
	v_fmac_f32_e32 v39, v45, v39
	v_div_scale_f32 v45, vcc, 1.0, v64, 1.0
	v_mul_f32_e32 v47, v45, v39
	v_fma_f32 v65, -v35, v47, v45
	v_fmac_f32_e32 v47, v65, v39
	v_fma_f32 v35, -v35, v47, v45
	v_div_fmas_f32 v35, v35, v39, v47
	v_div_fixup_f32 v64, v35, v64, 1.0
	v_pk_mul_f32 v[62:63], v[62:63], v[64:65] op_sel_hi:[1,0]
	v_pk_mul_f32 v[60:61], v[60:61], v[64:65] op_sel_hi:[1,0]
	v_pk_mul_f32 v[50:51], v[50:51], v[64:65] op_sel_hi:[1,0]
	v_pk_mul_f32 v[48:49], v[48:49], v[64:65] op_sel_hi:[1,0]
	v_div_scale_f32 v39, s[6:7], v44, v44, 1.0
	v_lshl_add_u64 v[74:75], v[74:75], 0, v[32:33]
	v_cvt_pk_bf16_f32 v60, v60, v61
	v_cvt_pk_bf16_f32 v61, v62, v63
	v_cvt_pk_bf16_f32 v48, v48, v49
	v_cvt_pk_bf16_f32 v49, v50, v51
	v_add_u32_e32 v35, 0x800, v19
	v_rcp_f32_e32 v45, v39
	global_load_dwordx4 v[76:79], v[72:73], off offset:1536
	s_nop 0
	global_load_dwordx4 v[72:75], v[74:75], off offset:1536
	s_barrier
	ds_write2_b64 v35, v[60:61], v[48:49] offset0:32 offset1:36
	v_pk_mul_f32 v[48:49], v[58:59], v[64:65] op_sel_hi:[1,0]
	v_pk_mul_f32 v[50:51], v[56:57], v[64:65] op_sel_hi:[1,0]
	v_pk_mul_f32 v[52:53], v[64:65], v[52:53] op_sel_hi:[0,1]
	v_cvt_pk_bf16_f32 v50, v50, v51
	v_cvt_pk_bf16_f32 v51, v48, v49
	v_pk_mul_f32 v[48:49], v[64:65], v[54:55] op_sel_hi:[0,1]
	v_cvt_pk_bf16_f32 v52, v52, v53
	v_cvt_pk_bf16_f32 v53, v48, v49
	ds_write2_b64 v35, v[50:51], v[52:53] offset0:40 offset1:44
	v_fma_f32 v35, -v39, v45, 1.0
	v_fmac_f32_e32 v45, v35, v45
	v_div_scale_f32 v35, vcc, 1.0, v44, 1.0
	v_mul_f32_e32 v47, v35, v45
	v_fma_f32 v48, -v39, v47, v35
	v_fmac_f32_e32 v47, v48, v45
	v_fma_f32 v35, -v39, v47, v35
	v_div_fmas_f32 v35, v35, v45, v47
	v_div_fixup_f32 v44, v35, v44, 1.0
	v_pk_mul_f32 v[42:43], v[42:43], v[44:45] op_sel_hi:[1,0]
	v_pk_mul_f32 v[40:41], v[40:41], v[44:45] op_sel_hi:[1,0]
	v_pk_mul_f32 v[22:23], v[22:23], v[44:45] op_sel_hi:[1,0]
	v_pk_mul_f32 v[20:21], v[20:21], v[44:45] op_sel_hi:[1,0]
	v_cvt_pk_bf16_f32 v40, v40, v41
	v_cvt_pk_bf16_f32 v41, v42, v43
	v_cvt_pk_bf16_f32 v20, v20, v21
	v_cvt_pk_bf16_f32 v21, v22, v23
	v_add_u32_e32 v35, 0x1000, v19
	ds_write2_b64 v35, v[40:41], v[20:21] offset0:64 offset1:68
	v_pk_mul_f32 v[20:21], v[44:45], v[30:31] op_sel_hi:[0,1]
	v_pk_mul_f32 v[22:23], v[44:45], v[28:29] op_sel_hi:[0,1]
	v_cvt_pk_bf16_f32 v22, v22, v23
	v_cvt_pk_bf16_f32 v23, v20, v21
	v_pk_mul_f32 v[20:21], v[44:45], v[26:27] op_sel_hi:[0,1]
	v_div_scale_f32 v26, s[6:7], v16, v16, 1.0
	v_rcp_f32_e32 v27, v26
	v_pk_mul_f32 v[24:25], v[44:45], v[24:25] op_sel_hi:[0,1]
	v_cvt_pk_bf16_f32 v24, v24, v25
	v_cvt_pk_bf16_f32 v25, v20, v21
	v_fma_f32 v20, -v26, v27, 1.0
	v_fmac_f32_e32 v27, v20, v27
	v_div_scale_f32 v20, vcc, 1.0, v16, 1.0
	v_mul_f32_e32 v21, v20, v27
	ds_write2_b64 v35, v[22:23], v[24:25] offset0:72 offset1:76
	v_fma_f32 v22, -v26, v21, v20
	v_fmac_f32_e32 v21, v22, v27
	v_fma_f32 v20, -v26, v21, v20
	v_div_fmas_f32 v20, v20, v27, v21
	v_div_fixup_f32 v16, v20, v16, 1.0
	v_pk_mul_f32 v[10:11], v[10:11], v[16:17] op_sel_hi:[1,0]
	v_pk_mul_f32 v[8:9], v[8:9], v[16:17] op_sel_hi:[1,0]
	v_pk_mul_f32 v[2:3], v[2:3], v[16:17] op_sel_hi:[1,0]
	v_pk_mul_f32 v[0:1], v[0:1], v[16:17] op_sel_hi:[1,0]
	v_cvt_pk_bf16_f32 v8, v8, v9
	v_cvt_pk_bf16_f32 v9, v10, v11
	v_cvt_pk_bf16_f32 v0, v0, v1
	v_cvt_pk_bf16_f32 v1, v2, v3
	v_add_u32_e32 v10, 0x1800, v19
	v_readlane_b32 s0, v254, 46
	ds_write2_b64 v10, v[8:9], v[0:1] offset0:96 offset1:100
	v_pk_mul_f32 v[0:1], v[16:17], v[14:15] op_sel_hi:[0,1]
	v_pk_mul_f32 v[2:3], v[16:17], v[12:13] op_sel_hi:[0,1]
	s_add_u32 s6, s0, s92
	v_readlane_b32 s0, v254, 47
	v_cvt_pk_bf16_f32 v2, v2, v3
	v_cvt_pk_bf16_f32 v3, v0, v1
	v_pk_mul_f32 v[0:1], v[16:17], v[6:7] op_sel_hi:[0,1]
	v_pk_mul_f32 v[4:5], v[16:17], v[4:5] op_sel_hi:[0,1]
	s_addc_u32 s7, s0, 0
	s_movk_i32 s0, 0x48
	v_cvt_pk_bf16_f32 v4, v4, v5
	v_cvt_pk_bf16_f32 v5, v0, v1
	v_mad_u32_u24 v0, v17, s0, v37
	ds_write2_b64 v10, v[2:3], v[4:5] offset0:104 offset1:108
	v_lshl_add_u32 v2, v0, 1, s5
	s_waitcnt vmcnt(7)
	v_lshlrev_b32_e32 v0, 16, v112
	v_and_b32_e32 v1, 0xffff0000, v112
	v_mul_f32_e32 v3, 0xbfb8aa3b, v0
	v_pk_mul_f32 v[98:99], v[98:99], v[116:117] op_sel_hi:[1,0]
	v_pk_mul_f32 v[96:97], v[96:97], v[116:117] op_sel_hi:[1,0]
	v_pk_mul_f32 v[70:71], v[70:71], v[116:117] op_sel_hi:[1,0]
	v_pk_mul_f32 v[68:69], v[68:69], v[116:117] op_sel_hi:[1,0]
	v_exp_f32_e32 v3, v3
	v_mul_f32_e32 v4, 0xbfb8aa3b, v1
	v_cvt_pk_bf16_f32 v96, v96, v97
	v_cvt_pk_bf16_f32 v97, v98, v99
	v_cvt_pk_bf16_f32 v68, v68, v69
	v_cvt_pk_bf16_f32 v69, v70, v71
	v_exp_f32_e32 v8, v4
	ds_write2_b64 v19, v[96:97], v[68:69] offset1:4
	v_pk_mul_f32 v[68:69], v[94:95], v[116:117] op_sel_hi:[1,0]
	v_pk_mul_f32 v[70:71], v[92:93], v[116:117] op_sel_hi:[1,0]
	v_pk_mul_f32 v[80:81], v[116:117], v[80:81] op_sel_hi:[0,1]
	v_cvt_pk_bf16_f32 v70, v70, v71
	v_cvt_pk_bf16_f32 v71, v68, v69
	v_pk_mul_f32 v[68:69], v[116:117], v[82:83] op_sel_hi:[0,1]
	v_cvt_pk_bf16_f32 v80, v80, v81
	v_cvt_pk_bf16_f32 v81, v68, v69
	v_add_f32_e32 v3, 1.0, v3
	ds_write2_b64 v19, v[70:71], v[80:81] offset0:8 offset1:12
	v_rcp_f32_e32 v12, v3
	v_add_f32_e32 v3, 1.0, v8
	s_waitcnt lgkmcnt(0)
	v_rcp_f32_e32 v13, v3
	ds_read_b128 v[4:7], v2
	ds_read_b128 v[8:11], v2 offset:1152
	s_mov_b32 s18, s94
	v_pk_mul_f32 v[0:1], v[12:13], v[0:1]
	v_lshlrev_b32_e32 v12, 16, v113
	v_and_b32_e32 v13, 0xffff0000, v113
	v_mul_f32_e32 v3, 0xbfb8aa3b, v12
	s_waitcnt lgkmcnt(1)
	v_lshlrev_b32_e32 v14, 16, v4
	v_and_b32_e32 v15, 0xffff0000, v4
	v_exp_f32_e32 v3, v3
	v_mul_f32_e32 v4, 0xbfb8aa3b, v13
	v_exp_f32_e32 v4, v4
	v_pk_mul_f32 v[0:1], v[0:1], v[14:15]
	v_add_f32_e32 v3, 1.0, v3
	v_rcp_f32_e32 v14, v3
	v_add_f32_e32 v3, 1.0, v4
	v_rcp_f32_e32 v15, v3
	v_cvt_pk_bf16_f32 v4, v0, v1
	v_lshlrev_b32_e32 v0, 16, v5
	v_and_b32_e32 v1, 0xffff0000, v5
	v_pk_mul_f32 v[12:13], v[14:15], v[12:13]
	v_lshlrev_b32_e32 v14, 16, v114
	v_and_b32_e32 v15, 0xffff0000, v114
	v_mul_f32_e32 v3, 0xbfb8aa3b, v14
	v_exp_f32_e32 v3, v3
	v_mul_f32_e32 v5, 0xbfb8aa3b, v15
	v_exp_f32_e32 v5, v5
	v_pk_mul_f32 v[0:1], v[12:13], v[0:1]
	v_add_f32_e32 v3, 1.0, v3
	v_rcp_f32_e32 v12, v3
	v_add_f32_e32 v3, 1.0, v5
	v_rcp_f32_e32 v13, v3
	v_cvt_pk_bf16_f32 v5, v0, v1
	v_lshlrev_b32_e32 v0, 16, v6
	v_and_b32_e32 v1, 0xffff0000, v6
	v_pk_mul_f32 v[12:13], v[12:13], v[14:15]
	v_lshlrev_b32_e32 v14, 16, v115
	v_and_b32_e32 v15, 0xffff0000, v115
	v_mul_f32_e32 v3, 0xbfb8aa3b, v14
	v_exp_f32_e32 v3, v3
	v_mul_f32_e32 v6, 0xbfb8aa3b, v15
	v_exp_f32_e32 v6, v6
	v_pk_mul_f32 v[0:1], v[12:13], v[0:1]
	v_add_f32_e32 v3, 1.0, v3
	v_rcp_f32_e32 v12, v3
	v_add_f32_e32 v3, 1.0, v6
	v_rcp_f32_e32 v13, v3
	v_cvt_pk_bf16_f32 v6, v0, v1
	v_lshlrev_b32_e32 v0, 16, v7
	v_and_b32_e32 v1, 0xffff0000, v7
	v_pk_mul_f32 v[12:13], v[12:13], v[14:15]
	s_waitcnt vmcnt(6)
	v_lshlrev_b32_e32 v14, 16, v108
	v_and_b32_e32 v15, 0xffff0000, v108
	v_mul_f32_e32 v3, 0xbfb8aa3b, v14
	v_exp_f32_e32 v3, v3
	v_mul_f32_e32 v16, 0xbfb8aa3b, v15
	v_pk_mul_f32 v[0:1], v[12:13], v[0:1]
	v_exp_f32_e32 v17, v16
	v_cvt_pk_bf16_f32 v7, v0, v1
	v_mov_b64_e32 v[0:1], s[6:7]
	v_mad_i64_i32 v[12:13], s[6:7], v122, s44, v[0:1]
	v_lshl_add_u64 v[12:13], v[12:13], 0, v[32:33]
	v_add_f32_e32 v3, 1.0, v3
	v_rcp_f32_e32 v16, v3
	v_add_f32_e32 v3, 1.0, v17
	global_store_dwordx4 v[12:13], v[4:7], off sc1
	v_lshlrev_b32_e32 v12, 16, v109
	v_rcp_f32_e32 v17, v3
	v_and_b32_e32 v13, 0xffff0000, v109
	v_mul_f32_e32 v3, 0xbfb8aa3b, v12
	s_waitcnt lgkmcnt(0)
	v_lshlrev_b32_e32 v4, 16, v8
	v_and_b32_e32 v5, 0xffff0000, v8
	v_exp_f32_e32 v3, v3
	v_mul_f32_e32 v8, 0xbfb8aa3b, v13
	v_exp_f32_e32 v8, v8
	v_pk_mul_f32 v[6:7], v[16:17], v[14:15]
	v_add_f32_e32 v3, 1.0, v3
	v_pk_mul_f32 v[4:5], v[6:7], v[4:5]
	v_rcp_f32_e32 v6, v3
	v_add_f32_e32 v3, 1.0, v8
	v_rcp_f32_e32 v7, v3
	v_cvt_pk_bf16_f32 v4, v4, v5
	v_lshlrev_b32_e32 v8, 16, v9
	v_and_b32_e32 v9, 0xffff0000, v9
	v_pk_mul_f32 v[6:7], v[6:7], v[12:13]
	v_lshlrev_b32_e32 v12, 16, v110
	v_and_b32_e32 v13, 0xffff0000, v110
	v_mul_f32_e32 v3, 0xbfb8aa3b, v12
	v_exp_f32_e32 v3, v3
	v_mul_f32_e32 v5, 0xbfb8aa3b, v13
	v_exp_f32_e32 v5, v5
	v_pk_mul_f32 v[6:7], v[6:7], v[8:9]
	v_add_f32_e32 v3, 1.0, v3
	v_rcp_f32_e32 v8, v3
	v_add_f32_e32 v3, 1.0, v5
	v_rcp_f32_e32 v9, v3
	v_cvt_pk_bf16_f32 v5, v6, v7
	v_lshlrev_b32_e32 v6, 16, v10
	v_and_b32_e32 v7, 0xffff0000, v10
	v_pk_mul_f32 v[8:9], v[8:9], v[12:13]
	v_lshlrev_b32_e32 v12, 16, v111
	v_and_b32_e32 v13, 0xffff0000, v111
	v_mul_f32_e32 v3, 0xbfb8aa3b, v12
	v_exp_f32_e32 v3, v3
	v_mul_f32_e32 v10, 0xbfb8aa3b, v13
	v_exp_f32_e32 v10, v10
	v_pk_mul_f32 v[6:7], v[8:9], v[6:7]
	v_add_f32_e32 v3, 1.0, v3
	v_rcp_f32_e32 v8, v3
	v_add_f32_e32 v3, 1.0, v10
	v_rcp_f32_e32 v9, v3
	v_lshlrev_b32_e32 v10, 16, v11
	v_and_b32_e32 v11, 0xffff0000, v11
	v_cvt_pk_bf16_f32 v6, v6, v7
	v_pk_mul_f32 v[8:9], v[8:9], v[12:13]
	s_waitcnt vmcnt(6)
	v_lshlrev_b32_e32 v12, 16, v104
	v_pk_mul_f32 v[8:9], v[8:9], v[10:11]
	v_and_b32_e32 v13, 0xffff0000, v104
	v_cvt_pk_bf16_f32 v7, v8, v9
	v_mad_i64_i32 v[8:9], s[6:7], v120, s44, v[0:1]
	v_lshl_add_u64 v[8:9], v[8:9], 0, v[32:33]
	v_mul_f32_e32 v3, 0xbfb8aa3b, v12
	global_store_dwordx4 v[8:9], v[4:7], off sc1
	v_exp_f32_e32 v3, v3
	v_readlane_b32 s96, v254, 31
	v_mul_f32_e32 v4, 0xbfb8aa3b, v13
	v_exp_f32_e32 v8, v4
	v_add_f32_e32 v3, 1.0, v3
	v_rcp_f32_e32 v14, v3
	ds_read_b128 v[4:7], v2 offset:2304
	v_add_f32_e32 v3, 1.0, v8
	v_rcp_f32_e32 v15, v3
	ds_read_b128 v[8:11], v2 offset:3456
	v_readlane_b32 s83, v254, 33
	s_waitcnt lgkmcnt(1)
	v_lshlrev_b32_e32 v16, 16, v4
	v_pk_mul_f32 v[12:13], v[14:15], v[12:13]
	v_lshlrev_b32_e32 v14, 16, v105
	v_and_b32_e32 v15, 0xffff0000, v105
	v_mul_f32_e32 v3, 0xbfb8aa3b, v14
	v_and_b32_e32 v17, 0xffff0000, v4
	v_exp_f32_e32 v3, v3
	v_mul_f32_e32 v4, 0xbfb8aa3b, v15
	v_exp_f32_e32 v4, v4
	v_pk_mul_f32 v[12:13], v[12:13], v[16:17]
	v_add_f32_e32 v3, 1.0, v3
	v_rcp_f32_e32 v16, v3
	v_add_f32_e32 v3, 1.0, v4
	v_rcp_f32_e32 v17, v3
	v_cvt_pk_bf16_f32 v4, v12, v13
	v_lshlrev_b32_e32 v12, 16, v5
	v_and_b32_e32 v13, 0xffff0000, v5
	v_pk_mul_f32 v[14:15], v[16:17], v[14:15]
	v_lshlrev_b32_e32 v16, 16, v106
	v_and_b32_e32 v17, 0xffff0000, v106
	v_mul_f32_e32 v3, 0xbfb8aa3b, v16
	v_exp_f32_e32 v3, v3
	v_mul_f32_e32 v5, 0xbfb8aa3b, v17
	v_exp_f32_e32 v5, v5
	v_pk_mul_f32 v[12:13], v[14:15], v[12:13]
	v_add_f32_e32 v3, 1.0, v3
	v_rcp_f32_e32 v14, v3
	v_add_f32_e32 v3, 1.0, v5
	v_rcp_f32_e32 v15, v3
	v_cvt_pk_bf16_f32 v5, v12, v13
	v_lshlrev_b32_e32 v12, 16, v6
	v_and_b32_e32 v13, 0xffff0000, v6
	v_pk_mul_f32 v[14:15], v[14:15], v[16:17]
	v_lshlrev_b32_e32 v16, 16, v107
	v_and_b32_e32 v17, 0xffff0000, v107
	v_mul_f32_e32 v3, 0xbfb8aa3b, v16
	v_exp_f32_e32 v3, v3
	v_mul_f32_e32 v6, 0xbfb8aa3b, v17
	v_exp_f32_e32 v6, v6
	v_pk_mul_f32 v[12:13], v[14:15], v[12:13]
	v_add_f32_e32 v3, 1.0, v3
	v_rcp_f32_e32 v14, v3
	v_add_f32_e32 v3, 1.0, v6
	v_rcp_f32_e32 v15, v3
	v_cvt_pk_bf16_f32 v6, v12, v13
	v_lshlrev_b32_e32 v12, 16, v7
	v_and_b32_e32 v13, 0xffff0000, v7
	v_pk_mul_f32 v[14:15], v[14:15], v[16:17]
	s_movk_i32 s79, 0x100
	v_pk_mul_f32 v[12:13], v[14:15], v[12:13]
	s_waitcnt vmcnt(6)
	v_lshlrev_b32_e32 v14, 16, v100
	v_and_b32_e32 v15, 0xffff0000, v100
	v_mul_f32_e32 v3, 0xbfb8aa3b, v14
	v_exp_f32_e32 v3, v3
	v_mul_f32_e32 v16, 0xbfb8aa3b, v15
	v_exp_f32_e32 v17, v16
	v_cvt_pk_bf16_f32 v7, v12, v13
	v_mad_i64_i32 v[12:13], s[6:7], v118, s44, v[0:1]
	v_lshl_add_u64 v[12:13], v[12:13], 0, v[32:33]
	v_add_f32_e32 v3, 1.0, v3
	v_rcp_f32_e32 v16, v3
	v_add_f32_e32 v3, 1.0, v17
	global_store_dwordx4 v[12:13], v[4:7], off sc1
	v_lshlrev_b32_e32 v12, 16, v101
	v_rcp_f32_e32 v17, v3
	v_and_b32_e32 v13, 0xffff0000, v101
	v_mul_f32_e32 v3, 0xbfb8aa3b, v12
	s_waitcnt lgkmcnt(0)
	v_lshlrev_b32_e32 v4, 16, v8
	v_and_b32_e32 v5, 0xffff0000, v8
	v_exp_f32_e32 v3, v3
	v_mul_f32_e32 v8, 0xbfb8aa3b, v13
	v_exp_f32_e32 v8, v8
	v_pk_mul_f32 v[6:7], v[16:17], v[14:15]
	v_add_f32_e32 v3, 1.0, v3
	v_pk_mul_f32 v[4:5], v[6:7], v[4:5]
	v_rcp_f32_e32 v6, v3
	v_add_f32_e32 v3, 1.0, v8
	v_rcp_f32_e32 v7, v3
	v_cvt_pk_bf16_f32 v4, v4, v5
	v_lshlrev_b32_e32 v8, 16, v9
	v_and_b32_e32 v9, 0xffff0000, v9
	v_pk_mul_f32 v[6:7], v[6:7], v[12:13]
	v_lshlrev_b32_e32 v12, 16, v102
	v_and_b32_e32 v13, 0xffff0000, v102
	v_mul_f32_e32 v3, 0xbfb8aa3b, v12
	v_exp_f32_e32 v3, v3
	v_mul_f32_e32 v5, 0xbfb8aa3b, v13
	v_exp_f32_e32 v5, v5
	v_pk_mul_f32 v[6:7], v[6:7], v[8:9]
	v_add_f32_e32 v3, 1.0, v3
	v_rcp_f32_e32 v8, v3
	v_add_f32_e32 v3, 1.0, v5
	v_rcp_f32_e32 v9, v3
	v_cvt_pk_bf16_f32 v5, v6, v7
	v_lshlrev_b32_e32 v6, 16, v10
	v_and_b32_e32 v7, 0xffff0000, v10
	v_pk_mul_f32 v[8:9], v[8:9], v[12:13]
	v_lshlrev_b32_e32 v12, 16, v103
	v_and_b32_e32 v13, 0xffff0000, v103
	v_mul_f32_e32 v3, 0xbfb8aa3b, v12
	v_exp_f32_e32 v3, v3
	v_mul_f32_e32 v10, 0xbfb8aa3b, v13
	v_exp_f32_e32 v10, v10
	v_pk_mul_f32 v[6:7], v[8:9], v[6:7]
	v_add_f32_e32 v3, 1.0, v3
	v_rcp_f32_e32 v8, v3
	v_add_f32_e32 v3, 1.0, v10
	v_rcp_f32_e32 v9, v3
	v_lshlrev_b32_e32 v10, 16, v11
	v_and_b32_e32 v11, 0xffff0000, v11
	v_cvt_pk_bf16_f32 v6, v6, v7
	v_pk_mul_f32 v[8:9], v[8:9], v[12:13]
	s_waitcnt vmcnt(6)
	v_lshlrev_b32_e32 v12, 16, v88
	v_pk_mul_f32 v[8:9], v[8:9], v[10:11]
	v_and_b32_e32 v13, 0xffff0000, v88
	v_cvt_pk_bf16_f32 v7, v8, v9
	v_mad_i64_i32 v[8:9], s[6:7], v66, s44, v[0:1]
	v_lshl_add_u64 v[8:9], v[8:9], 0, v[32:33]
	v_mul_f32_e32 v3, 0xbfb8aa3b, v12
	global_store_dwordx4 v[8:9], v[4:7], off sc1
	v_exp_f32_e32 v3, v3
	s_movk_i32 s81, 0xff
	v_mul_f32_e32 v4, 0xbfb8aa3b, v13
	v_exp_f32_e32 v8, v4
	v_add_f32_e32 v3, 1.0, v3
	v_rcp_f32_e32 v14, v3
	ds_read_b128 v[4:7], v2 offset:4608
	v_add_f32_e32 v3, 1.0, v8
	v_rcp_f32_e32 v15, v3
	ds_read_b128 v[8:11], v2 offset:5760
	v_readlane_b32 s97, v254, 32
	s_waitcnt lgkmcnt(1)
	v_lshlrev_b32_e32 v16, 16, v4
	v_pk_mul_f32 v[12:13], v[14:15], v[12:13]
	v_lshlrev_b32_e32 v14, 16, v89
	v_and_b32_e32 v15, 0xffff0000, v89
	v_mul_f32_e32 v3, 0xbfb8aa3b, v14
	v_and_b32_e32 v17, 0xffff0000, v4
	v_exp_f32_e32 v3, v3
	v_mul_f32_e32 v4, 0xbfb8aa3b, v15
	v_exp_f32_e32 v4, v4
	v_pk_mul_f32 v[12:13], v[12:13], v[16:17]
	v_add_f32_e32 v3, 1.0, v3
	v_rcp_f32_e32 v16, v3
	v_add_f32_e32 v3, 1.0, v4
	v_rcp_f32_e32 v17, v3
	v_cvt_pk_bf16_f32 v4, v12, v13
	v_lshlrev_b32_e32 v12, 16, v5
	v_and_b32_e32 v13, 0xffff0000, v5
	v_pk_mul_f32 v[14:15], v[16:17], v[14:15]
	v_lshlrev_b32_e32 v16, 16, v90
	v_and_b32_e32 v17, 0xffff0000, v90
	v_mul_f32_e32 v3, 0xbfb8aa3b, v16
	v_exp_f32_e32 v3, v3
	v_mul_f32_e32 v5, 0xbfb8aa3b, v17
	v_exp_f32_e32 v5, v5
	v_pk_mul_f32 v[12:13], v[14:15], v[12:13]
	v_add_f32_e32 v3, 1.0, v3
	v_rcp_f32_e32 v14, v3
	v_add_f32_e32 v3, 1.0, v5
	v_rcp_f32_e32 v15, v3
	v_cvt_pk_bf16_f32 v5, v12, v13
	v_lshlrev_b32_e32 v12, 16, v6
	v_and_b32_e32 v13, 0xffff0000, v6
	v_pk_mul_f32 v[14:15], v[14:15], v[16:17]
	v_lshlrev_b32_e32 v16, 16, v91
	v_and_b32_e32 v17, 0xffff0000, v91
	v_mul_f32_e32 v3, 0xbfb8aa3b, v16
	v_exp_f32_e32 v3, v3
	v_mul_f32_e32 v6, 0xbfb8aa3b, v17
	v_exp_f32_e32 v6, v6
	v_pk_mul_f32 v[12:13], v[14:15], v[12:13]
	v_add_f32_e32 v3, 1.0, v3
	v_rcp_f32_e32 v14, v3
	v_add_f32_e32 v3, 1.0, v6
	v_rcp_f32_e32 v15, v3
	v_cvt_pk_bf16_f32 v6, v12, v13
	v_lshlrev_b32_e32 v12, 16, v7
	v_and_b32_e32 v13, 0xffff0000, v7
	v_pk_mul_f32 v[14:15], v[14:15], v[16:17]
	s_mov_b32 s82, 0x10000
	v_pk_mul_f32 v[12:13], v[14:15], v[12:13]
	s_waitcnt vmcnt(6)
	v_lshlrev_b32_e32 v14, 16, v84
	v_and_b32_e32 v15, 0xffff0000, v84
	v_mul_f32_e32 v3, 0xbfb8aa3b, v14
	v_exp_f32_e32 v3, v3
	v_mul_f32_e32 v16, 0xbfb8aa3b, v15
	v_exp_f32_e32 v17, v16
	v_cvt_pk_bf16_f32 v7, v12, v13
	v_mad_i64_i32 v[12:13], s[6:7], v46, s44, v[0:1]
	v_lshl_add_u64 v[12:13], v[12:13], 0, v[32:33]
	v_add_f32_e32 v3, 1.0, v3
	v_rcp_f32_e32 v16, v3
	v_add_f32_e32 v3, 1.0, v17
	global_store_dwordx4 v[12:13], v[4:7], off sc1
	v_lshlrev_b32_e32 v12, 16, v85
	v_rcp_f32_e32 v17, v3
	v_and_b32_e32 v13, 0xffff0000, v85
	v_mul_f32_e32 v3, 0xbfb8aa3b, v12
	s_waitcnt lgkmcnt(0)
	v_lshlrev_b32_e32 v4, 16, v8
	v_and_b32_e32 v5, 0xffff0000, v8
	v_exp_f32_e32 v3, v3
	v_mul_f32_e32 v8, 0xbfb8aa3b, v13
	v_exp_f32_e32 v8, v8
	v_pk_mul_f32 v[6:7], v[16:17], v[14:15]
	v_add_f32_e32 v3, 1.0, v3
	v_pk_mul_f32 v[4:5], v[6:7], v[4:5]
	v_rcp_f32_e32 v6, v3
	v_add_f32_e32 v3, 1.0, v8
	v_rcp_f32_e32 v7, v3
	v_cvt_pk_bf16_f32 v4, v4, v5
	v_lshlrev_b32_e32 v8, 16, v9
	v_and_b32_e32 v9, 0xffff0000, v9
	v_pk_mul_f32 v[6:7], v[6:7], v[12:13]
	v_lshlrev_b32_e32 v12, 16, v86
	v_and_b32_e32 v13, 0xffff0000, v86
	v_mul_f32_e32 v3, 0xbfb8aa3b, v12
	v_exp_f32_e32 v3, v3
	v_mul_f32_e32 v5, 0xbfb8aa3b, v13
	v_exp_f32_e32 v5, v5
	v_pk_mul_f32 v[6:7], v[6:7], v[8:9]
	v_add_f32_e32 v3, 1.0, v3
	v_rcp_f32_e32 v8, v3
	v_add_f32_e32 v3, 1.0, v5
	v_rcp_f32_e32 v9, v3
	v_cvt_pk_bf16_f32 v5, v6, v7
	v_lshlrev_b32_e32 v6, 16, v10
	v_and_b32_e32 v7, 0xffff0000, v10
	v_pk_mul_f32 v[8:9], v[8:9], v[12:13]
	v_lshlrev_b32_e32 v12, 16, v87
	v_and_b32_e32 v13, 0xffff0000, v87
	v_mul_f32_e32 v3, 0xbfb8aa3b, v12
	v_exp_f32_e32 v3, v3
	v_mul_f32_e32 v10, 0xbfb8aa3b, v13
	v_exp_f32_e32 v10, v10
	v_pk_mul_f32 v[6:7], v[8:9], v[6:7]
	v_add_f32_e32 v3, 1.0, v3
	v_rcp_f32_e32 v8, v3
	v_add_f32_e32 v3, 1.0, v10
	v_rcp_f32_e32 v9, v3
	v_lshlrev_b32_e32 v10, 16, v11
	v_and_b32_e32 v11, 0xffff0000, v11
	v_cvt_pk_bf16_f32 v6, v6, v7
	v_pk_mul_f32 v[8:9], v[8:9], v[12:13]
	s_waitcnt vmcnt(6)
	v_lshlrev_b32_e32 v12, 16, v76
	v_pk_mul_f32 v[8:9], v[8:9], v[10:11]
	v_and_b32_e32 v13, 0xffff0000, v76
	v_cvt_pk_bf16_f32 v7, v8, v9
	v_mad_i64_i32 v[8:9], s[6:7], v38, s44, v[0:1]
	v_lshl_add_u64 v[8:9], v[8:9], 0, v[32:33]
	v_mul_f32_e32 v3, 0xbfb8aa3b, v12
	global_store_dwordx4 v[8:9], v[4:7], off sc1
	v_exp_f32_e32 v3, v3
	s_nop 0
	v_mul_f32_e32 v4, 0xbfb8aa3b, v13
	v_exp_f32_e32 v8, v4
	v_add_f32_e32 v3, 1.0, v3
	v_rcp_f32_e32 v14, v3
	ds_read_b128 v[4:7], v2 offset:6912
	v_add_f32_e32 v3, 1.0, v8
	v_rcp_f32_e32 v15, v3
	ds_read_b128 v[8:11], v2 offset:8064
	s_waitcnt lgkmcnt(1)
	v_lshlrev_b32_e32 v2, 16, v4
	v_pk_mul_f32 v[12:13], v[14:15], v[12:13]
	v_lshlrev_b32_e32 v14, 16, v77
	v_and_b32_e32 v3, 0xffff0000, v4
	v_and_b32_e32 v15, 0xffff0000, v77
	v_mul_f32_e32 v4, 0xbfb8aa3b, v14
	v_exp_f32_e32 v4, v4
	v_mul_f32_e32 v16, 0xbfb8aa3b, v15
	v_exp_f32_e32 v16, v16
	v_pk_mul_f32 v[2:3], v[12:13], v[2:3]
	v_add_f32_e32 v4, 1.0, v4
	v_rcp_f32_e32 v12, v4
	v_add_f32_e32 v4, 1.0, v16
	v_rcp_f32_e32 v13, v4
	v_cvt_pk_bf16_f32 v2, v2, v3
	v_lshlrev_b32_e32 v4, 16, v5
	v_and_b32_e32 v5, 0xffff0000, v5
	v_pk_mul_f32 v[12:13], v[12:13], v[14:15]
	v_lshlrev_b32_e32 v14, 16, v78
	v_and_b32_e32 v15, 0xffff0000, v78
	v_mul_f32_e32 v3, 0xbfb8aa3b, v14
	v_exp_f32_e32 v3, v3
	v_mul_f32_e32 v16, 0xbfb8aa3b, v15
	v_exp_f32_e32 v16, v16
	v_pk_mul_f32 v[4:5], v[12:13], v[4:5]
	v_add_f32_e32 v3, 1.0, v3
	v_rcp_f32_e32 v12, v3
	v_add_f32_e32 v3, 1.0, v16
	v_rcp_f32_e32 v13, v3
	v_cvt_pk_bf16_f32 v3, v4, v5
	v_lshlrev_b32_e32 v4, 16, v6
	v_and_b32_e32 v5, 0xffff0000, v6
	v_pk_mul_f32 v[12:13], v[12:13], v[14:15]
	v_lshlrev_b32_e32 v14, 16, v79
	v_and_b32_e32 v15, 0xffff0000, v79
	v_mul_f32_e32 v6, 0xbfb8aa3b, v14
	v_exp_f32_e32 v6, v6
	v_mul_f32_e32 v16, 0xbfb8aa3b, v15
	v_exp_f32_e32 v16, v16
	v_pk_mul_f32 v[4:5], v[12:13], v[4:5]
	v_add_f32_e32 v6, 1.0, v6
	v_rcp_f32_e32 v12, v6
	v_add_f32_e32 v6, 1.0, v16
	v_rcp_f32_e32 v13, v6
	v_lshlrev_b32_e32 v6, 16, v7
	v_and_b32_e32 v7, 0xffff0000, v7
	v_cvt_pk_bf16_f32 v4, v4, v5
	v_pk_mul_f32 v[12:13], v[12:13], v[14:15]
	s_nop 0
	v_pk_mul_f32 v[6:7], v[12:13], v[6:7]
	s_waitcnt vmcnt(6)
	v_lshlrev_b32_e32 v12, 16, v72
	v_and_b32_e32 v13, 0xffff0000, v72
	v_mul_f32_e32 v14, 0xbfb8aa3b, v12
	v_mul_f32_e32 v15, 0xbfb8aa3b, v13
	v_exp_f32_e32 v14, v14
	v_exp_f32_e32 v15, v15
	v_cvt_pk_bf16_f32 v5, v6, v7
	v_mad_i64_i32 v[6:7], s[6:7], v34, s44, v[0:1]
	v_add_f32_e32 v14, 1.0, v14
	v_add_f32_e32 v15, 1.0, v15
	v_rcp_f32_e32 v14, v14
	v_rcp_f32_e32 v15, v15
	v_lshl_add_u64 v[6:7], v[6:7], 0, v[32:33]
	global_store_dwordx4 v[6:7], v[2:5], off sc1
	v_lshlrev_b32_e32 v6, 16, v73
	v_and_b32_e32 v7, 0xffff0000, v73
	s_waitcnt lgkmcnt(0)
	v_lshlrev_b32_e32 v2, 16, v8
	v_and_b32_e32 v3, 0xffff0000, v8
	v_pk_mul_f32 v[4:5], v[14:15], v[12:13]
	v_mul_f32_e32 v8, 0xbfb8aa3b, v6
	v_mul_f32_e32 v12, 0xbfb8aa3b, v7
	v_exp_f32_e32 v8, v8
	v_exp_f32_e32 v12, v12
	v_pk_mul_f32 v[2:3], v[4:5], v[2:3]
	v_mad_i64_i32 v[0:1], s[6:7], v18, s44, v[0:1]
	v_add_f32_e32 v4, 1.0, v8
	v_add_f32_e32 v5, 1.0, v12
	v_rcp_f32_e32 v4, v4
	v_rcp_f32_e32 v5, v5
	v_cvt_pk_bf16_f32 v2, v2, v3
	v_lshlrev_b32_e32 v8, 16, v9
	v_and_b32_e32 v9, 0xffff0000, v9
	v_pk_mul_f32 v[4:5], v[4:5], v[6:7]
	v_lshlrev_b32_e32 v6, 16, v74
	v_and_b32_e32 v7, 0xffff0000, v74
	v_mul_f32_e32 v3, 0xbfb8aa3b, v6
	v_exp_f32_e32 v3, v3
	v_mul_f32_e32 v12, 0xbfb8aa3b, v7
	v_exp_f32_e32 v12, v12
	v_pk_mul_f32 v[4:5], v[4:5], v[8:9]
	v_add_f32_e32 v3, 1.0, v3
	v_rcp_f32_e32 v8, v3
	v_add_f32_e32 v3, 1.0, v12
	v_rcp_f32_e32 v9, v3
	v_cvt_pk_bf16_f32 v3, v4, v5
	v_lshlrev_b32_e32 v4, 16, v10
	v_and_b32_e32 v5, 0xffff0000, v10
	v_pk_mul_f32 v[6:7], v[8:9], v[6:7]
	v_lshlrev_b32_e32 v8, 16, v75
	v_and_b32_e32 v9, 0xffff0000, v75
	v_mul_f32_e32 v10, 0xbfb8aa3b, v8
	v_mul_f32_e32 v12, 0xbfb8aa3b, v9
	v_exp_f32_e32 v10, v10
	v_exp_f32_e32 v12, v12
	v_pk_mul_f32 v[4:5], v[6:7], v[4:5]
	v_lshl_add_u64 v[0:1], v[0:1], 0, v[32:33]
	v_add_f32_e32 v6, 1.0, v10
	v_add_f32_e32 v7, 1.0, v12
	v_rcp_f32_e32 v6, v6
	v_rcp_f32_e32 v7, v7
	v_lshlrev_b32_e32 v10, 16, v11
	v_and_b32_e32 v11, 0xffff0000, v11
	v_cvt_pk_bf16_f32 v4, v4, v5
	v_pk_mul_f32 v[6:7], v[6:7], v[8:9]
	s_mov_b64 s[6:7], s[76:77]
	v_pk_mul_f32 v[6:7], v[6:7], v[10:11]
	s_nop 0
	v_cvt_pk_bf16_f32 v5, v6, v7
	global_store_dwordx4 v[0:1], v[2:5], off sc1

.LBB0_848:
	s_andn2_saveexec_b64 s[8:9], s[8:9]
	s_cbranch_execz .LBB0_868
	s_mov_b64 s[8:9], exec
	s_waitcnt lgkmcnt(0)
	s_waitcnt vmcnt(0)
	v_mbcnt_lo_u32_b32 v1, s8, 0
	v_mbcnt_hi_u32_b32 v1, s9, v1
	v_cmp_eq_u32_e32 vcc, 0, v1
	s_and_saveexec_b64 s[10:11], vcc
	s_cbranch_execz .LBB0_851
	s_bcnt1_i32_b64 s5, s[8:9]
	v_readlane_b32 s8, v253, 22
	v_mov_b32_e32 v2, s5
	v_readlane_b32 s9, v253, 23
	s_nop 4
	global_atomic_add v2, v33, v2, s[8:9] sc0
